# K-loop MFMA order: the two k-steps of each accumulator issue back to back (plus tail-4 barrier, S5 wait, hoisted row-sum loads)
# speedup vs baseline: 1.0053x; 1.0053x over previous
; #define PG8_STAGE(bufoff, gbase, voff) do { _Pragma("unroll") for (int _i = 0; _i < 2; ++_i) \
;         __builtin_amdgcn_global_load_lds((const unsigned*)((const char*)(gbase) + (voff)[_i]), (PG8_LAS unsigned*)(lds + (bufoff) + ldsw + _i * 8192), 16, 0, 0); } while (0)
; #define PG8_LDA(dst, b, h) do { _Pragma("unroll") for (int m = 0; m < 4; ++m) _Pragma("unroll") for (int k = 0; k < 2; ++k) dst[m][k] = *(const PG8_LAS bf16x8*)(lds + PG8_SA(b, h) + aoff + m * 2048 + k * 1024); } while (0)
; #define PG8_LDB(dst, b, h) do { _Pragma("unroll") for (int n = 0; n < 2; ++n) _Pragma("unroll") for (int k = 0; k < 2; ++k) dst[n][k] = *(const PG8_LAS bf16x8*)(lds + PG8_SB(b, h) + boff + n * 2048 + k * 1024); } while (0)
; #define PG8_MMA(ai, bj, At, Bt) do { __builtin_amdgcn_s_setprio(1); _Pragma("unroll") for (int m = 0; m < 4; ++m) _Pragma("unroll") for (int n = 0; n < 2; ++n) _Pragma("unroll") for (int k = 0; k < 2; ++k) \
;         acc[ai][bj][m][n] = __builtin_amdgcn_mfma_f32_16x16x32_bf16(Bt[n][k], At[m][k], acc[ai][bj][m][n], 0, 0, 0); __builtin_amdgcn_s_setprio(0); } while (0)
; #define PG8_WAIT_V(n) asm volatile("s_waitcnt vmcnt(" #n ")" ::: "memory")
; #define PG8_WAIT_L(n) asm volatile("s_waitcnt lgkmcnt(" #n ")" ::: "memory")
; #define PG8_BAR __builtin_amdgcn_s_barrier()
; #define PG8_SCHED __builtin_amdgcn_sched_barrier(0)
; template <class Epi, class Sched, bool ALIGN_EPI = false, bool SP2 = false>
; __device__ __forceinline__ void gemm_phase(PG8_LAS unsigned char* lds, const Gemm g, const Sched& S, const Epi& E) {
;     ...
;             const char* a1 = cA + (size_t)(t + 1) * kstep;
;             const char* a2 = last ? nA : cA + (size_t)(t + 2) * kstep; const char* b2 = last ? nB : cB + (size_t)(t + 2) * kstep;
;             const char* a3 = a2 + kstep; const char* b3 = b2 + kstep;
;             if (last && has_next) S.a_ready(nxt);
;             if constexpr (SP2) {
;             PG8_LDB(B0, 0, 0); PG8_LDB(B1, 0, 1); PG8_SCHED; PG8_LDA(At, 0, 0); PG8_STAGE(PG8_SA(1, 1), a1 + hstep, voffA);
;             PG8_WAIT_V(8); PG8_WAIT_L(0); PG8_BAR; PG8_MMA(0, 0, At, B0); PG8_MMA(0, 1, At, B1); PG8_BAR; PG8_SCHED;
;             PG8_LDA(At, 0, 1); PG8_STAGE(PG8_SB(0, 0), b2, voffB); PG8_STAGE(PG8_SB(0, 1), b2 + hstep, voffB); PG8_STAGE(PG8_SA(0, 0), a2, voffA);
.LBB0_110:
	ds_read_b128 v[136:139], v161
	ds_read_b128 v[140:143], v161 offset:1024
	ds_read_b128 v[176:179], v161 offset:2048
	ds_read_b128 v[180:183], v161 offset:3072
	ds_read_b128 v[184:187], v162
	ds_read_b128 v[202:205], v162 offset:1024
	ds_read_b128 v[206:209], v162 offset:2048
	ds_read_b128 v[210:213], v162 offset:3072
	s_add_u32 s28, s52, 0xfff80080
	s_addc_u32 s29, s53, -1
	s_cmp_eq_u32 s74, 28
	s_cselect_b32 s49, s25, s29
	s_cselect_b32 s48, s34, s28
	s_cselect_b32 s29, s23, s73
	s_cselect_b32 s28, s35, s72
	v_lshl_add_u64 v[246:247], s[52:53], 0, v[128:129]
	s_add_i32 m0, s9, 0xc000
	ds_read_b128 v[214:217], v163
	ds_read_b128 v[218:221], v163 offset:1024
	ds_read_b128 v[222:225], v163 offset:2048
	ds_read_b128 v[226:229], v163 offset:3072
	ds_read_b128 v[230:233], v163 offset:4096
	ds_read_b128 v[234:237], v163 offset:5120
	ds_read_b128 v[238:241], v163 offset:6144
	ds_read_b128 v[242:245], v163 offset:7168
	global_load_lds_dwordx4 v[246:247], off
	v_lshl_add_u64 v[246:247], s[52:53], 0, v[130:131]
	s_add_i32 m0, s9, 0xe000
	s_nop 0
	global_load_lds_dwordx4 v[246:247], off
	s_waitcnt vmcnt(8)
	s_waitcnt lgkmcnt(0)
	s_barrier
	s_setprio 1
	s_waitcnt lgkmcnt(0)
	v_mfma_f32_16x16x32_bf16 v[124:127], v[136:139], v[214:217], v[124:127]
	v_mfma_f32_16x16x32_bf16 v[124:127], v[140:143], v[218:221], v[124:127]
	v_mfma_f32_16x16x32_bf16 v[120:123], v[176:179], v[214:217], v[120:123]
	v_mfma_f32_16x16x32_bf16 v[120:123], v[180:183], v[218:221], v[120:123]
	v_mfma_f32_16x16x32_bf16 v[108:111], v[136:139], v[222:225], v[108:111]
	v_mfma_f32_16x16x32_bf16 v[108:111], v[140:143], v[226:229], v[108:111]
	v_mfma_f32_16x16x32_bf16 v[104:107], v[176:179], v[222:225], v[104:107]
	v_mfma_f32_16x16x32_bf16 v[104:107], v[180:183], v[226:229], v[104:107]
	v_mfma_f32_16x16x32_bf16 v[96:99], v[136:139], v[230:233], v[96:99]
	v_mfma_f32_16x16x32_bf16 v[96:99], v[140:143], v[234:237], v[96:99]
	v_mfma_f32_16x16x32_bf16 v[88:91], v[176:179], v[230:233], v[88:91]
	v_mfma_f32_16x16x32_bf16 v[88:91], v[180:183], v[234:237], v[88:91]
	v_mfma_f32_16x16x32_bf16 v[80:83], v[136:139], v[238:241], v[80:83]
	v_mfma_f32_16x16x32_bf16 v[80:83], v[140:143], v[242:245], v[80:83]
	v_mfma_f32_16x16x32_bf16 v[72:75], v[176:179], v[238:241], v[72:75]
	v_mfma_f32_16x16x32_bf16 v[72:75], v[180:183], v[242:245], v[72:75]
	s_setprio 0
	s_setprio 1
	v_mfma_f32_16x16x32_bf16 v[116:119], v[184:187], v[214:217], v[116:119]
	v_mfma_f32_16x16x32_bf16 v[116:119], v[202:205], v[218:221], v[116:119]
	v_mfma_f32_16x16x32_bf16 v[112:115], v[206:209], v[214:217], v[112:115]
	v_mfma_f32_16x16x32_bf16 v[112:115], v[210:213], v[218:221], v[112:115]
	v_mfma_f32_16x16x32_bf16 v[100:103], v[184:187], v[222:225], v[100:103]
	v_mfma_f32_16x16x32_bf16 v[100:103], v[202:205], v[226:229], v[100:103]
	v_mfma_f32_16x16x32_bf16 v[92:95], v[206:209], v[222:225], v[92:95]
	v_mfma_f32_16x16x32_bf16 v[92:95], v[210:213], v[226:229], v[92:95]
	v_mfma_f32_16x16x32_bf16 v[84:87], v[184:187], v[230:233], v[84:87]
	v_mfma_f32_16x16x32_bf16 v[84:87], v[202:205], v[234:237], v[84:87]
	v_mfma_f32_16x16x32_bf16 v[76:79], v[206:209], v[230:233], v[76:79]
	v_mfma_f32_16x16x32_bf16 v[76:79], v[210:213], v[234:237], v[76:79]
	s_setprio 2
	s_barrier
	v_mfma_f32_16x16x32_bf16 v[68:71], v[184:187], v[238:241], v[68:71]
	v_mfma_f32_16x16x32_bf16 v[68:71], v[202:205], v[242:245], v[68:71]
	v_mfma_f32_16x16x32_bf16 v[64:67], v[206:209], v[238:241], v[64:67]
	v_mfma_f32_16x16x32_bf16 v[64:67], v[210:213], v[242:245], v[64:67]
	s_setprio 0
	s_add_i32 s75, s63, s45
	v_lshl_add_u64 v[246:247], s[28:29], 0, v[166:167]
	s_mov_b32 m0, s75
	ds_read_b128 v[214:217], v163 offset:16384
	ds_read_b128 v[218:221], v163 offset:17408
	ds_read_b128 v[222:225], v163 offset:18432
	ds_read_b128 v[226:229], v163 offset:19456
	ds_read_b128 v[230:233], v163 offset:20480
	ds_read_b128 v[234:237], v163 offset:21504
	ds_read_b128 v[238:241], v163 offset:22528
	ds_read_b128 v[242:245], v163 offset:23552
	global_load_lds_dwordx4 v[246:247], off
	s_add_i32 m0, s75, 0x2000
	s_add_u32 s76, s28, 0x80000
	v_lshl_add_u64 v[248:249], s[28:29], 0, v[170:171]
	s_addc_u32 s77, s29, 0
	s_add_i32 s75, s64, s45
	global_load_lds_dwordx4 v[248:249], off
	v_lshl_add_u64 v[250:251], s[76:77], 0, v[166:167]
	s_mov_b32 m0, s75
	v_lshl_add_u64 v[252:253], s[48:49], 0, v[168:169]
	global_load_lds_dwordx4 v[250:251], off
	v_lshl_add_u64 v[250:251], s[76:77], 0, v[170:171]
	s_add_i32 m0, s75, 0x2000
	s_nop 0
	global_load_lds_dwordx4 v[250:251], off
	v_lshl_add_u64 v[250:251], s[48:49], 0, v[164:165]
	s_mov_b32 m0, s9
	s_nop 0
	global_load_lds_dwordx4 v[250:251], off
	s_mov_b32 m0, s57
	s_nop 0
	global_load_lds_dwordx4 v[252:253], off
	s_waitcnt vmcnt(8)
	s_waitcnt lgkmcnt(0)
	s_barrier
; #define PG8_STAGE(bufoff, gbase, voff) do { _Pragma("unroll") for (int _i = 0; _i < 2; ++_i) \
;         __builtin_amdgcn_global_load_lds((const unsigned*)((const char*)(gbase) + (voff)[_i]), (PG8_LAS unsigned*)(lds + (bufoff) + ldsw + _i * 8192), 16, 0, 0); } while (0)
; #define PG8_LDA(dst, b, h) do { _Pragma("unroll") for (int m = 0; m < 4; ++m) _Pragma("unroll") for (int k = 0; k < 2; ++k) dst[m][k] = *(const PG8_LAS bf16x8*)(lds + PG8_SA(b, h) + aoff + m * 2048 + k * 1024); } while (0)
; #define PG8_LDB(dst, b, h) do { _Pragma("unroll") for (int n = 0; n < 2; ++n) _Pragma("unroll") for (int k = 0; k < 2; ++k) dst[n][k] = *(const PG8_LAS bf16x8*)(lds + PG8_SB(b, h) + boff + n * 2048 + k * 1024); } while (0)
; #define PG8_MMA(ai, bj, At, Bt) do { __builtin_amdgcn_s_setprio(1); _Pragma("unroll") for (int m = 0; m < 4; ++m) _Pragma("unroll") for (int n = 0; n < 2; ++n) _Pragma("unroll") for (int k = 0; k < 2; ++k) \
;         acc[ai][bj][m][n] = __builtin_amdgcn_mfma_f32_16x16x32_bf16(Bt[n][k], At[m][k], acc[ai][bj][m][n], 0, 0, 0); __builtin_amdgcn_s_setprio(0); } while (0)
; #define PG8_WAIT_V(n) asm volatile("s_waitcnt vmcnt(" #n ")" ::: "memory")
; #define PG8_WAIT_L(n) asm volatile("s_waitcnt lgkmcnt(" #n ")" ::: "memory")
; #define PG8_BAR __builtin_amdgcn_s_barrier()
; #define PG8_SCHED __builtin_amdgcn_sched_barrier(0)
; template <class Epi, class Sched, bool ALIGN_EPI = false, bool SP2 = false>
; __device__ __forceinline__ void gemm_phase(PG8_LAS unsigned char* lds, const Gemm g, const Sched& S, const Epi& E) {
;     ...
;             PG8_WAIT_V(8); PG8_WAIT_L(0); PG8_BAR; PG8_MMA(1, 0, At, B0); PG8_MMA(1, 1, At, B1); PG8_BAR; PG8_SCHED;
;             PG8_LDB(B0, 1, 0); PG8_LDB(B1, 1, 1); PG8_SCHED; PG8_LDA(At, 1, 0); PG8_STAGE(PG8_SA(0, 1), a2 + hstep, voffA);
;             PG8_WAIT_V(8); PG8_WAIT_L(0); PG8_BAR; PG8_MMA(0, 0, At, B0); PG8_MMA(0, 1, At, B1); PG8_BAR; PG8_SCHED;
	s_setprio 1
	s_waitcnt lgkmcnt(0)
	v_mfma_f32_16x16x32_bf16 v[60:63], v[136:139], v[214:217], v[60:63]
	v_mfma_f32_16x16x32_bf16 v[60:63], v[140:143], v[218:221], v[60:63]
	v_mfma_f32_16x16x32_bf16 v[56:59], v[176:179], v[214:217], v[56:59]
	v_mfma_f32_16x16x32_bf16 v[56:59], v[180:183], v[218:221], v[56:59]
	v_mfma_f32_16x16x32_bf16 v[48:51], v[136:139], v[222:225], v[48:51]
	v_mfma_f32_16x16x32_bf16 v[48:51], v[140:143], v[226:229], v[48:51]
	v_mfma_f32_16x16x32_bf16 v[40:43], v[176:179], v[222:225], v[40:43]
	v_mfma_f32_16x16x32_bf16 v[40:43], v[180:183], v[226:229], v[40:43]
	v_mfma_f32_16x16x32_bf16 v[32:35], v[136:139], v[230:233], v[32:35]
	v_mfma_f32_16x16x32_bf16 v[32:35], v[140:143], v[234:237], v[32:35]
	v_mfma_f32_16x16x32_bf16 v[24:27], v[176:179], v[230:233], v[24:27]
	v_mfma_f32_16x16x32_bf16 v[24:27], v[180:183], v[234:237], v[24:27]
	v_mfma_f32_16x16x32_bf16 v[12:15], v[136:139], v[238:241], v[12:15]
	v_mfma_f32_16x16x32_bf16 v[12:15], v[140:143], v[242:245], v[12:15]
	v_mfma_f32_16x16x32_bf16 v[8:11], v[176:179], v[238:241], v[8:11]
	v_mfma_f32_16x16x32_bf16 v[8:11], v[180:183], v[242:245], v[8:11]
	s_setprio 0
	s_setprio 1
	v_mfma_f32_16x16x32_bf16 v[52:55], v[184:187], v[214:217], v[52:55]
	v_mfma_f32_16x16x32_bf16 v[52:55], v[202:205], v[218:221], v[52:55]
	v_mfma_f32_16x16x32_bf16 v[44:47], v[206:209], v[214:217], v[44:47]
	v_mfma_f32_16x16x32_bf16 v[44:47], v[210:213], v[218:221], v[44:47]
	v_mfma_f32_16x16x32_bf16 v[36:39], v[184:187], v[222:225], v[36:39]
	v_mfma_f32_16x16x32_bf16 v[36:39], v[202:205], v[226:229], v[36:39]
	v_mfma_f32_16x16x32_bf16 v[28:31], v[206:209], v[222:225], v[28:31]
	v_mfma_f32_16x16x32_bf16 v[28:31], v[210:213], v[226:229], v[28:31]
	v_mfma_f32_16x16x32_bf16 v[20:23], v[184:187], v[230:233], v[20:23]
	v_mfma_f32_16x16x32_bf16 v[20:23], v[202:205], v[234:237], v[20:23]
	v_mfma_f32_16x16x32_bf16 v[16:19], v[206:209], v[230:233], v[16:19]
	v_mfma_f32_16x16x32_bf16 v[16:19], v[210:213], v[234:237], v[16:19]
	s_setprio 2
	s_barrier
	v_mfma_f32_16x16x32_bf16 v[4:7], v[184:187], v[238:241], v[4:7]
	v_mfma_f32_16x16x32_bf16 v[4:7], v[202:205], v[242:245], v[4:7]
	v_mfma_f32_16x16x32_bf16 v[0:3], v[206:209], v[238:241], v[0:3]
	v_mfma_f32_16x16x32_bf16 v[0:3], v[210:213], v[242:245], v[0:3]
	s_setprio 0
	s_add_i32 s75, 0, 0x18000
	v_add_u32_e32 v144, s75, v151
	s_add_i32 s76, 0, 0x1c000
	ds_read_b128 v[136:139], v144
	ds_read_b128 v[140:143], v144 offset:1024
	ds_read_b128 v[176:179], v144 offset:2048
	ds_read_b128 v[180:183], v144 offset:3072
	v_add_u32_e32 v144, s76, v151
	ds_read_b128 v[184:187], v144
	ds_read_b128 v[202:205], v144 offset:1024
	ds_read_b128 v[206:209], v144 offset:2048
	ds_read_b128 v[210:213], v144 offset:3072
	s_add_u32 s48, s48, 0x80000
	s_addc_u32 s49, s49, 0
	s_mov_b32 m0, s58
	v_lshl_add_u64 v[200:201], s[48:49], 0, v[164:165]
	ds_read_b128 v[214:217], v163 offset:32768
	ds_read_b128 v[218:221], v163 offset:33792
	ds_read_b128 v[222:225], v163 offset:34816
	ds_read_b128 v[226:229], v163 offset:35840
	ds_read_b128 v[230:233], v163 offset:36864
	ds_read_b128 v[234:237], v163 offset:37888
	ds_read_b128 v[238:241], v163 offset:38912
	ds_read_b128 v[242:245], v163 offset:39936
	global_load_lds_dwordx4 v[200:201], off
	v_lshl_add_u64 v[200:201], s[48:49], 0, v[168:169]
	s_mov_b32 m0, s59
	s_nop 0
	global_load_lds_dwordx4 v[200:201], off
	s_waitcnt vmcnt(8)
	s_waitcnt lgkmcnt(0)
	s_barrier
	s_setprio 1
	s_waitcnt lgkmcnt(0)
	v_mfma_f32_16x16x32_bf16 v[124:127], v[136:139], v[214:217], v[124:127]
	v_mfma_f32_16x16x32_bf16 v[124:127], v[140:143], v[218:221], v[124:127]
	v_mfma_f32_16x16x32_bf16 v[120:123], v[176:179], v[214:217], v[120:123]
	v_mfma_f32_16x16x32_bf16 v[120:123], v[180:183], v[218:221], v[120:123]
	v_mfma_f32_16x16x32_bf16 v[108:111], v[136:139], v[222:225], v[108:111]
	v_mfma_f32_16x16x32_bf16 v[108:111], v[140:143], v[226:229], v[108:111]
	v_mfma_f32_16x16x32_bf16 v[104:107], v[176:179], v[222:225], v[104:107]
	v_mfma_f32_16x16x32_bf16 v[104:107], v[180:183], v[226:229], v[104:107]
	v_mfma_f32_16x16x32_bf16 v[96:99], v[136:139], v[230:233], v[96:99]
	v_mfma_f32_16x16x32_bf16 v[96:99], v[140:143], v[234:237], v[96:99]
	v_mfma_f32_16x16x32_bf16 v[88:91], v[176:179], v[230:233], v[88:91]
	v_mfma_f32_16x16x32_bf16 v[88:91], v[180:183], v[234:237], v[88:91]
	v_mfma_f32_16x16x32_bf16 v[80:83], v[136:139], v[238:241], v[80:83]
	v_mfma_f32_16x16x32_bf16 v[80:83], v[140:143], v[242:245], v[80:83]
	v_mfma_f32_16x16x32_bf16 v[72:75], v[176:179], v[238:241], v[72:75]
	v_mfma_f32_16x16x32_bf16 v[72:75], v[180:183], v[242:245], v[72:75]
	s_setprio 0
	s_setprio 1
	v_mfma_f32_16x16x32_bf16 v[116:119], v[184:187], v[214:217], v[116:119]
	v_mfma_f32_16x16x32_bf16 v[116:119], v[202:205], v[218:221], v[116:119]
	v_mfma_f32_16x16x32_bf16 v[112:115], v[206:209], v[214:217], v[112:115]
	v_mfma_f32_16x16x32_bf16 v[112:115], v[210:213], v[218:221], v[112:115]
	v_mfma_f32_16x16x32_bf16 v[100:103], v[184:187], v[222:225], v[100:103]
	v_mfma_f32_16x16x32_bf16 v[100:103], v[202:205], v[226:229], v[100:103]
	v_mfma_f32_16x16x32_bf16 v[92:95], v[206:209], v[222:225], v[92:95]
	v_mfma_f32_16x16x32_bf16 v[92:95], v[210:213], v[226:229], v[92:95]
	v_mfma_f32_16x16x32_bf16 v[84:87], v[184:187], v[230:233], v[84:87]
	v_mfma_f32_16x16x32_bf16 v[84:87], v[202:205], v[234:237], v[84:87]
	v_mfma_f32_16x16x32_bf16 v[76:79], v[206:209], v[230:233], v[76:79]
	v_mfma_f32_16x16x32_bf16 v[76:79], v[210:213], v[234:237], v[76:79]
	s_setprio 2
	s_barrier
; #define PG8_STAGE(bufoff, gbase, voff) do { _Pragma("unroll") for (int _i = 0; _i < 2; ++_i) \
;         __builtin_amdgcn_global_load_lds((const unsigned*)((const char*)(gbase) + (voff)[_i]), (PG8_LAS unsigned*)(lds + (bufoff) + ldsw + _i * 8192), 16, 0, 0); } while (0)
; #define PG8_LDA(dst, b, h) do { _Pragma("unroll") for (int m = 0; m < 4; ++m) _Pragma("unroll") for (int k = 0; k < 2; ++k) dst[m][k] = *(const PG8_LAS bf16x8*)(lds + PG8_SA(b, h) + aoff + m * 2048 + k * 1024); } while (0)
; #define PG8_MMA(ai, bj, At, Bt) do { __builtin_amdgcn_s_setprio(1); _Pragma("unroll") for (int m = 0; m < 4; ++m) _Pragma("unroll") for (int n = 0; n < 2; ++n) _Pragma("unroll") for (int k = 0; k < 2; ++k) \
;         acc[ai][bj][m][n] = __builtin_amdgcn_mfma_f32_16x16x32_bf16(Bt[n][k], At[m][k], acc[ai][bj][m][n], 0, 0, 0); __builtin_amdgcn_s_setprio(0); } while (0)
; #define PG8_WAIT_V(n) asm volatile("s_waitcnt vmcnt(" #n ")" ::: "memory")
; #define PG8_WAIT_L(n) asm volatile("s_waitcnt lgkmcnt(" #n ")" ::: "memory")
; #define PG8_BAR __builtin_amdgcn_s_barrier()
; #define PG8_SCHED __builtin_amdgcn_sched_barrier(0)
; template <class Epi, class Sched, bool ALIGN_EPI = false, bool SP2 = false>
; __device__ __forceinline__ void gemm_phase(PG8_LAS unsigned char* lds, const Gemm g, const Sched& S, const Epi& E) {
;     ...
;             PG8_LDA(At, 1, 1); PG8_STAGE(PG8_SB(1, 0), b3, voffB); PG8_STAGE(PG8_SB(1, 1), b3 + hstep, voffB); PG8_STAGE(PG8_SA(1, 0), a3, voffA);
;             PG8_WAIT_V(8); PG8_WAIT_L(0); PG8_BAR; PG8_MMA(1, 0, At, B0); PG8_MMA(1, 1, At, B1); PG8_BAR; PG8_SCHED;
;     ...
;         if constexpr (ALIGN_EPI) { if (wr == 0) PG8_BAR; }
	v_mfma_f32_16x16x32_bf16 v[68:71], v[184:187], v[238:241], v[68:71]
	v_mfma_f32_16x16x32_bf16 v[68:71], v[202:205], v[242:245], v[68:71]
	v_mfma_f32_16x16x32_bf16 v[64:67], v[206:209], v[238:241], v[64:67]
	v_mfma_f32_16x16x32_bf16 v[64:67], v[210:213], v[242:245], v[64:67]
	s_setprio 0
	s_add_i32 s48, s75, s45
	v_lshl_add_u64 v[200:201], v[246:247], 0, s[18:19]
	s_mov_b32 m0, s48
	ds_read_b128 v[214:217], v163 offset:49152
	ds_read_b128 v[218:221], v163 offset:50176
	ds_read_b128 v[222:225], v163 offset:51200
	ds_read_b128 v[226:229], v163 offset:52224
	ds_read_b128 v[230:233], v163 offset:53248
	ds_read_b128 v[234:237], v163 offset:54272
	ds_read_b128 v[238:241], v163 offset:55296
	ds_read_b128 v[242:245], v163 offset:56320
	global_load_lds_dwordx4 v[200:201], off
	s_add_i32 m0, s48, 0x2000
	s_add_u32 s28, s28, 0x80080
	v_lshl_add_u64 v[200:201], v[248:249], 0, s[18:19]
	s_addc_u32 s29, s29, 0
	s_add_i32 s48, s76, s45
	global_load_lds_dwordx4 v[200:201], off
	v_lshl_add_u64 v[200:201], s[28:29], 0, v[166:167]
	s_mov_b32 m0, s48
	s_nop 0
	global_load_lds_dwordx4 v[200:201], off
	v_lshl_add_u64 v[200:201], s[28:29], 0, v[170:171]
	s_add_i32 m0, s48, 0x2000
	s_nop 0
	global_load_lds_dwordx4 v[200:201], off
	v_lshl_add_u64 v[200:201], v[250:251], 0, s[18:19]
	s_mov_b32 m0, s61
	s_nop 0
	global_load_lds_dwordx4 v[200:201], off
	v_lshl_add_u64 v[200:201], v[252:253], 0, s[18:19]
	s_mov_b32 m0, s62
	s_nop 0
	global_load_lds_dwordx4 v[200:201], off
	s_waitcnt vmcnt(8)
	s_waitcnt lgkmcnt(0)
	s_barrier
	s_setprio 1
	s_waitcnt lgkmcnt(0)
	v_mfma_f32_16x16x32_bf16 v[60:63], v[136:139], v[214:217], v[60:63]
	v_mfma_f32_16x16x32_bf16 v[60:63], v[140:143], v[218:221], v[60:63]
	v_mfma_f32_16x16x32_bf16 v[56:59], v[176:179], v[214:217], v[56:59]
	v_mfma_f32_16x16x32_bf16 v[56:59], v[180:183], v[218:221], v[56:59]
	v_mfma_f32_16x16x32_bf16 v[48:51], v[136:139], v[222:225], v[48:51]
	v_mfma_f32_16x16x32_bf16 v[48:51], v[140:143], v[226:229], v[48:51]
	v_mfma_f32_16x16x32_bf16 v[40:43], v[176:179], v[222:225], v[40:43]
	v_mfma_f32_16x16x32_bf16 v[40:43], v[180:183], v[226:229], v[40:43]
	v_mfma_f32_16x16x32_bf16 v[32:35], v[136:139], v[230:233], v[32:35]
	v_mfma_f32_16x16x32_bf16 v[32:35], v[140:143], v[234:237], v[32:35]
	v_mfma_f32_16x16x32_bf16 v[24:27], v[176:179], v[230:233], v[24:27]
	v_mfma_f32_16x16x32_bf16 v[24:27], v[180:183], v[234:237], v[24:27]
	v_mfma_f32_16x16x32_bf16 v[12:15], v[136:139], v[238:241], v[12:15]
	v_mfma_f32_16x16x32_bf16 v[12:15], v[140:143], v[242:245], v[12:15]
	v_mfma_f32_16x16x32_bf16 v[8:11], v[176:179], v[238:241], v[8:11]
	v_mfma_f32_16x16x32_bf16 v[8:11], v[180:183], v[242:245], v[8:11]
	s_setprio 0
	s_setprio 1
	v_mfma_f32_16x16x32_bf16 v[52:55], v[184:187], v[214:217], v[52:55]
	v_mfma_f32_16x16x32_bf16 v[52:55], v[202:205], v[218:221], v[52:55]
	v_mfma_f32_16x16x32_bf16 v[44:47], v[206:209], v[214:217], v[44:47]
	v_mfma_f32_16x16x32_bf16 v[44:47], v[210:213], v[218:221], v[44:47]
	v_mfma_f32_16x16x32_bf16 v[36:39], v[184:187], v[222:225], v[36:39]
	v_mfma_f32_16x16x32_bf16 v[36:39], v[202:205], v[226:229], v[36:39]
	v_mfma_f32_16x16x32_bf16 v[28:31], v[206:209], v[222:225], v[28:31]
	v_mfma_f32_16x16x32_bf16 v[28:31], v[210:213], v[226:229], v[28:31]
	v_mfma_f32_16x16x32_bf16 v[20:23], v[184:187], v[230:233], v[20:23]
	v_mfma_f32_16x16x32_bf16 v[20:23], v[202:205], v[234:237], v[20:23]
	v_mfma_f32_16x16x32_bf16 v[16:19], v[206:209], v[230:233], v[16:19]
	v_mfma_f32_16x16x32_bf16 v[16:19], v[210:213], v[234:237], v[16:19]
	s_setprio 2
	s_barrier
	v_mfma_f32_16x16x32_bf16 v[4:7], v[184:187], v[238:241], v[4:7]
	v_mfma_f32_16x16x32_bf16 v[4:7], v[202:205], v[242:245], v[4:7]
	v_mfma_f32_16x16x32_bf16 v[0:3], v[206:209], v[238:241], v[0:3]
	v_mfma_f32_16x16x32_bf16 v[0:3], v[210:213], v[242:245], v[0:3]
	s_setprio 0
	s_add_i32 s74, s74, 2
	s_add_u32 s52, s52, 0x100
	s_addc_u32 s53, s53, 0
	s_add_u32 s72, s72, 0x100
	s_addc_u32 s73, s73, 0
	s_cmp_gt_u32 s74, 29
	s_cbranch_scc0 .LBB0_110
	s_and_b64 vcc, exec, s[20:21]
	s_cbranch_vccz .LBB0_113
	s_barrier

; #define PG8_STAGE(bufoff, gbase, voff) do { _Pragma("unroll") for (int _i = 0; _i < 2; ++_i) \
;         __builtin_amdgcn_global_load_lds((const unsigned*)((const char*)(gbase) + (voff)[_i]), (PG8_LAS unsigned*)(lds + (bufoff) + ldsw + _i * 8192), 16, 0, 0); } while (0)
; #define PG8_LDA(dst, b, h) do { _Pragma("unroll") for (int m = 0; m < 4; ++m) _Pragma("unroll") for (int k = 0; k < 2; ++k) dst[m][k] = *(const PG8_LAS bf16x8*)(lds + PG8_SA(b, h) + aoff + m * 2048 + k * 1024); } while (0)
; #define PG8_LDB(dst, b, h) do { _Pragma("unroll") for (int n = 0; n < 2; ++n) _Pragma("unroll") for (int k = 0; k < 2; ++k) dst[n][k] = *(const PG8_LAS bf16x8*)(lds + PG8_SB(b, h) + boff + n * 2048 + k * 1024); } while (0)
; #define PG8_MMA(ai, bj, At, Bt) do { __builtin_amdgcn_s_setprio(1); _Pragma("unroll") for (int m = 0; m < 4; ++m) _Pragma("unroll") for (int n = 0; n < 2; ++n) _Pragma("unroll") for (int k = 0; k < 2; ++k) \
;         acc[ai][bj][m][n] = __builtin_amdgcn_mfma_f32_16x16x32_bf16(Bt[n][k], At[m][k], acc[ai][bj][m][n], 0, 0, 0); __builtin_amdgcn_s_setprio(0); } while (0)
; #define PG8_WAIT_V(n) asm volatile("s_waitcnt vmcnt(" #n ")" ::: "memory")
; #define PG8_WAIT_L(n) asm volatile("s_waitcnt lgkmcnt(" #n ")" ::: "memory")
; #define PG8_BAR __builtin_amdgcn_s_barrier()
; #define PG8_SCHED __builtin_amdgcn_sched_barrier(0)
; template <class Epi, class Sched, bool ALIGN_EPI = false, bool SP2 = false>
; __device__ __forceinline__ void gemm_phase(PG8_LAS unsigned char* lds, const Gemm g, const Sched& S, const Epi& E) {
;     ...
;             const char* a1 = cA + (size_t)(t + 1) * kstep;
;             const char* a2 = last ? nA : cA + (size_t)(t + 2) * kstep; const char* b2 = last ? nB : cB + (size_t)(t + 2) * kstep;
;             const char* a3 = a2 + kstep; const char* b3 = b2 + kstep;
;             if (last && has_next) S.a_ready(nxt);
;             if constexpr (SP2) {
;             PG8_LDB(B0, 0, 0); PG8_LDB(B1, 0, 1); PG8_SCHED; PG8_LDA(At, 0, 0); PG8_STAGE(PG8_SA(1, 1), a1 + hstep, voffA);
;             PG8_WAIT_V(8); PG8_WAIT_L(0); PG8_BAR; PG8_MMA(0, 0, At, B0); PG8_MMA(0, 1, At, B1); PG8_BAR; PG8_SCHED;
;             PG8_LDA(At, 0, 1); PG8_STAGE(PG8_SB(0, 0), b2, voffB); PG8_STAGE(PG8_SB(0, 1), b2 + hstep, voffB); PG8_STAGE(PG8_SA(0, 0), a2, voffA);
.LBB0_177:
	ds_read_b128 v[80:83], v171
	ds_read_b128 v[84:87], v171 offset:1024
	ds_read_b128 v[92:95], v171 offset:2048
	ds_read_b128 v[100:103], v171 offset:3072
	ds_read_b128 v[144:147], v206
	ds_read_b128 v[148:151], v206 offset:1024
	ds_read_b128 v[152:155], v206 offset:2048
	ds_read_b128 v[156:159], v206 offset:3072
	s_add_u32 s28, s72, 0xffea0080
	s_addc_u32 s29, s73, -1
	s_cmpk_eq_i32 s76, 0x54
	s_cselect_b32 s49, s69, s29
	s_cselect_b32 s48, s68, s28
	s_cselect_b32 s29, s71, s35
	s_cselect_b32 s28, s70, s34
	v_lshl_add_u64 v[234:235], s[72:73], 0, v[174:175]
	s_add_i32 m0, s40, 0xc000
	ds_read_b128 v[180:183], v207
	ds_read_b128 v[184:187], v207 offset:1024
	ds_read_b128 v[210:213], v207 offset:2048
	ds_read_b128 v[214:217], v207 offset:3072
	ds_read_b128 v[218:221], v207 offset:4096
	ds_read_b128 v[222:225], v207 offset:5120
	ds_read_b128 v[226:229], v207 offset:6144
	ds_read_b128 v[230:233], v207 offset:7168
	global_load_lds_dwordx4 v[234:235], off
	v_lshl_add_u64 v[234:235], s[72:73], 0, v[176:177]
	s_add_i32 m0, s40, 0xe000
	s_nop 0
	global_load_lds_dwordx4 v[234:235], off
	s_waitcnt vmcnt(8)
	s_waitcnt lgkmcnt(0)
	s_barrier
	s_setprio 1
	s_waitcnt lgkmcnt(0)
	v_mfma_f32_16x16x32_bf16 v[140:143], v[80:83], v[180:183], v[140:143]
	v_mfma_f32_16x16x32_bf16 v[140:143], v[84:87], v[184:187], v[140:143]
	v_mfma_f32_16x16x32_bf16 v[136:139], v[92:95], v[180:183], v[136:139]
	v_mfma_f32_16x16x32_bf16 v[136:139], v[100:103], v[184:187], v[136:139]
	v_mfma_f32_16x16x32_bf16 v[124:127], v[80:83], v[210:213], v[124:127]
	v_mfma_f32_16x16x32_bf16 v[124:127], v[84:87], v[214:217], v[124:127]
	v_mfma_f32_16x16x32_bf16 v[120:123], v[92:95], v[210:213], v[120:123]
	v_mfma_f32_16x16x32_bf16 v[120:123], v[100:103], v[214:217], v[120:123]
	v_mfma_f32_16x16x32_bf16 v[108:111], v[80:83], v[218:221], v[108:111]
	v_mfma_f32_16x16x32_bf16 v[108:111], v[84:87], v[222:225], v[108:111]
	v_mfma_f32_16x16x32_bf16 v[104:107], v[92:95], v[218:221], v[104:107]
	v_mfma_f32_16x16x32_bf16 v[104:107], v[100:103], v[222:225], v[104:107]
	v_mfma_f32_16x16x32_bf16 v[76:79], v[80:83], v[226:229], v[76:79]
	v_mfma_f32_16x16x32_bf16 v[76:79], v[84:87], v[230:233], v[76:79]
	v_mfma_f32_16x16x32_bf16 v[72:75], v[92:95], v[226:229], v[72:75]
	v_mfma_f32_16x16x32_bf16 v[72:75], v[100:103], v[230:233], v[72:75]
	s_setprio 0
	s_setprio 1
	v_mfma_f32_16x16x32_bf16 v[132:135], v[144:147], v[180:183], v[132:135]
	v_mfma_f32_16x16x32_bf16 v[132:135], v[148:151], v[184:187], v[132:135]
	v_mfma_f32_16x16x32_bf16 v[128:131], v[152:155], v[180:183], v[128:131]
	v_mfma_f32_16x16x32_bf16 v[128:131], v[156:159], v[184:187], v[128:131]
	v_mfma_f32_16x16x32_bf16 v[116:119], v[144:147], v[210:213], v[116:119]
	v_mfma_f32_16x16x32_bf16 v[116:119], v[148:151], v[214:217], v[116:119]
	v_mfma_f32_16x16x32_bf16 v[112:115], v[152:155], v[210:213], v[112:115]
	v_mfma_f32_16x16x32_bf16 v[112:115], v[156:159], v[214:217], v[112:115]
	v_mfma_f32_16x16x32_bf16 v[96:99], v[144:147], v[218:221], v[96:99]
	v_mfma_f32_16x16x32_bf16 v[96:99], v[148:151], v[222:225], v[96:99]
	v_mfma_f32_16x16x32_bf16 v[88:91], v[152:155], v[218:221], v[88:91]
	v_mfma_f32_16x16x32_bf16 v[88:91], v[156:159], v[222:225], v[88:91]
	s_setprio 2
	s_barrier
	v_mfma_f32_16x16x32_bf16 v[68:71], v[144:147], v[226:229], v[68:71]
	v_mfma_f32_16x16x32_bf16 v[68:71], v[148:151], v[230:233], v[68:71]
	v_mfma_f32_16x16x32_bf16 v[64:67], v[152:155], v[226:229], v[64:67]
	v_mfma_f32_16x16x32_bf16 v[64:67], v[156:159], v[230:233], v[64:67]
	s_setprio 0
	s_add_i32 s77, s61, s13
	v_lshl_add_u64 v[234:235], s[28:29], 0, v[160:161]
	s_mov_b32 m0, s77
	ds_read_b128 v[180:183], v207 offset:16384
	ds_read_b128 v[184:187], v207 offset:17408
	ds_read_b128 v[210:213], v207 offset:18432
	ds_read_b128 v[214:217], v207 offset:19456
	ds_read_b128 v[218:221], v207 offset:20480
	ds_read_b128 v[222:225], v207 offset:21504
	ds_read_b128 v[226:229], v207 offset:22528
	ds_read_b128 v[230:233], v207 offset:23552
	global_load_lds_dwordx4 v[234:235], off
	s_add_i32 m0, s77, 0x2000
	s_add_u32 s78, s28, 0x160000
	v_lshl_add_u64 v[236:237], s[28:29], 0, v[162:163]
	s_addc_u32 s79, s29, 0
	s_add_i32 s77, s62, s13
	global_load_lds_dwordx4 v[236:237], off
	v_lshl_add_u64 v[238:239], s[78:79], 0, v[160:161]
	s_mov_b32 m0, s77
	v_lshl_add_u64 v[240:241], s[48:49], 0, v[162:163]
	global_load_lds_dwordx4 v[238:239], off
	v_lshl_add_u64 v[238:239], s[78:79], 0, v[162:163]
	s_add_i32 m0, s77, 0x2000
	s_nop 0
	global_load_lds_dwordx4 v[238:239], off
	v_lshl_add_u64 v[238:239], s[48:49], 0, v[160:161]
	s_mov_b32 m0, s40
	s_nop 0
	global_load_lds_dwordx4 v[238:239], off
	s_mov_b32 m0, s41
	s_nop 0
	global_load_lds_dwordx4 v[240:241], off
	s_waitcnt vmcnt(8)
	s_waitcnt lgkmcnt(0)
	s_barrier
; #define PG8_STAGE(bufoff, gbase, voff) do { _Pragma("unroll") for (int _i = 0; _i < 2; ++_i) \
;         __builtin_amdgcn_global_load_lds((const unsigned*)((const char*)(gbase) + (voff)[_i]), (PG8_LAS unsigned*)(lds + (bufoff) + ldsw + _i * 8192), 16, 0, 0); } while (0)
; #define PG8_LDA(dst, b, h) do { _Pragma("unroll") for (int m = 0; m < 4; ++m) _Pragma("unroll") for (int k = 0; k < 2; ++k) dst[m][k] = *(const PG8_LAS bf16x8*)(lds + PG8_SA(b, h) + aoff + m * 2048 + k * 1024); } while (0)
; #define PG8_LDB(dst, b, h) do { _Pragma("unroll") for (int n = 0; n < 2; ++n) _Pragma("unroll") for (int k = 0; k < 2; ++k) dst[n][k] = *(const PG8_LAS bf16x8*)(lds + PG8_SB(b, h) + boff + n * 2048 + k * 1024); } while (0)
; #define PG8_MMA(ai, bj, At, Bt) do { __builtin_amdgcn_s_setprio(1); _Pragma("unroll") for (int m = 0; m < 4; ++m) _Pragma("unroll") for (int n = 0; n < 2; ++n) _Pragma("unroll") for (int k = 0; k < 2; ++k) \
;         acc[ai][bj][m][n] = __builtin_amdgcn_mfma_f32_16x16x32_bf16(Bt[n][k], At[m][k], acc[ai][bj][m][n], 0, 0, 0); __builtin_amdgcn_s_setprio(0); } while (0)
; #define PG8_WAIT_V(n) asm volatile("s_waitcnt vmcnt(" #n ")" ::: "memory")
; #define PG8_WAIT_L(n) asm volatile("s_waitcnt lgkmcnt(" #n ")" ::: "memory")
; #define PG8_BAR __builtin_amdgcn_s_barrier()
; #define PG8_SCHED __builtin_amdgcn_sched_barrier(0)
; template <class Epi, class Sched, bool ALIGN_EPI = false, bool SP2 = false>
; __device__ __forceinline__ void gemm_phase(PG8_LAS unsigned char* lds, const Gemm g, const Sched& S, const Epi& E) {
;     ...
;             PG8_WAIT_V(8); PG8_WAIT_L(0); PG8_BAR; PG8_MMA(1, 0, At, B0); PG8_MMA(1, 1, At, B1); PG8_BAR; PG8_SCHED;
;             PG8_LDB(B0, 1, 0); PG8_LDB(B1, 1, 1); PG8_SCHED; PG8_LDA(At, 1, 0); PG8_STAGE(PG8_SA(0, 1), a2 + hstep, voffA);
;             PG8_WAIT_V(8); PG8_WAIT_L(0); PG8_BAR; PG8_MMA(0, 0, At, B0); PG8_MMA(0, 1, At, B1); PG8_BAR; PG8_SCHED;
	s_setprio 1
	s_waitcnt lgkmcnt(0)
	v_mfma_f32_16x16x32_bf16 v[60:63], v[80:83], v[180:183], v[60:63]
	v_mfma_f32_16x16x32_bf16 v[60:63], v[84:87], v[184:187], v[60:63]
	v_mfma_f32_16x16x32_bf16 v[56:59], v[92:95], v[180:183], v[56:59]
	v_mfma_f32_16x16x32_bf16 v[56:59], v[100:103], v[184:187], v[56:59]
	v_mfma_f32_16x16x32_bf16 v[44:47], v[80:83], v[210:213], v[44:47]
	v_mfma_f32_16x16x32_bf16 v[44:47], v[84:87], v[214:217], v[44:47]
	v_mfma_f32_16x16x32_bf16 v[40:43], v[92:95], v[210:213], v[40:43]
	v_mfma_f32_16x16x32_bf16 v[40:43], v[100:103], v[214:217], v[40:43]
	v_mfma_f32_16x16x32_bf16 v[28:31], v[80:83], v[218:221], v[28:31]
	v_mfma_f32_16x16x32_bf16 v[28:31], v[84:87], v[222:225], v[28:31]
	v_mfma_f32_16x16x32_bf16 v[24:27], v[92:95], v[218:221], v[24:27]
	v_mfma_f32_16x16x32_bf16 v[24:27], v[100:103], v[222:225], v[24:27]
	v_mfma_f32_16x16x32_bf16 v[12:15], v[80:83], v[226:229], v[12:15]
	v_mfma_f32_16x16x32_bf16 v[12:15], v[84:87], v[230:233], v[12:15]
	v_mfma_f32_16x16x32_bf16 v[8:11], v[92:95], v[226:229], v[8:11]
	v_mfma_f32_16x16x32_bf16 v[8:11], v[100:103], v[230:233], v[8:11]
	s_setprio 0
	s_setprio 1
	v_mfma_f32_16x16x32_bf16 v[52:55], v[144:147], v[180:183], v[52:55]
	v_mfma_f32_16x16x32_bf16 v[52:55], v[148:151], v[184:187], v[52:55]
	v_mfma_f32_16x16x32_bf16 v[48:51], v[152:155], v[180:183], v[48:51]
	v_mfma_f32_16x16x32_bf16 v[48:51], v[156:159], v[184:187], v[48:51]
	v_mfma_f32_16x16x32_bf16 v[36:39], v[144:147], v[210:213], v[36:39]
	v_mfma_f32_16x16x32_bf16 v[36:39], v[148:151], v[214:217], v[36:39]
	v_mfma_f32_16x16x32_bf16 v[32:35], v[152:155], v[210:213], v[32:35]
	v_mfma_f32_16x16x32_bf16 v[32:35], v[156:159], v[214:217], v[32:35]
	v_mfma_f32_16x16x32_bf16 v[20:23], v[144:147], v[218:221], v[20:23]
	v_mfma_f32_16x16x32_bf16 v[20:23], v[148:151], v[222:225], v[20:23]
	v_mfma_f32_16x16x32_bf16 v[16:19], v[152:155], v[218:221], v[16:19]
	v_mfma_f32_16x16x32_bf16 v[16:19], v[156:159], v[222:225], v[16:19]
	s_setprio 2
	s_barrier
	v_mfma_f32_16x16x32_bf16 v[4:7], v[144:147], v[226:229], v[4:7]
	v_mfma_f32_16x16x32_bf16 v[4:7], v[148:151], v[230:233], v[4:7]
	v_mfma_f32_16x16x32_bf16 v[0:3], v[152:155], v[226:229], v[0:3]
	v_mfma_f32_16x16x32_bf16 v[0:3], v[156:159], v[230:233], v[0:3]
	s_setprio 0
	s_add_i32 s77, 0, 0x18000
	s_add_i32 s78, 0, 0x1c000
	v_add_u32_e32 v100, s77, v167
	v_add_u32_e32 v156, s78, v167
	ds_read_b128 v[80:83], v100
	ds_read_b128 v[84:87], v100 offset:1024
	ds_read_b128 v[92:95], v100 offset:2048
	ds_read_b128 v[100:103], v100 offset:3072
	ds_read_b128 v[144:147], v156
	ds_read_b128 v[148:151], v156 offset:1024
	ds_read_b128 v[152:155], v156 offset:2048
	ds_read_b128 v[156:159], v156 offset:3072
	s_add_u32 s48, s48, 0x160000
	s_addc_u32 s49, s49, 0
	s_mov_b32 m0, s44
	v_lshl_add_u64 v[242:243], s[48:49], 0, v[160:161]
	ds_read_b128 v[180:183], v207 offset:32768
	ds_read_b128 v[184:187], v207 offset:33792
	ds_read_b128 v[210:213], v207 offset:34816
	ds_read_b128 v[214:217], v207 offset:35840
	ds_read_b128 v[218:221], v207 offset:36864
	ds_read_b128 v[222:225], v207 offset:37888
	ds_read_b128 v[226:229], v207 offset:38912
	ds_read_b128 v[230:233], v207 offset:39936
	global_load_lds_dwordx4 v[242:243], off
	v_lshl_add_u64 v[242:243], s[48:49], 0, v[162:163]
	s_mov_b32 m0, s45
	s_nop 0
	global_load_lds_dwordx4 v[242:243], off
	s_waitcnt vmcnt(8)
	s_waitcnt lgkmcnt(0)
	s_barrier
	s_setprio 1
	s_waitcnt lgkmcnt(0)
	v_mfma_f32_16x16x32_bf16 v[140:143], v[80:83], v[180:183], v[140:143]
	v_mfma_f32_16x16x32_bf16 v[140:143], v[84:87], v[184:187], v[140:143]
	v_mfma_f32_16x16x32_bf16 v[136:139], v[92:95], v[180:183], v[136:139]
	v_mfma_f32_16x16x32_bf16 v[136:139], v[100:103], v[184:187], v[136:139]
	v_mfma_f32_16x16x32_bf16 v[124:127], v[80:83], v[210:213], v[124:127]
	v_mfma_f32_16x16x32_bf16 v[124:127], v[84:87], v[214:217], v[124:127]
	v_mfma_f32_16x16x32_bf16 v[120:123], v[92:95], v[210:213], v[120:123]
	v_mfma_f32_16x16x32_bf16 v[120:123], v[100:103], v[214:217], v[120:123]
	v_mfma_f32_16x16x32_bf16 v[108:111], v[80:83], v[218:221], v[108:111]
	v_mfma_f32_16x16x32_bf16 v[108:111], v[84:87], v[222:225], v[108:111]
	v_mfma_f32_16x16x32_bf16 v[104:107], v[92:95], v[218:221], v[104:107]
	v_mfma_f32_16x16x32_bf16 v[104:107], v[100:103], v[222:225], v[104:107]
	v_mfma_f32_16x16x32_bf16 v[76:79], v[80:83], v[226:229], v[76:79]
	v_mfma_f32_16x16x32_bf16 v[76:79], v[84:87], v[230:233], v[76:79]
	v_mfma_f32_16x16x32_bf16 v[72:75], v[92:95], v[226:229], v[72:75]
	v_mfma_f32_16x16x32_bf16 v[72:75], v[100:103], v[230:233], v[72:75]
	s_setprio 0
	s_setprio 1
	v_mfma_f32_16x16x32_bf16 v[132:135], v[144:147], v[180:183], v[132:135]
	v_mfma_f32_16x16x32_bf16 v[132:135], v[148:151], v[184:187], v[132:135]
	v_mfma_f32_16x16x32_bf16 v[128:131], v[152:155], v[180:183], v[128:131]
	v_mfma_f32_16x16x32_bf16 v[128:131], v[156:159], v[184:187], v[128:131]
	v_mfma_f32_16x16x32_bf16 v[116:119], v[144:147], v[210:213], v[116:119]
	v_mfma_f32_16x16x32_bf16 v[116:119], v[148:151], v[214:217], v[116:119]
	v_mfma_f32_16x16x32_bf16 v[112:115], v[152:155], v[210:213], v[112:115]
	v_mfma_f32_16x16x32_bf16 v[112:115], v[156:159], v[214:217], v[112:115]
	v_mfma_f32_16x16x32_bf16 v[96:99], v[144:147], v[218:221], v[96:99]
	v_mfma_f32_16x16x32_bf16 v[96:99], v[148:151], v[222:225], v[96:99]
	v_mfma_f32_16x16x32_bf16 v[88:91], v[152:155], v[218:221], v[88:91]
	v_mfma_f32_16x16x32_bf16 v[88:91], v[156:159], v[222:225], v[88:91]
	s_setprio 2
	s_barrier
; #define PG8_STAGE(bufoff, gbase, voff) do { _Pragma("unroll") for (int _i = 0; _i < 2; ++_i) \
;         __builtin_amdgcn_global_load_lds((const unsigned*)((const char*)(gbase) + (voff)[_i]), (PG8_LAS unsigned*)(lds + (bufoff) + ldsw + _i * 8192), 16, 0, 0); } while (0)
; #define PG8_LDA(dst, b, h) do { _Pragma("unroll") for (int m = 0; m < 4; ++m) _Pragma("unroll") for (int k = 0; k < 2; ++k) dst[m][k] = *(const PG8_LAS bf16x8*)(lds + PG8_SA(b, h) + aoff + m * 2048 + k * 1024); } while (0)
; #define PG8_MMA(ai, bj, At, Bt) do { __builtin_amdgcn_s_setprio(1); _Pragma("unroll") for (int m = 0; m < 4; ++m) _Pragma("unroll") for (int n = 0; n < 2; ++n) _Pragma("unroll") for (int k = 0; k < 2; ++k) \
;         acc[ai][bj][m][n] = __builtin_amdgcn_mfma_f32_16x16x32_bf16(Bt[n][k], At[m][k], acc[ai][bj][m][n], 0, 0, 0); __builtin_amdgcn_s_setprio(0); } while (0)
; #define PG8_WAIT_V(n) asm volatile("s_waitcnt vmcnt(" #n ")" ::: "memory")
; #define PG8_WAIT_L(n) asm volatile("s_waitcnt lgkmcnt(" #n ")" ::: "memory")
; #define PG8_BAR __builtin_amdgcn_s_barrier()
; #define PG8_SCHED __builtin_amdgcn_sched_barrier(0)
; template <class Epi, class Sched, bool ALIGN_EPI = false, bool SP2 = false>
; __device__ __forceinline__ void gemm_phase(PG8_LAS unsigned char* lds, const Gemm g, const Sched& S, const Epi& E) {
;     ...
;             PG8_LDA(At, 1, 1); PG8_STAGE(PG8_SB(1, 0), b3, voffB); PG8_STAGE(PG8_SB(1, 1), b3 + hstep, voffB); PG8_STAGE(PG8_SA(1, 0), a3, voffA);
;             PG8_WAIT_V(8); PG8_WAIT_L(0); PG8_BAR; PG8_MMA(1, 0, At, B0); PG8_MMA(1, 1, At, B1); PG8_BAR; PG8_SCHED;
;     ...
;         if constexpr (ALIGN_EPI) { if (wr == 0) PG8_BAR; }
	v_mfma_f32_16x16x32_bf16 v[68:71], v[144:147], v[226:229], v[68:71]
	v_mfma_f32_16x16x32_bf16 v[68:71], v[148:151], v[230:233], v[68:71]
	v_mfma_f32_16x16x32_bf16 v[64:67], v[152:155], v[226:229], v[64:67]
	v_mfma_f32_16x16x32_bf16 v[64:67], v[156:159], v[230:233], v[64:67]
	s_setprio 0
	s_add_i32 s48, s77, s13
	v_lshl_add_u64 v[234:235], v[234:235], 0, s[50:51]
	s_mov_b32 m0, s48
	ds_read_b128 v[180:183], v207 offset:49152
	ds_read_b128 v[184:187], v207 offset:50176
	ds_read_b128 v[210:213], v207 offset:51200
	ds_read_b128 v[214:217], v207 offset:52224
	ds_read_b128 v[218:221], v207 offset:53248
	ds_read_b128 v[222:225], v207 offset:54272
	ds_read_b128 v[226:229], v207 offset:55296
	ds_read_b128 v[230:233], v207 offset:56320
	global_load_lds_dwordx4 v[234:235], off
	s_add_i32 m0, s48, 0x2000
	s_add_u32 s28, s28, 0x160080
	v_lshl_add_u64 v[234:235], v[236:237], 0, s[50:51]
	s_addc_u32 s29, s29, 0
	s_add_i32 s48, s78, s13
	global_load_lds_dwordx4 v[234:235], off
	v_lshl_add_u64 v[234:235], s[28:29], 0, v[160:161]
	s_mov_b32 m0, s48
	s_nop 0
	global_load_lds_dwordx4 v[234:235], off
	v_lshl_add_u64 v[234:235], s[28:29], 0, v[162:163]
	s_add_i32 m0, s48, 0x2000
	s_nop 0
	global_load_lds_dwordx4 v[234:235], off
	v_lshl_add_u64 v[234:235], v[238:239], 0, s[50:51]
	s_mov_b32 m0, s56
	s_nop 0
	global_load_lds_dwordx4 v[234:235], off
	v_lshl_add_u64 v[234:235], v[240:241], 0, s[50:51]
	s_mov_b32 m0, s57
	s_nop 0
	global_load_lds_dwordx4 v[234:235], off
	s_waitcnt vmcnt(8)
	s_waitcnt lgkmcnt(0)
	s_barrier
	s_setprio 1
	s_waitcnt lgkmcnt(0)
	v_mfma_f32_16x16x32_bf16 v[60:63], v[80:83], v[180:183], v[60:63]
	v_mfma_f32_16x16x32_bf16 v[60:63], v[84:87], v[184:187], v[60:63]
	v_mfma_f32_16x16x32_bf16 v[56:59], v[92:95], v[180:183], v[56:59]
	v_mfma_f32_16x16x32_bf16 v[56:59], v[100:103], v[184:187], v[56:59]
	v_mfma_f32_16x16x32_bf16 v[44:47], v[80:83], v[210:213], v[44:47]
	v_mfma_f32_16x16x32_bf16 v[44:47], v[84:87], v[214:217], v[44:47]
	v_mfma_f32_16x16x32_bf16 v[40:43], v[92:95], v[210:213], v[40:43]
	v_mfma_f32_16x16x32_bf16 v[40:43], v[100:103], v[214:217], v[40:43]
	v_mfma_f32_16x16x32_bf16 v[28:31], v[80:83], v[218:221], v[28:31]
	v_mfma_f32_16x16x32_bf16 v[28:31], v[84:87], v[222:225], v[28:31]
	v_mfma_f32_16x16x32_bf16 v[24:27], v[92:95], v[218:221], v[24:27]
	v_mfma_f32_16x16x32_bf16 v[24:27], v[100:103], v[222:225], v[24:27]
	v_mfma_f32_16x16x32_bf16 v[12:15], v[80:83], v[226:229], v[12:15]
	v_mfma_f32_16x16x32_bf16 v[12:15], v[84:87], v[230:233], v[12:15]
	v_mfma_f32_16x16x32_bf16 v[8:11], v[92:95], v[226:229], v[8:11]
	v_mfma_f32_16x16x32_bf16 v[8:11], v[100:103], v[230:233], v[8:11]
	s_setprio 0
	s_setprio 1
	v_mfma_f32_16x16x32_bf16 v[52:55], v[144:147], v[180:183], v[52:55]
	v_mfma_f32_16x16x32_bf16 v[52:55], v[148:151], v[184:187], v[52:55]
	v_mfma_f32_16x16x32_bf16 v[48:51], v[152:155], v[180:183], v[48:51]
	v_mfma_f32_16x16x32_bf16 v[48:51], v[156:159], v[184:187], v[48:51]
	v_mfma_f32_16x16x32_bf16 v[36:39], v[144:147], v[210:213], v[36:39]
	v_mfma_f32_16x16x32_bf16 v[36:39], v[148:151], v[214:217], v[36:39]
	v_mfma_f32_16x16x32_bf16 v[32:35], v[152:155], v[210:213], v[32:35]
	v_mfma_f32_16x16x32_bf16 v[32:35], v[156:159], v[214:217], v[32:35]
	v_mfma_f32_16x16x32_bf16 v[20:23], v[144:147], v[218:221], v[20:23]
	v_mfma_f32_16x16x32_bf16 v[20:23], v[148:151], v[222:225], v[20:23]
	v_mfma_f32_16x16x32_bf16 v[16:19], v[152:155], v[218:221], v[16:19]
	v_mfma_f32_16x16x32_bf16 v[16:19], v[156:159], v[222:225], v[16:19]
	s_setprio 2
	s_barrier
	v_mfma_f32_16x16x32_bf16 v[4:7], v[144:147], v[226:229], v[4:7]
	v_mfma_f32_16x16x32_bf16 v[4:7], v[148:151], v[230:233], v[4:7]
	v_mfma_f32_16x16x32_bf16 v[0:3], v[152:155], v[226:229], v[0:3]
	v_mfma_f32_16x16x32_bf16 v[0:3], v[156:159], v[230:233], v[0:3]
	s_setprio 0
	s_add_i32 s76, s76, 2
	s_add_u32 s72, s72, 0x100
	s_addc_u32 s73, s73, 0
	s_add_u32 s34, s34, 0x100
	s_addc_u32 s35, s35, 0
	s_cmpk_gt_u32 s76, 0x55
	s_cbranch_scc0 .LBB0_177
	s_and_b64 vcc, exec, s[52:53]
	s_cbranch_vccz .LBB0_180
	s_barrier

; #define PG8_STAGE(bufoff, gbase, voff) do { _Pragma("unroll") for (int _i = 0; _i < 2; ++_i) \
;         __builtin_amdgcn_global_load_lds((const unsigned*)((const char*)(gbase) + (voff)[_i]), (PG8_LAS unsigned*)(lds + (bufoff) + ldsw + _i * 8192), 16, 0, 0); } while (0)
; #define PG8_LDA(dst, b, h) do { _Pragma("unroll") for (int m = 0; m < 4; ++m) _Pragma("unroll") for (int k = 0; k < 2; ++k) dst[m][k] = *(const PG8_LAS bf16x8*)(lds + PG8_SA(b, h) + aoff + m * 2048 + k * 1024); } while (0)
; #define PG8_LDB(dst, b, h) do { _Pragma("unroll") for (int n = 0; n < 2; ++n) _Pragma("unroll") for (int k = 0; k < 2; ++k) dst[n][k] = *(const PG8_LAS bf16x8*)(lds + PG8_SB(b, h) + boff + n * 2048 + k * 1024); } while (0)
; #define PG8_MMA(ai, bj, At, Bt) do { __builtin_amdgcn_s_setprio(1); _Pragma("unroll") for (int m = 0; m < 4; ++m) _Pragma("unroll") for (int n = 0; n < 2; ++n) _Pragma("unroll") for (int k = 0; k < 2; ++k) \
;         acc[ai][bj][m][n] = __builtin_amdgcn_mfma_f32_16x16x32_bf16(Bt[n][k], At[m][k], acc[ai][bj][m][n], 0, 0, 0); __builtin_amdgcn_s_setprio(0); } while (0)
; #define PG8_WAIT_V(n) asm volatile("s_waitcnt vmcnt(" #n ")" ::: "memory")
; #define PG8_WAIT_L(n) asm volatile("s_waitcnt lgkmcnt(" #n ")" ::: "memory")
; #define PG8_BAR __builtin_amdgcn_s_barrier()
; #define PG8_SCHED __builtin_amdgcn_sched_barrier(0)
; template <class Epi, class Sched, bool ALIGN_EPI = false, bool SP2 = false>
; __device__ __forceinline__ void gemm_phase(PG8_LAS unsigned char* lds, const Gemm g, const Sched& S, const Epi& E) {
;     ...
;             const char* a1 = cA + (size_t)(t + 1) * kstep;
;             const char* a2 = last ? nA : cA + (size_t)(t + 2) * kstep; const char* b2 = last ? nB : cB + (size_t)(t + 2) * kstep;
;             const char* a3 = a2 + kstep; const char* b3 = b2 + kstep;
;             if (last && has_next) S.a_ready(nxt);
;             if constexpr (SP2) {
;             PG8_LDB(B0, 0, 0); PG8_LDB(B1, 0, 1); PG8_SCHED; PG8_LDA(At, 0, 0); PG8_STAGE(PG8_SA(1, 1), a1 + hstep, voffA);
;             PG8_WAIT_V(8); PG8_WAIT_L(0); PG8_BAR; PG8_MMA(0, 0, At, B0); PG8_MMA(0, 1, At, B1); PG8_BAR; PG8_SCHED;
;             PG8_LDA(At, 0, 1); PG8_STAGE(PG8_SB(0, 0), b2, voffB); PG8_STAGE(PG8_SB(0, 1), b2 + hstep, voffB); PG8_STAGE(PG8_SA(0, 0), a2, voffA);
.LBB0_231:
	ds_read_b128 v[142:145], v153
	ds_read_b128 v[146:149], v153 offset:1024
	ds_read_b128 v[174:177], v153 offset:2048
	ds_read_b128 v[178:181], v153 offset:3072
	ds_read_b128 v[182:185], v154
	ds_read_b128 v[206:209], v154 offset:1024
	ds_read_b128 v[210:213], v154 offset:2048
	ds_read_b128 v[214:217], v154 offset:3072
	s_add_u32 s28, s84, 0xfff80080
	s_addc_u32 s29, s85, -1
	s_cmp_eq_u32 s97, 28
	s_cselect_b32 s49, s34, s29
	s_cselect_b32 s48, s35, s28
	s_cselect_b32 s29, s75, s96
	s_cselect_b32 s28, s77, s95
	v_lshl_add_u64 v[158:159], s[84:85], 0, v[134:135]
	s_add_i32 m0, s56, 0xc000
	ds_read_b128 v[218:221], v155
	ds_read_b128 v[222:225], v155 offset:1024
	ds_read_b128 v[226:229], v155 offset:2048
	ds_read_b128 v[230:233], v155 offset:3072
	ds_read_b128 v[234:237], v155 offset:4096
	ds_read_b128 v[238:241], v155 offset:5120
	ds_read_b128 v[242:245], v155 offset:6144
	ds_read_b128 v[246:249], v155 offset:7168
	global_load_lds_dwordx4 v[158:159], off
	v_lshl_add_u64 v[158:159], s[84:85], 0, v[136:137]
	s_add_i32 m0, s56, 0xe000
	s_nop 0
	global_load_lds_dwordx4 v[158:159], off
	s_waitcnt vmcnt(8)
	s_waitcnt lgkmcnt(0)
	s_barrier
	s_setprio 1
	s_waitcnt lgkmcnt(0)
	v_mfma_f32_16x16x32_bf16 v[124:127], v[142:145], v[218:221], v[124:127]
	v_mfma_f32_16x16x32_bf16 v[124:127], v[146:149], v[222:225], v[124:127]
	v_mfma_f32_16x16x32_bf16 v[120:123], v[174:177], v[218:221], v[120:123]
	v_mfma_f32_16x16x32_bf16 v[120:123], v[178:181], v[222:225], v[120:123]
	v_mfma_f32_16x16x32_bf16 v[108:111], v[142:145], v[226:229], v[108:111]
	v_mfma_f32_16x16x32_bf16 v[108:111], v[146:149], v[230:233], v[108:111]
	v_mfma_f32_16x16x32_bf16 v[104:107], v[174:177], v[226:229], v[104:107]
	v_mfma_f32_16x16x32_bf16 v[104:107], v[178:181], v[230:233], v[104:107]
	v_mfma_f32_16x16x32_bf16 v[92:95], v[142:145], v[234:237], v[92:95]
	v_mfma_f32_16x16x32_bf16 v[92:95], v[146:149], v[238:241], v[92:95]
	v_mfma_f32_16x16x32_bf16 v[88:91], v[174:177], v[234:237], v[88:91]
	v_mfma_f32_16x16x32_bf16 v[88:91], v[178:181], v[238:241], v[88:91]
	v_mfma_f32_16x16x32_bf16 v[76:79], v[142:145], v[242:245], v[76:79]
	v_mfma_f32_16x16x32_bf16 v[76:79], v[146:149], v[246:249], v[76:79]
	v_mfma_f32_16x16x32_bf16 v[72:75], v[174:177], v[242:245], v[72:75]
	v_mfma_f32_16x16x32_bf16 v[72:75], v[178:181], v[246:249], v[72:75]
	s_setprio 0
	s_setprio 1
	v_mfma_f32_16x16x32_bf16 v[116:119], v[182:185], v[218:221], v[116:119]
	v_mfma_f32_16x16x32_bf16 v[116:119], v[206:209], v[222:225], v[116:119]
	v_mfma_f32_16x16x32_bf16 v[112:115], v[210:213], v[218:221], v[112:115]
	v_mfma_f32_16x16x32_bf16 v[112:115], v[214:217], v[222:225], v[112:115]
	v_mfma_f32_16x16x32_bf16 v[100:103], v[182:185], v[226:229], v[100:103]
	v_mfma_f32_16x16x32_bf16 v[100:103], v[206:209], v[230:233], v[100:103]
	v_mfma_f32_16x16x32_bf16 v[96:99], v[210:213], v[226:229], v[96:99]
	v_mfma_f32_16x16x32_bf16 v[96:99], v[214:217], v[230:233], v[96:99]
	v_mfma_f32_16x16x32_bf16 v[84:87], v[182:185], v[234:237], v[84:87]
	v_mfma_f32_16x16x32_bf16 v[84:87], v[206:209], v[238:241], v[84:87]
	v_mfma_f32_16x16x32_bf16 v[80:83], v[210:213], v[234:237], v[80:83]
	v_mfma_f32_16x16x32_bf16 v[80:83], v[214:217], v[238:241], v[80:83]
	s_setprio 2
	s_barrier
	v_mfma_f32_16x16x32_bf16 v[68:71], v[182:185], v[242:245], v[68:71]
	v_mfma_f32_16x16x32_bf16 v[68:71], v[206:209], v[246:249], v[68:71]
	v_mfma_f32_16x16x32_bf16 v[64:67], v[210:213], v[242:245], v[64:67]
	v_mfma_f32_16x16x32_bf16 v[64:67], v[214:217], v[246:249], v[64:67]
	s_setprio 0
	s_add_i32 vcc_lo, s83, s13
	v_lshl_add_u64 v[158:159], s[28:29], 0, v[166:167]
	s_mov_b32 m0, vcc_lo
	ds_read_b128 v[218:221], v155 offset:16384
	ds_read_b128 v[222:225], v155 offset:17408
	ds_read_b128 v[226:229], v155 offset:18432
	ds_read_b128 v[230:233], v155 offset:19456
	ds_read_b128 v[234:237], v155 offset:20480
	ds_read_b128 v[238:241], v155 offset:21504
	ds_read_b128 v[242:245], v155 offset:22528
	ds_read_b128 v[246:249], v155 offset:23552
	global_load_lds_dwordx4 v[158:159], off
	s_add_i32 m0, vcc_lo, 0x2000
	s_add_u32 vcc_lo, s28, 0x80000
	v_lshl_add_u64 v[186:187], s[28:29], 0, v[170:171]
	s_addc_u32 vcc_hi, s29, 0
	s_add_i32 s44, s90, s13
	global_load_lds_dwordx4 v[186:187], off
	v_lshl_add_u64 v[250:251], vcc, 0, v[166:167]
	s_mov_b32 m0, s44
	v_lshl_add_u64 v[252:253], s[48:49], 0, v[168:169]
	global_load_lds_dwordx4 v[250:251], off
	v_lshl_add_u64 v[250:251], vcc, 0, v[170:171]
	s_add_i32 m0, s44, 0x2000
	s_nop 0
	global_load_lds_dwordx4 v[250:251], off
	v_lshl_add_u64 v[250:251], s[48:49], 0, v[164:165]
	s_mov_b32 m0, s56
	s_nop 0
	global_load_lds_dwordx4 v[250:251], off
	s_mov_b32 m0, s57
	s_nop 0
	global_load_lds_dwordx4 v[252:253], off
	s_waitcnt vmcnt(8)
	s_waitcnt lgkmcnt(0)
	s_barrier
; #define PG8_STAGE(bufoff, gbase, voff) do { _Pragma("unroll") for (int _i = 0; _i < 2; ++_i) \
;         __builtin_amdgcn_global_load_lds((const unsigned*)((const char*)(gbase) + (voff)[_i]), (PG8_LAS unsigned*)(lds + (bufoff) + ldsw + _i * 8192), 16, 0, 0); } while (0)
; #define PG8_LDA(dst, b, h) do { _Pragma("unroll") for (int m = 0; m < 4; ++m) _Pragma("unroll") for (int k = 0; k < 2; ++k) dst[m][k] = *(const PG8_LAS bf16x8*)(lds + PG8_SA(b, h) + aoff + m * 2048 + k * 1024); } while (0)
; #define PG8_LDB(dst, b, h) do { _Pragma("unroll") for (int n = 0; n < 2; ++n) _Pragma("unroll") for (int k = 0; k < 2; ++k) dst[n][k] = *(const PG8_LAS bf16x8*)(lds + PG8_SB(b, h) + boff + n * 2048 + k * 1024); } while (0)
; #define PG8_MMA(ai, bj, At, Bt) do { __builtin_amdgcn_s_setprio(1); _Pragma("unroll") for (int m = 0; m < 4; ++m) _Pragma("unroll") for (int n = 0; n < 2; ++n) _Pragma("unroll") for (int k = 0; k < 2; ++k) \
;         acc[ai][bj][m][n] = __builtin_amdgcn_mfma_f32_16x16x32_bf16(Bt[n][k], At[m][k], acc[ai][bj][m][n], 0, 0, 0); __builtin_amdgcn_s_setprio(0); } while (0)
; #define PG8_WAIT_V(n) asm volatile("s_waitcnt vmcnt(" #n ")" ::: "memory")
; #define PG8_WAIT_L(n) asm volatile("s_waitcnt lgkmcnt(" #n ")" ::: "memory")
; #define PG8_BAR __builtin_amdgcn_s_barrier()
; #define PG8_SCHED __builtin_amdgcn_sched_barrier(0)
; template <class Epi, class Sched, bool ALIGN_EPI = false, bool SP2 = false>
; __device__ __forceinline__ void gemm_phase(PG8_LAS unsigned char* lds, const Gemm g, const Sched& S, const Epi& E) {
;     ...
;             PG8_WAIT_V(8); PG8_WAIT_L(0); PG8_BAR; PG8_MMA(1, 0, At, B0); PG8_MMA(1, 1, At, B1); PG8_BAR; PG8_SCHED;
;             PG8_LDB(B0, 1, 0); PG8_LDB(B1, 1, 1); PG8_SCHED; PG8_LDA(At, 1, 0); PG8_STAGE(PG8_SA(0, 1), a2 + hstep, voffA);
;             PG8_WAIT_V(8); PG8_WAIT_L(0); PG8_BAR; PG8_MMA(0, 0, At, B0); PG8_MMA(0, 1, At, B1); PG8_BAR; PG8_SCHED;
	s_setprio 1
	s_waitcnt lgkmcnt(0)
	v_mfma_f32_16x16x32_bf16 v[60:63], v[142:145], v[218:221], v[60:63]
	v_mfma_f32_16x16x32_bf16 v[60:63], v[146:149], v[222:225], v[60:63]
	v_mfma_f32_16x16x32_bf16 v[56:59], v[174:177], v[218:221], v[56:59]
	v_mfma_f32_16x16x32_bf16 v[56:59], v[178:181], v[222:225], v[56:59]
	v_mfma_f32_16x16x32_bf16 v[44:47], v[142:145], v[226:229], v[44:47]
	v_mfma_f32_16x16x32_bf16 v[44:47], v[146:149], v[230:233], v[44:47]
	v_mfma_f32_16x16x32_bf16 v[40:43], v[174:177], v[226:229], v[40:43]
	v_mfma_f32_16x16x32_bf16 v[40:43], v[178:181], v[230:233], v[40:43]
	v_mfma_f32_16x16x32_bf16 v[28:31], v[142:145], v[234:237], v[28:31]
	v_mfma_f32_16x16x32_bf16 v[28:31], v[146:149], v[238:241], v[28:31]
	v_mfma_f32_16x16x32_bf16 v[24:27], v[174:177], v[234:237], v[24:27]
	v_mfma_f32_16x16x32_bf16 v[24:27], v[178:181], v[238:241], v[24:27]
	v_mfma_f32_16x16x32_bf16 v[12:15], v[142:145], v[242:245], v[12:15]
	v_mfma_f32_16x16x32_bf16 v[12:15], v[146:149], v[246:249], v[12:15]
	v_mfma_f32_16x16x32_bf16 v[8:11], v[174:177], v[242:245], v[8:11]
	v_mfma_f32_16x16x32_bf16 v[8:11], v[178:181], v[246:249], v[8:11]
	s_setprio 0
	s_setprio 1
	v_mfma_f32_16x16x32_bf16 v[52:55], v[182:185], v[218:221], v[52:55]
	v_mfma_f32_16x16x32_bf16 v[52:55], v[206:209], v[222:225], v[52:55]
	v_mfma_f32_16x16x32_bf16 v[48:51], v[210:213], v[218:221], v[48:51]
	v_mfma_f32_16x16x32_bf16 v[48:51], v[214:217], v[222:225], v[48:51]
	v_mfma_f32_16x16x32_bf16 v[36:39], v[182:185], v[226:229], v[36:39]
	v_mfma_f32_16x16x32_bf16 v[36:39], v[206:209], v[230:233], v[36:39]
	v_mfma_f32_16x16x32_bf16 v[32:35], v[210:213], v[226:229], v[32:35]
	v_mfma_f32_16x16x32_bf16 v[32:35], v[214:217], v[230:233], v[32:35]
	v_mfma_f32_16x16x32_bf16 v[20:23], v[182:185], v[234:237], v[20:23]
	v_mfma_f32_16x16x32_bf16 v[20:23], v[206:209], v[238:241], v[20:23]
	v_mfma_f32_16x16x32_bf16 v[16:19], v[210:213], v[234:237], v[16:19]
	v_mfma_f32_16x16x32_bf16 v[16:19], v[214:217], v[238:241], v[16:19]
	s_setprio 2
	s_barrier
	v_mfma_f32_16x16x32_bf16 v[4:7], v[182:185], v[242:245], v[4:7]
	v_mfma_f32_16x16x32_bf16 v[4:7], v[206:209], v[246:249], v[4:7]
	v_mfma_f32_16x16x32_bf16 v[0:3], v[210:213], v[242:245], v[0:3]
	v_mfma_f32_16x16x32_bf16 v[0:3], v[214:217], v[246:249], v[0:3]
	s_setprio 0
	s_add_i32 s44, 0, 0x18000
	v_add_u32_e32 v161, s44, v151
	s_add_i32 s45, 0, 0x1c000
	ds_read_b128 v[142:145], v161
	ds_read_b128 v[146:149], v161 offset:1024
	ds_read_b128 v[174:177], v161 offset:2048
	ds_read_b128 v[178:181], v161 offset:3072
	v_add_u32_e32 v161, s45, v151
	ds_read_b128 v[182:185], v161
	ds_read_b128 v[206:209], v161 offset:1024
	ds_read_b128 v[210:213], v161 offset:2048
	ds_read_b128 v[214:217], v161 offset:3072
	s_add_u32 s48, s48, 0x80000
	s_addc_u32 s49, s49, 0
	s_mov_b32 m0, s60
	v_lshl_add_u64 v[200:201], s[48:49], 0, v[164:165]
	ds_read_b128 v[218:221], v155 offset:32768
	ds_read_b128 v[222:225], v155 offset:33792
	ds_read_b128 v[226:229], v155 offset:34816
	ds_read_b128 v[230:233], v155 offset:35840
	ds_read_b128 v[234:237], v155 offset:36864
	ds_read_b128 v[238:241], v155 offset:37888
	ds_read_b128 v[242:245], v155 offset:38912
	ds_read_b128 v[246:249], v155 offset:39936
	global_load_lds_dwordx4 v[200:201], off
	v_lshl_add_u64 v[200:201], s[48:49], 0, v[168:169]
	s_mov_b32 m0, s61
	s_nop 0
	global_load_lds_dwordx4 v[200:201], off
	s_waitcnt vmcnt(8)
	s_waitcnt lgkmcnt(0)
	s_barrier
	s_setprio 1
	s_waitcnt lgkmcnt(0)
	v_mfma_f32_16x16x32_bf16 v[124:127], v[142:145], v[218:221], v[124:127]
	v_mfma_f32_16x16x32_bf16 v[124:127], v[146:149], v[222:225], v[124:127]
	v_mfma_f32_16x16x32_bf16 v[120:123], v[174:177], v[218:221], v[120:123]
	v_mfma_f32_16x16x32_bf16 v[120:123], v[178:181], v[222:225], v[120:123]
	v_mfma_f32_16x16x32_bf16 v[108:111], v[142:145], v[226:229], v[108:111]
	v_mfma_f32_16x16x32_bf16 v[108:111], v[146:149], v[230:233], v[108:111]
	v_mfma_f32_16x16x32_bf16 v[104:107], v[174:177], v[226:229], v[104:107]
	v_mfma_f32_16x16x32_bf16 v[104:107], v[178:181], v[230:233], v[104:107]
	v_mfma_f32_16x16x32_bf16 v[92:95], v[142:145], v[234:237], v[92:95]
	v_mfma_f32_16x16x32_bf16 v[92:95], v[146:149], v[238:241], v[92:95]
	v_mfma_f32_16x16x32_bf16 v[88:91], v[174:177], v[234:237], v[88:91]
	v_mfma_f32_16x16x32_bf16 v[88:91], v[178:181], v[238:241], v[88:91]
	v_mfma_f32_16x16x32_bf16 v[76:79], v[142:145], v[242:245], v[76:79]
	v_mfma_f32_16x16x32_bf16 v[76:79], v[146:149], v[246:249], v[76:79]
	v_mfma_f32_16x16x32_bf16 v[72:75], v[174:177], v[242:245], v[72:75]
	v_mfma_f32_16x16x32_bf16 v[72:75], v[178:181], v[246:249], v[72:75]
	s_setprio 0
	s_setprio 1
	v_mfma_f32_16x16x32_bf16 v[116:119], v[182:185], v[218:221], v[116:119]
	v_mfma_f32_16x16x32_bf16 v[116:119], v[206:209], v[222:225], v[116:119]
	v_mfma_f32_16x16x32_bf16 v[112:115], v[210:213], v[218:221], v[112:115]
	v_mfma_f32_16x16x32_bf16 v[112:115], v[214:217], v[222:225], v[112:115]
	v_mfma_f32_16x16x32_bf16 v[100:103], v[182:185], v[226:229], v[100:103]
	v_mfma_f32_16x16x32_bf16 v[100:103], v[206:209], v[230:233], v[100:103]
	v_mfma_f32_16x16x32_bf16 v[96:99], v[210:213], v[226:229], v[96:99]
	v_mfma_f32_16x16x32_bf16 v[96:99], v[214:217], v[230:233], v[96:99]
	v_mfma_f32_16x16x32_bf16 v[84:87], v[182:185], v[234:237], v[84:87]
	v_mfma_f32_16x16x32_bf16 v[84:87], v[206:209], v[238:241], v[84:87]
	v_mfma_f32_16x16x32_bf16 v[80:83], v[210:213], v[234:237], v[80:83]
	v_mfma_f32_16x16x32_bf16 v[80:83], v[214:217], v[238:241], v[80:83]
	s_setprio 2
	s_barrier
; #define PG8_STAGE(bufoff, gbase, voff) do { _Pragma("unroll") for (int _i = 0; _i < 2; ++_i) \
;         __builtin_amdgcn_global_load_lds((const unsigned*)((const char*)(gbase) + (voff)[_i]), (PG8_LAS unsigned*)(lds + (bufoff) + ldsw + _i * 8192), 16, 0, 0); } while (0)
; #define PG8_LDA(dst, b, h) do { _Pragma("unroll") for (int m = 0; m < 4; ++m) _Pragma("unroll") for (int k = 0; k < 2; ++k) dst[m][k] = *(const PG8_LAS bf16x8*)(lds + PG8_SA(b, h) + aoff + m * 2048 + k * 1024); } while (0)
; #define PG8_MMA(ai, bj, At, Bt) do { __builtin_amdgcn_s_setprio(1); _Pragma("unroll") for (int m = 0; m < 4; ++m) _Pragma("unroll") for (int n = 0; n < 2; ++n) _Pragma("unroll") for (int k = 0; k < 2; ++k) \
;         acc[ai][bj][m][n] = __builtin_amdgcn_mfma_f32_16x16x32_bf16(Bt[n][k], At[m][k], acc[ai][bj][m][n], 0, 0, 0); __builtin_amdgcn_s_setprio(0); } while (0)
; #define PG8_WAIT_V(n) asm volatile("s_waitcnt vmcnt(" #n ")" ::: "memory")
; #define PG8_WAIT_L(n) asm volatile("s_waitcnt lgkmcnt(" #n ")" ::: "memory")
; #define PG8_BAR __builtin_amdgcn_s_barrier()
; #define PG8_SCHED __builtin_amdgcn_sched_barrier(0)
;     __device__ __forceinline__ void operator()(const f32x4 (&acc)[2][2][4][2], const Unit& u, int wr, int wc, int fr, int fq) const {
;         const int row0 = u.pm * BM + wr * 64 + fr;
;         if (u.pn < 8) {
; template <class Epi, class Sched, bool ALIGN_EPI = false, bool SP2 = false>
; __device__ __forceinline__ void gemm_phase(PG8_LAS unsigned char* lds, const Gemm g, const Sched& S, const Epi& E) {
;     ...
;             PG8_LDA(At, 1, 1); PG8_STAGE(PG8_SB(1, 0), b3, voffB); PG8_STAGE(PG8_SB(1, 1), b3 + hstep, voffB); PG8_STAGE(PG8_SA(1, 0), a3, voffA);
;             PG8_WAIT_V(8); PG8_WAIT_L(0); PG8_BAR; PG8_MMA(1, 0, At, B0); PG8_MMA(1, 1, At, B1); PG8_BAR; PG8_SCHED;
	v_mfma_f32_16x16x32_bf16 v[68:71], v[182:185], v[242:245], v[68:71]
	v_mfma_f32_16x16x32_bf16 v[68:71], v[206:209], v[246:249], v[68:71]
	v_mfma_f32_16x16x32_bf16 v[64:67], v[210:213], v[242:245], v[64:67]
	v_mfma_f32_16x16x32_bf16 v[64:67], v[214:217], v[246:249], v[64:67]
	s_setprio 0
	s_add_i32 s44, s44, s13
	v_lshl_add_u64 v[158:159], v[158:159], 0, s[52:53]
	s_mov_b32 m0, s44
	ds_read_b128 v[218:221], v155 offset:49152
	ds_read_b128 v[222:225], v155 offset:50176
	ds_read_b128 v[226:229], v155 offset:51200
	ds_read_b128 v[230:233], v155 offset:52224
	ds_read_b128 v[234:237], v155 offset:53248
	ds_read_b128 v[238:241], v155 offset:54272
	ds_read_b128 v[242:245], v155 offset:55296
	ds_read_b128 v[246:249], v155 offset:56320
	global_load_lds_dwordx4 v[158:159], off
	s_add_i32 m0, s44, 0x2000
	s_add_u32 s28, s28, 0x80080
	v_lshl_add_u64 v[158:159], v[186:187], 0, s[52:53]
	s_addc_u32 s29, s29, 0
	s_add_i32 s44, s45, s13
	global_load_lds_dwordx4 v[158:159], off
	v_lshl_add_u64 v[158:159], s[28:29], 0, v[166:167]
	s_mov_b32 m0, s44
	s_nop 0
	global_load_lds_dwordx4 v[158:159], off
	v_lshl_add_u64 v[158:159], s[28:29], 0, v[170:171]
	s_add_i32 m0, s44, 0x2000
	s_nop 0
	global_load_lds_dwordx4 v[158:159], off
	v_lshl_add_u64 v[158:159], v[250:251], 0, s[52:53]
	s_mov_b32 m0, s62
	s_nop 0
	global_load_lds_dwordx4 v[158:159], off
	v_lshl_add_u64 v[158:159], v[252:253], 0, s[52:53]
	s_mov_b32 m0, s63
	s_nop 0
	global_load_lds_dwordx4 v[158:159], off
	s_waitcnt vmcnt(8)
	s_waitcnt lgkmcnt(0)
	s_barrier
	s_setprio 1
	s_waitcnt lgkmcnt(0)
	v_mfma_f32_16x16x32_bf16 v[60:63], v[142:145], v[218:221], v[60:63]
	v_mfma_f32_16x16x32_bf16 v[60:63], v[146:149], v[222:225], v[60:63]
	v_mfma_f32_16x16x32_bf16 v[56:59], v[174:177], v[218:221], v[56:59]
	v_mfma_f32_16x16x32_bf16 v[56:59], v[178:181], v[222:225], v[56:59]
	v_mfma_f32_16x16x32_bf16 v[44:47], v[142:145], v[226:229], v[44:47]
	v_mfma_f32_16x16x32_bf16 v[44:47], v[146:149], v[230:233], v[44:47]
	v_mfma_f32_16x16x32_bf16 v[40:43], v[174:177], v[226:229], v[40:43]
	v_mfma_f32_16x16x32_bf16 v[40:43], v[178:181], v[230:233], v[40:43]
	v_mfma_f32_16x16x32_bf16 v[28:31], v[142:145], v[234:237], v[28:31]
	v_mfma_f32_16x16x32_bf16 v[28:31], v[146:149], v[238:241], v[28:31]
	v_mfma_f32_16x16x32_bf16 v[24:27], v[174:177], v[234:237], v[24:27]
	v_mfma_f32_16x16x32_bf16 v[24:27], v[178:181], v[238:241], v[24:27]
	v_mfma_f32_16x16x32_bf16 v[12:15], v[142:145], v[242:245], v[12:15]
	v_mfma_f32_16x16x32_bf16 v[12:15], v[146:149], v[246:249], v[12:15]
	v_mfma_f32_16x16x32_bf16 v[8:11], v[174:177], v[242:245], v[8:11]
	v_mfma_f32_16x16x32_bf16 v[8:11], v[178:181], v[246:249], v[8:11]
	s_setprio 0
	s_setprio 1
	v_mfma_f32_16x16x32_bf16 v[52:55], v[182:185], v[218:221], v[52:55]
	v_mfma_f32_16x16x32_bf16 v[52:55], v[206:209], v[222:225], v[52:55]
	v_mfma_f32_16x16x32_bf16 v[48:51], v[210:213], v[218:221], v[48:51]
	v_mfma_f32_16x16x32_bf16 v[48:51], v[214:217], v[222:225], v[48:51]
	v_mfma_f32_16x16x32_bf16 v[36:39], v[182:185], v[226:229], v[36:39]
	v_mfma_f32_16x16x32_bf16 v[36:39], v[206:209], v[230:233], v[36:39]
	v_mfma_f32_16x16x32_bf16 v[32:35], v[210:213], v[226:229], v[32:35]
	v_mfma_f32_16x16x32_bf16 v[32:35], v[214:217], v[230:233], v[32:35]
	v_mfma_f32_16x16x32_bf16 v[20:23], v[182:185], v[234:237], v[20:23]
	v_mfma_f32_16x16x32_bf16 v[20:23], v[206:209], v[238:241], v[20:23]
	v_mfma_f32_16x16x32_bf16 v[16:19], v[210:213], v[234:237], v[16:19]
	v_mfma_f32_16x16x32_bf16 v[16:19], v[214:217], v[238:241], v[16:19]
	s_setprio 2
	s_barrier
	v_mfma_f32_16x16x32_bf16 v[4:7], v[182:185], v[242:245], v[4:7]
	v_mfma_f32_16x16x32_bf16 v[4:7], v[206:209], v[246:249], v[4:7]
	v_mfma_f32_16x16x32_bf16 v[0:3], v[210:213], v[242:245], v[0:3]
	v_mfma_f32_16x16x32_bf16 v[0:3], v[214:217], v[246:249], v[0:3]
	s_setprio 0
	s_add_i32 s97, s97, 2
	s_add_u32 s84, s84, 0x100
	s_addc_u32 s85, s85, 0
	s_add_u32 s95, s95, 0x100
	s_addc_u32 s96, s96, 0
	s_cmp_gt_u32 s97, 29
	s_cbranch_scc0 .LBB0_231
	s_and_b64 vcc, exec, s[72:73]
	s_cbranch_vccz .LBB0_236
	s_barrier
	v_lshl_add_u32 v142, s82, 8, v150
	s_cmp_gt_i32 s94, 7
	s_mov_b64 s[28:29], -1
	s_cbranch_scc1 .LBB0_237

; #define PG8_STAGE(bufoff, gbase, voff) do { _Pragma("unroll") for (int _i = 0; _i < 2; ++_i) \
;         __builtin_amdgcn_global_load_lds((const unsigned*)((const char*)(gbase) + (voff)[_i]), (PG8_LAS unsigned*)(lds + (bufoff) + ldsw + _i * 8192), 16, 0, 0); } while (0)
; #define PG8_LDA(dst, b, h) do { _Pragma("unroll") for (int m = 0; m < 4; ++m) _Pragma("unroll") for (int k = 0; k < 2; ++k) dst[m][k] = *(const PG8_LAS bf16x8*)(lds + PG8_SA(b, h) + aoff + m * 2048 + k * 1024); } while (0)
; #define PG8_LDB(dst, b, h) do { _Pragma("unroll") for (int n = 0; n < 2; ++n) _Pragma("unroll") for (int k = 0; k < 2; ++k) dst[n][k] = *(const PG8_LAS bf16x8*)(lds + PG8_SB(b, h) + boff + n * 2048 + k * 1024); } while (0)
; #define PG8_MMA(ai, bj, At, Bt) do { __builtin_amdgcn_s_setprio(1); _Pragma("unroll") for (int m = 0; m < 4; ++m) _Pragma("unroll") for (int n = 0; n < 2; ++n) _Pragma("unroll") for (int k = 0; k < 2; ++k) \
;         acc[ai][bj][m][n] = __builtin_amdgcn_mfma_f32_16x16x32_bf16(Bt[n][k], At[m][k], acc[ai][bj][m][n], 0, 0, 0); __builtin_amdgcn_s_setprio(0); } while (0)
; #define PG8_WAIT_V(n) asm volatile("s_waitcnt vmcnt(" #n ")" ::: "memory")
; #define PG8_WAIT_L(n) asm volatile("s_waitcnt lgkmcnt(" #n ")" ::: "memory")
; #define PG8_BAR __builtin_amdgcn_s_barrier()
; #define PG8_SCHED __builtin_amdgcn_sched_barrier(0)
; template <class Epi, class Sched, bool ALIGN_EPI = false, bool SP2 = false>
; __device__ __forceinline__ void gemm_phase(PG8_LAS unsigned char* lds, const Gemm g, const Sched& S, const Epi& E) {
;     ...
;             const char* a1 = cA + (size_t)(t + 1) * kstep;
;             const char* a2 = last ? nA : cA + (size_t)(t + 2) * kstep; const char* b2 = last ? nB : cB + (size_t)(t + 2) * kstep;
;             const char* a3 = a2 + kstep; const char* b3 = b2 + kstep;
;             if (last && has_next) S.a_ready(nxt);
;             if constexpr (SP2) {
;             PG8_LDB(B0, 0, 0); PG8_LDB(B1, 0, 1); PG8_SCHED; PG8_LDA(At, 0, 0); PG8_STAGE(PG8_SA(1, 1), a1 + hstep, voffA);
;             PG8_WAIT_V(8); PG8_WAIT_L(0); PG8_BAR; PG8_MMA(0, 0, At, B0); PG8_MMA(0, 1, At, B1); PG8_BAR; PG8_SCHED;
;             PG8_LDA(At, 0, 1); PG8_STAGE(PG8_SB(0, 0), b2, voffB); PG8_STAGE(PG8_SB(0, 1), b2 + hstep, voffB); PG8_STAGE(PG8_SA(0, 0), a2, voffA);
.LBB0_362:
	ds_read_b128 v[80:83], v171
	ds_read_b128 v[84:87], v171 offset:1024
	ds_read_b128 v[92:95], v171 offset:2048
	ds_read_b128 v[100:103], v171 offset:3072
	ds_read_b128 v[144:147], v186
	ds_read_b128 v[148:151], v186 offset:1024
	ds_read_b128 v[152:155], v186 offset:2048
	ds_read_b128 v[156:159], v186 offset:3072
	s_add_u32 s28, s74, 0xfff80080
	s_addc_u32 s29, s75, -1
	s_cmp_eq_u32 s77, 28
	s_cselect_b32 s49, s23, s29
	s_cselect_b32 s48, s34, s28
	s_cselect_b32 s29, s21, s76
	s_cselect_b32 s28, s35, s73
	v_lshl_add_u64 v[200:201], s[74:75], 0, v[172:173]
	s_add_i32 m0, s38, 0xc000
	ds_read_b128 v[178:181], v187
	ds_read_b128 v[182:185], v187 offset:1024
	ds_read_b128 v[206:209], v187 offset:2048
	ds_read_b128 v[210:213], v187 offset:3072
	ds_read_b128 v[214:217], v187 offset:4096
	ds_read_b128 v[218:221], v187 offset:5120
	ds_read_b128 v[222:225], v187 offset:6144
	ds_read_b128 v[226:229], v187 offset:7168
	global_load_lds_dwordx4 v[200:201], off
	v_lshl_add_u64 v[200:201], s[74:75], 0, v[174:175]
	s_add_i32 m0, s38, 0xe000
	s_nop 0
	global_load_lds_dwordx4 v[200:201], off
	s_waitcnt vmcnt(8)
	s_waitcnt lgkmcnt(0)
	s_barrier
	s_setprio 1
	s_waitcnt lgkmcnt(0)
	v_mfma_f32_16x16x32_bf16 v[140:143], v[80:83], v[178:181], v[140:143]
	v_mfma_f32_16x16x32_bf16 v[140:143], v[84:87], v[182:185], v[140:143]
	v_mfma_f32_16x16x32_bf16 v[136:139], v[92:95], v[178:181], v[136:139]
	v_mfma_f32_16x16x32_bf16 v[136:139], v[100:103], v[182:185], v[136:139]
	v_mfma_f32_16x16x32_bf16 v[124:127], v[80:83], v[206:209], v[124:127]
	v_mfma_f32_16x16x32_bf16 v[124:127], v[84:87], v[210:213], v[124:127]
	v_mfma_f32_16x16x32_bf16 v[120:123], v[92:95], v[206:209], v[120:123]
	v_mfma_f32_16x16x32_bf16 v[120:123], v[100:103], v[210:213], v[120:123]
	v_mfma_f32_16x16x32_bf16 v[108:111], v[80:83], v[214:217], v[108:111]
	v_mfma_f32_16x16x32_bf16 v[108:111], v[84:87], v[218:221], v[108:111]
	v_mfma_f32_16x16x32_bf16 v[104:107], v[92:95], v[214:217], v[104:107]
	v_mfma_f32_16x16x32_bf16 v[104:107], v[100:103], v[218:221], v[104:107]
	v_mfma_f32_16x16x32_bf16 v[76:79], v[80:83], v[222:225], v[76:79]
	v_mfma_f32_16x16x32_bf16 v[76:79], v[84:87], v[226:229], v[76:79]
	v_mfma_f32_16x16x32_bf16 v[72:75], v[92:95], v[222:225], v[72:75]
	v_mfma_f32_16x16x32_bf16 v[72:75], v[100:103], v[226:229], v[72:75]
	s_setprio 0
	s_setprio 1
	v_mfma_f32_16x16x32_bf16 v[132:135], v[144:147], v[178:181], v[132:135]
	v_mfma_f32_16x16x32_bf16 v[132:135], v[148:151], v[182:185], v[132:135]
	v_mfma_f32_16x16x32_bf16 v[128:131], v[152:155], v[178:181], v[128:131]
	v_mfma_f32_16x16x32_bf16 v[128:131], v[156:159], v[182:185], v[128:131]
	v_mfma_f32_16x16x32_bf16 v[116:119], v[144:147], v[206:209], v[116:119]
	v_mfma_f32_16x16x32_bf16 v[116:119], v[148:151], v[210:213], v[116:119]
	v_mfma_f32_16x16x32_bf16 v[112:115], v[152:155], v[206:209], v[112:115]
	v_mfma_f32_16x16x32_bf16 v[112:115], v[156:159], v[210:213], v[112:115]
	v_mfma_f32_16x16x32_bf16 v[96:99], v[144:147], v[214:217], v[96:99]
	v_mfma_f32_16x16x32_bf16 v[96:99], v[148:151], v[218:221], v[96:99]
	v_mfma_f32_16x16x32_bf16 v[88:91], v[152:155], v[214:217], v[88:91]
	v_mfma_f32_16x16x32_bf16 v[88:91], v[156:159], v[218:221], v[88:91]
	s_setprio 2
	s_barrier
	v_mfma_f32_16x16x32_bf16 v[68:71], v[144:147], v[222:225], v[68:71]
	v_mfma_f32_16x16x32_bf16 v[68:71], v[148:151], v[226:229], v[68:71]
	v_mfma_f32_16x16x32_bf16 v[64:67], v[152:155], v[222:225], v[64:67]
	v_mfma_f32_16x16x32_bf16 v[64:67], v[156:159], v[226:229], v[64:67]
	s_setprio 0
	s_add_i32 s44, s62, s13
	v_lshl_add_u64 v[200:201], s[28:29], 0, v[164:165]
	s_mov_b32 m0, s44
	ds_read_b128 v[178:181], v187 offset:16384
	ds_read_b128 v[182:185], v187 offset:17408
	ds_read_b128 v[206:209], v187 offset:18432
	ds_read_b128 v[210:213], v187 offset:19456
	ds_read_b128 v[214:217], v187 offset:20480
	ds_read_b128 v[218:221], v187 offset:21504
	ds_read_b128 v[222:225], v187 offset:22528
	ds_read_b128 v[226:229], v187 offset:23552
	global_load_lds_dwordx4 v[200:201], off
	s_add_i32 m0, s44, 0x2000
	s_add_u32 s78, s28, 0x80000
	v_lshl_add_u64 v[230:231], s[28:29], 0, v[168:169]
	s_addc_u32 s79, s29, 0
	s_add_i32 s44, s63, s13
	global_load_lds_dwordx4 v[230:231], off
	v_lshl_add_u64 v[232:233], s[78:79], 0, v[164:165]
	s_mov_b32 m0, s44
	v_lshl_add_u64 v[234:235], s[48:49], 0, v[168:169]
	global_load_lds_dwordx4 v[232:233], off
	v_lshl_add_u64 v[232:233], s[78:79], 0, v[168:169]
	s_add_i32 m0, s44, 0x2000
	s_nop 0
	global_load_lds_dwordx4 v[232:233], off
	v_lshl_add_u64 v[232:233], s[48:49], 0, v[164:165]
	s_mov_b32 m0, s38
	s_nop 0
	global_load_lds_dwordx4 v[232:233], off
	s_mov_b32 m0, s39
	s_nop 0
	global_load_lds_dwordx4 v[234:235], off
	s_waitcnt vmcnt(8)
	s_waitcnt lgkmcnt(0)
	s_barrier
; #define PG8_STAGE(bufoff, gbase, voff) do { _Pragma("unroll") for (int _i = 0; _i < 2; ++_i) \
;         __builtin_amdgcn_global_load_lds((const unsigned*)((const char*)(gbase) + (voff)[_i]), (PG8_LAS unsigned*)(lds + (bufoff) + ldsw + _i * 8192), 16, 0, 0); } while (0)
; #define PG8_LDA(dst, b, h) do { _Pragma("unroll") for (int m = 0; m < 4; ++m) _Pragma("unroll") for (int k = 0; k < 2; ++k) dst[m][k] = *(const PG8_LAS bf16x8*)(lds + PG8_SA(b, h) + aoff + m * 2048 + k * 1024); } while (0)
; #define PG8_LDB(dst, b, h) do { _Pragma("unroll") for (int n = 0; n < 2; ++n) _Pragma("unroll") for (int k = 0; k < 2; ++k) dst[n][k] = *(const PG8_LAS bf16x8*)(lds + PG8_SB(b, h) + boff + n * 2048 + k * 1024); } while (0)
; #define PG8_MMA(ai, bj, At, Bt) do { __builtin_amdgcn_s_setprio(1); _Pragma("unroll") for (int m = 0; m < 4; ++m) _Pragma("unroll") for (int n = 0; n < 2; ++n) _Pragma("unroll") for (int k = 0; k < 2; ++k) \
;         acc[ai][bj][m][n] = __builtin_amdgcn_mfma_f32_16x16x32_bf16(Bt[n][k], At[m][k], acc[ai][bj][m][n], 0, 0, 0); __builtin_amdgcn_s_setprio(0); } while (0)
; #define PG8_WAIT_V(n) asm volatile("s_waitcnt vmcnt(" #n ")" ::: "memory")
; #define PG8_WAIT_L(n) asm volatile("s_waitcnt lgkmcnt(" #n ")" ::: "memory")
; #define PG8_BAR __builtin_amdgcn_s_barrier()
; #define PG8_SCHED __builtin_amdgcn_sched_barrier(0)
; template <class Epi, class Sched, bool ALIGN_EPI = false, bool SP2 = false>
; __device__ __forceinline__ void gemm_phase(PG8_LAS unsigned char* lds, const Gemm g, const Sched& S, const Epi& E) {
;     ...
;             PG8_WAIT_V(8); PG8_WAIT_L(0); PG8_BAR; PG8_MMA(1, 0, At, B0); PG8_MMA(1, 1, At, B1); PG8_BAR; PG8_SCHED;
;             PG8_LDB(B0, 1, 0); PG8_LDB(B1, 1, 1); PG8_SCHED; PG8_LDA(At, 1, 0); PG8_STAGE(PG8_SA(0, 1), a2 + hstep, voffA);
;             PG8_WAIT_V(8); PG8_WAIT_L(0); PG8_BAR; PG8_MMA(0, 0, At, B0); PG8_MMA(0, 1, At, B1); PG8_BAR; PG8_SCHED;
	s_setprio 1
	s_waitcnt lgkmcnt(0)
	v_mfma_f32_16x16x32_bf16 v[60:63], v[80:83], v[178:181], v[60:63]
	v_mfma_f32_16x16x32_bf16 v[60:63], v[84:87], v[182:185], v[60:63]
	v_mfma_f32_16x16x32_bf16 v[56:59], v[92:95], v[178:181], v[56:59]
	v_mfma_f32_16x16x32_bf16 v[56:59], v[100:103], v[182:185], v[56:59]
	v_mfma_f32_16x16x32_bf16 v[44:47], v[80:83], v[206:209], v[44:47]
	v_mfma_f32_16x16x32_bf16 v[44:47], v[84:87], v[210:213], v[44:47]
	v_mfma_f32_16x16x32_bf16 v[40:43], v[92:95], v[206:209], v[40:43]
	v_mfma_f32_16x16x32_bf16 v[40:43], v[100:103], v[210:213], v[40:43]
	v_mfma_f32_16x16x32_bf16 v[28:31], v[80:83], v[214:217], v[28:31]
	v_mfma_f32_16x16x32_bf16 v[28:31], v[84:87], v[218:221], v[28:31]
	v_mfma_f32_16x16x32_bf16 v[24:27], v[92:95], v[214:217], v[24:27]
	v_mfma_f32_16x16x32_bf16 v[24:27], v[100:103], v[218:221], v[24:27]
	v_mfma_f32_16x16x32_bf16 v[12:15], v[80:83], v[222:225], v[12:15]
	v_mfma_f32_16x16x32_bf16 v[12:15], v[84:87], v[226:229], v[12:15]
	v_mfma_f32_16x16x32_bf16 v[8:11], v[92:95], v[222:225], v[8:11]
	v_mfma_f32_16x16x32_bf16 v[8:11], v[100:103], v[226:229], v[8:11]
	s_setprio 0
	s_setprio 1
	v_mfma_f32_16x16x32_bf16 v[52:55], v[144:147], v[178:181], v[52:55]
	v_mfma_f32_16x16x32_bf16 v[52:55], v[148:151], v[182:185], v[52:55]
	v_mfma_f32_16x16x32_bf16 v[48:51], v[152:155], v[178:181], v[48:51]
	v_mfma_f32_16x16x32_bf16 v[48:51], v[156:159], v[182:185], v[48:51]
	v_mfma_f32_16x16x32_bf16 v[36:39], v[144:147], v[206:209], v[36:39]
	v_mfma_f32_16x16x32_bf16 v[36:39], v[148:151], v[210:213], v[36:39]
	v_mfma_f32_16x16x32_bf16 v[32:35], v[152:155], v[206:209], v[32:35]
	v_mfma_f32_16x16x32_bf16 v[32:35], v[156:159], v[210:213], v[32:35]
	v_mfma_f32_16x16x32_bf16 v[20:23], v[144:147], v[214:217], v[20:23]
	v_mfma_f32_16x16x32_bf16 v[20:23], v[148:151], v[218:221], v[20:23]
	v_mfma_f32_16x16x32_bf16 v[16:19], v[152:155], v[214:217], v[16:19]
	v_mfma_f32_16x16x32_bf16 v[16:19], v[156:159], v[218:221], v[16:19]
	s_setprio 2
	s_barrier
	v_mfma_f32_16x16x32_bf16 v[4:7], v[144:147], v[222:225], v[4:7]
	v_mfma_f32_16x16x32_bf16 v[4:7], v[148:151], v[226:229], v[4:7]
	v_mfma_f32_16x16x32_bf16 v[0:3], v[152:155], v[222:225], v[0:3]
	v_mfma_f32_16x16x32_bf16 v[0:3], v[156:159], v[226:229], v[0:3]
	s_setprio 0
	s_add_i32 s44, 0, 0x18000
	s_add_i32 s45, 0, 0x1c000
	v_add_u32_e32 v100, s44, v163
	v_add_u32_e32 v156, s45, v163
	ds_read_b128 v[80:83], v100
	ds_read_b128 v[84:87], v100 offset:1024
	ds_read_b128 v[92:95], v100 offset:2048
	ds_read_b128 v[100:103], v100 offset:3072
	ds_read_b128 v[144:147], v156
	ds_read_b128 v[148:151], v156 offset:1024
	ds_read_b128 v[152:155], v156 offset:2048
	ds_read_b128 v[156:159], v156 offset:3072
	s_add_u32 s48, s48, 0x80000
	s_addc_u32 s49, s49, 0
	s_mov_b32 m0, s40
	v_lshl_add_u64 v[236:237], s[48:49], 0, v[164:165]
	ds_read_b128 v[178:181], v187 offset:32768
	ds_read_b128 v[182:185], v187 offset:33792
	ds_read_b128 v[206:209], v187 offset:34816
	ds_read_b128 v[210:213], v187 offset:35840
	ds_read_b128 v[214:217], v187 offset:36864
	ds_read_b128 v[218:221], v187 offset:37888
	ds_read_b128 v[222:225], v187 offset:38912
	ds_read_b128 v[226:229], v187 offset:39936
	global_load_lds_dwordx4 v[236:237], off
	v_lshl_add_u64 v[236:237], s[48:49], 0, v[168:169]
	s_mov_b32 m0, s41
	s_nop 0
	global_load_lds_dwordx4 v[236:237], off
	s_waitcnt vmcnt(8)
	s_waitcnt lgkmcnt(0)
	s_barrier
	s_setprio 1
	s_waitcnt lgkmcnt(0)
	v_mfma_f32_16x16x32_bf16 v[140:143], v[80:83], v[178:181], v[140:143]
	v_mfma_f32_16x16x32_bf16 v[140:143], v[84:87], v[182:185], v[140:143]
	v_mfma_f32_16x16x32_bf16 v[136:139], v[92:95], v[178:181], v[136:139]
	v_mfma_f32_16x16x32_bf16 v[136:139], v[100:103], v[182:185], v[136:139]
	v_mfma_f32_16x16x32_bf16 v[124:127], v[80:83], v[206:209], v[124:127]
	v_mfma_f32_16x16x32_bf16 v[124:127], v[84:87], v[210:213], v[124:127]
	v_mfma_f32_16x16x32_bf16 v[120:123], v[92:95], v[206:209], v[120:123]
	v_mfma_f32_16x16x32_bf16 v[120:123], v[100:103], v[210:213], v[120:123]
	v_mfma_f32_16x16x32_bf16 v[108:111], v[80:83], v[214:217], v[108:111]
	v_mfma_f32_16x16x32_bf16 v[108:111], v[84:87], v[218:221], v[108:111]
	v_mfma_f32_16x16x32_bf16 v[104:107], v[92:95], v[214:217], v[104:107]
	v_mfma_f32_16x16x32_bf16 v[104:107], v[100:103], v[218:221], v[104:107]
	v_mfma_f32_16x16x32_bf16 v[76:79], v[80:83], v[222:225], v[76:79]
	v_mfma_f32_16x16x32_bf16 v[76:79], v[84:87], v[226:229], v[76:79]
	v_mfma_f32_16x16x32_bf16 v[72:75], v[92:95], v[222:225], v[72:75]
	v_mfma_f32_16x16x32_bf16 v[72:75], v[100:103], v[226:229], v[72:75]
	s_setprio 0
	s_setprio 1
	v_mfma_f32_16x16x32_bf16 v[132:135], v[144:147], v[178:181], v[132:135]
	v_mfma_f32_16x16x32_bf16 v[132:135], v[148:151], v[182:185], v[132:135]
	v_mfma_f32_16x16x32_bf16 v[128:131], v[152:155], v[178:181], v[128:131]
	v_mfma_f32_16x16x32_bf16 v[128:131], v[156:159], v[182:185], v[128:131]
	v_mfma_f32_16x16x32_bf16 v[116:119], v[144:147], v[206:209], v[116:119]
	v_mfma_f32_16x16x32_bf16 v[116:119], v[148:151], v[210:213], v[116:119]
	v_mfma_f32_16x16x32_bf16 v[112:115], v[152:155], v[206:209], v[112:115]
	v_mfma_f32_16x16x32_bf16 v[112:115], v[156:159], v[210:213], v[112:115]
	v_mfma_f32_16x16x32_bf16 v[96:99], v[144:147], v[214:217], v[96:99]
	v_mfma_f32_16x16x32_bf16 v[96:99], v[148:151], v[218:221], v[96:99]
	v_mfma_f32_16x16x32_bf16 v[88:91], v[152:155], v[214:217], v[88:91]
	v_mfma_f32_16x16x32_bf16 v[88:91], v[156:159], v[218:221], v[88:91]
	s_setprio 2
	s_barrier
; #define PG8_STAGE(bufoff, gbase, voff) do { _Pragma("unroll") for (int _i = 0; _i < 2; ++_i) \
;         __builtin_amdgcn_global_load_lds((const unsigned*)((const char*)(gbase) + (voff)[_i]), (PG8_LAS unsigned*)(lds + (bufoff) + ldsw + _i * 8192), 16, 0, 0); } while (0)
; #define PG8_LDA(dst, b, h) do { _Pragma("unroll") for (int m = 0; m < 4; ++m) _Pragma("unroll") for (int k = 0; k < 2; ++k) dst[m][k] = *(const PG8_LAS bf16x8*)(lds + PG8_SA(b, h) + aoff + m * 2048 + k * 1024); } while (0)
; #define PG8_MMA(ai, bj, At, Bt) do { __builtin_amdgcn_s_setprio(1); _Pragma("unroll") for (int m = 0; m < 4; ++m) _Pragma("unroll") for (int n = 0; n < 2; ++n) _Pragma("unroll") for (int k = 0; k < 2; ++k) \
;         acc[ai][bj][m][n] = __builtin_amdgcn_mfma_f32_16x16x32_bf16(Bt[n][k], At[m][k], acc[ai][bj][m][n], 0, 0, 0); __builtin_amdgcn_s_setprio(0); } while (0)
; #define PG8_WAIT_V(n) asm volatile("s_waitcnt vmcnt(" #n ")" ::: "memory")
; #define PG8_WAIT_L(n) asm volatile("s_waitcnt lgkmcnt(" #n ")" ::: "memory")
; #define PG8_BAR __builtin_amdgcn_s_barrier()
; #define PG8_SCHED __builtin_amdgcn_sched_barrier(0)
; template <class Epi, class Sched, bool ALIGN_EPI = false, bool SP2 = false>
; __device__ __forceinline__ void gemm_phase(PG8_LAS unsigned char* lds, const Gemm g, const Sched& S, const Epi& E) {
;     ...
;             PG8_LDA(At, 1, 1); PG8_STAGE(PG8_SB(1, 0), b3, voffB); PG8_STAGE(PG8_SB(1, 1), b3 + hstep, voffB); PG8_STAGE(PG8_SA(1, 0), a3, voffA);
;             PG8_WAIT_V(8); PG8_WAIT_L(0); PG8_BAR; PG8_MMA(1, 0, At, B0); PG8_MMA(1, 1, At, B1); PG8_BAR; PG8_SCHED;
;     ...
;         if constexpr (ALIGN_EPI) { if (wr == 0) PG8_BAR; }
	v_mfma_f32_16x16x32_bf16 v[68:71], v[144:147], v[222:225], v[68:71]
	v_mfma_f32_16x16x32_bf16 v[68:71], v[148:151], v[226:229], v[68:71]
	v_mfma_f32_16x16x32_bf16 v[64:67], v[152:155], v[222:225], v[64:67]
	v_mfma_f32_16x16x32_bf16 v[64:67], v[156:159], v[226:229], v[64:67]
	s_setprio 0
	s_add_i32 s44, s44, s13
	v_lshl_add_u64 v[200:201], v[200:201], 0, s[16:17]
	s_mov_b32 m0, s44
	ds_read_b128 v[178:181], v187 offset:49152
	ds_read_b128 v[182:185], v187 offset:50176
	ds_read_b128 v[206:209], v187 offset:51200
	ds_read_b128 v[210:213], v187 offset:52224
	ds_read_b128 v[214:217], v187 offset:53248
	ds_read_b128 v[218:221], v187 offset:54272
	ds_read_b128 v[222:225], v187 offset:55296
	ds_read_b128 v[226:229], v187 offset:56320
	global_load_lds_dwordx4 v[200:201], off
	s_add_i32 m0, s44, 0x2000
	s_add_u32 s28, s28, 0x80080
	v_lshl_add_u64 v[200:201], v[230:231], 0, s[16:17]
	s_addc_u32 s29, s29, 0
	s_add_i32 s44, s45, s13
	global_load_lds_dwordx4 v[200:201], off
	v_lshl_add_u64 v[200:201], s[28:29], 0, v[164:165]
	s_mov_b32 m0, s44
	s_nop 0
	global_load_lds_dwordx4 v[200:201], off
	v_lshl_add_u64 v[200:201], s[28:29], 0, v[168:169]
	s_add_i32 m0, s44, 0x2000
	s_nop 0
	global_load_lds_dwordx4 v[200:201], off
	v_lshl_add_u64 v[200:201], v[232:233], 0, s[16:17]
	s_mov_b32 m0, s56
	s_nop 0
	global_load_lds_dwordx4 v[200:201], off
	v_lshl_add_u64 v[200:201], v[234:235], 0, s[16:17]
	s_mov_b32 m0, s57
	s_nop 0
	global_load_lds_dwordx4 v[200:201], off
	s_waitcnt vmcnt(8)
	s_waitcnt lgkmcnt(0)
	s_barrier
	s_setprio 1
	s_waitcnt lgkmcnt(0)
	v_mfma_f32_16x16x32_bf16 v[60:63], v[80:83], v[178:181], v[60:63]
	v_mfma_f32_16x16x32_bf16 v[60:63], v[84:87], v[182:185], v[60:63]
	v_mfma_f32_16x16x32_bf16 v[56:59], v[92:95], v[178:181], v[56:59]
	v_mfma_f32_16x16x32_bf16 v[56:59], v[100:103], v[182:185], v[56:59]
	v_mfma_f32_16x16x32_bf16 v[44:47], v[80:83], v[206:209], v[44:47]
	v_mfma_f32_16x16x32_bf16 v[44:47], v[84:87], v[210:213], v[44:47]
	v_mfma_f32_16x16x32_bf16 v[40:43], v[92:95], v[206:209], v[40:43]
	v_mfma_f32_16x16x32_bf16 v[40:43], v[100:103], v[210:213], v[40:43]
	v_mfma_f32_16x16x32_bf16 v[28:31], v[80:83], v[214:217], v[28:31]
	v_mfma_f32_16x16x32_bf16 v[28:31], v[84:87], v[218:221], v[28:31]
	v_mfma_f32_16x16x32_bf16 v[24:27], v[92:95], v[214:217], v[24:27]
	v_mfma_f32_16x16x32_bf16 v[24:27], v[100:103], v[218:221], v[24:27]
	v_mfma_f32_16x16x32_bf16 v[12:15], v[80:83], v[222:225], v[12:15]
	v_mfma_f32_16x16x32_bf16 v[12:15], v[84:87], v[226:229], v[12:15]
	v_mfma_f32_16x16x32_bf16 v[8:11], v[92:95], v[222:225], v[8:11]
	v_mfma_f32_16x16x32_bf16 v[8:11], v[100:103], v[226:229], v[8:11]
	s_setprio 0
	s_setprio 1
	v_mfma_f32_16x16x32_bf16 v[52:55], v[144:147], v[178:181], v[52:55]
	v_mfma_f32_16x16x32_bf16 v[52:55], v[148:151], v[182:185], v[52:55]
	v_mfma_f32_16x16x32_bf16 v[48:51], v[152:155], v[178:181], v[48:51]
	v_mfma_f32_16x16x32_bf16 v[48:51], v[156:159], v[182:185], v[48:51]
	v_mfma_f32_16x16x32_bf16 v[36:39], v[144:147], v[206:209], v[36:39]
	v_mfma_f32_16x16x32_bf16 v[36:39], v[148:151], v[210:213], v[36:39]
	v_mfma_f32_16x16x32_bf16 v[32:35], v[152:155], v[206:209], v[32:35]
	v_mfma_f32_16x16x32_bf16 v[32:35], v[156:159], v[210:213], v[32:35]
	v_mfma_f32_16x16x32_bf16 v[20:23], v[144:147], v[214:217], v[20:23]
	v_mfma_f32_16x16x32_bf16 v[20:23], v[148:151], v[218:221], v[20:23]
	v_mfma_f32_16x16x32_bf16 v[16:19], v[152:155], v[214:217], v[16:19]
	v_mfma_f32_16x16x32_bf16 v[16:19], v[156:159], v[218:221], v[16:19]
	s_setprio 2
	s_barrier
	v_mfma_f32_16x16x32_bf16 v[4:7], v[144:147], v[222:225], v[4:7]
	v_mfma_f32_16x16x32_bf16 v[4:7], v[148:151], v[226:229], v[4:7]
	v_mfma_f32_16x16x32_bf16 v[0:3], v[152:155], v[222:225], v[0:3]
	v_mfma_f32_16x16x32_bf16 v[0:3], v[156:159], v[226:229], v[0:3]
	s_setprio 0
	s_add_i32 s77, s77, 2
	s_add_u32 s74, s74, 0x100
	s_addc_u32 s75, s75, 0
	s_add_u32 s73, s73, 0x100
	s_addc_u32 s76, s76, 0
	s_cmp_gt_u32 s77, 29
	s_cbranch_scc0 .LBB0_362
	s_and_b64 vcc, exec, s[18:19]
	s_cbranch_vccz .LBB0_365
	s_barrier

; #define PG8_STAGE(bufoff, gbase, voff) do { _Pragma("unroll") for (int _i = 0; _i < 2; ++_i) \
;         __builtin_amdgcn_global_load_lds((const unsigned*)((const char*)(gbase) + (voff)[_i]), (PG8_LAS unsigned*)(lds + (bufoff) + ldsw + _i * 8192), 16, 0, 0); } while (0)
; #define PG8_LDA(dst, b, h) do { _Pragma("unroll") for (int m = 0; m < 4; ++m) _Pragma("unroll") for (int k = 0; k < 2; ++k) dst[m][k] = *(const PG8_LAS bf16x8*)(lds + PG8_SA(b, h) + aoff + m * 2048 + k * 1024); } while (0)
; #define PG8_LDB(dst, b, h) do { _Pragma("unroll") for (int n = 0; n < 2; ++n) _Pragma("unroll") for (int k = 0; k < 2; ++k) dst[n][k] = *(const PG8_LAS bf16x8*)(lds + PG8_SB(b, h) + boff + n * 2048 + k * 1024); } while (0)
; #define PG8_MMA(ai, bj, At, Bt) do { __builtin_amdgcn_s_setprio(1); _Pragma("unroll") for (int m = 0; m < 4; ++m) _Pragma("unroll") for (int n = 0; n < 2; ++n) _Pragma("unroll") for (int k = 0; k < 2; ++k) \
;         acc[ai][bj][m][n] = __builtin_amdgcn_mfma_f32_16x16x32_bf16(Bt[n][k], At[m][k], acc[ai][bj][m][n], 0, 0, 0); __builtin_amdgcn_s_setprio(0); } while (0)
; #define PG8_WAIT_V(n) asm volatile("s_waitcnt vmcnt(" #n ")" ::: "memory")
; #define PG8_WAIT_L(n) asm volatile("s_waitcnt lgkmcnt(" #n ")" ::: "memory")
; #define PG8_BAR __builtin_amdgcn_s_barrier()
; #define PG8_SCHED __builtin_amdgcn_sched_barrier(0)
; template <class Epi, class Sched, bool ALIGN_EPI = false, bool SP2 = false>
; __device__ __forceinline__ void gemm_phase(PG8_LAS unsigned char* lds, const Gemm g, const Sched& S, const Epi& E) {
;     ...
;             const char* a1 = cA + (size_t)(t + 1) * kstep;
;             const char* a2 = last ? nA : cA + (size_t)(t + 2) * kstep; const char* b2 = last ? nB : cB + (size_t)(t + 2) * kstep;
;             const char* a3 = a2 + kstep; const char* b3 = b2 + kstep;
;             if (last && has_next) S.a_ready(nxt);
;             if constexpr (SP2) {
;             PG8_LDB(B0, 0, 0); PG8_LDB(B1, 0, 1); PG8_SCHED; PG8_LDA(At, 0, 0); PG8_STAGE(PG8_SA(1, 1), a1 + hstep, voffA);
;             PG8_WAIT_V(8); PG8_WAIT_L(0); PG8_BAR; PG8_MMA(0, 0, At, B0); PG8_MMA(0, 1, At, B1); PG8_BAR; PG8_SCHED;
;             PG8_LDA(At, 0, 1); PG8_STAGE(PG8_SB(0, 0), b2, voffB); PG8_STAGE(PG8_SB(0, 1), b2 + hstep, voffB); PG8_STAGE(PG8_SA(0, 0), a2, voffA);
.LBB0_416:
	ds_read_b128 v[136:139], v156
	ds_read_b128 v[140:143], v156 offset:1024
	ds_read_b128 v[172:175], v156 offset:2048
	ds_read_b128 v[176:179], v156 offset:3072
	ds_read_b128 v[180:183], v157
	ds_read_b128 v[184:187], v157 offset:1024
	ds_read_b128 v[206:209], v157 offset:2048
	ds_read_b128 v[210:213], v157 offset:3072
	s_add_u32 s28, s68, 0xfff80080
	s_addc_u32 s29, s69, -1
	s_cmp_eq_u32 s79, 28
	s_cselect_b32 s49, s34, s29
	s_cselect_b32 s48, s35, s28
	s_cselect_b32 s29, s23, s78
	s_cselect_b32 s28, s63, s77
	v_lshl_add_u64 v[200:201], s[68:69], 0, v[128:129]
	s_add_i32 m0, s15, 0xc000
	ds_read_b128 v[214:217], v158
	ds_read_b128 v[218:221], v158 offset:1024
	ds_read_b128 v[222:225], v158 offset:2048
	ds_read_b128 v[226:229], v158 offset:3072
	ds_read_b128 v[230:233], v158 offset:4096
	ds_read_b128 v[234:237], v158 offset:5120
	ds_read_b128 v[238:241], v158 offset:6144
	ds_read_b128 v[242:245], v158 offset:7168
	global_load_lds_dwordx4 v[200:201], off
	v_lshl_add_u64 v[200:201], s[68:69], 0, v[130:131]
	s_add_i32 m0, s15, 0xe000
	s_nop 0
	global_load_lds_dwordx4 v[200:201], off
	s_waitcnt vmcnt(8)
	s_waitcnt lgkmcnt(0)
	s_barrier
	s_setprio 1
	s_waitcnt lgkmcnt(0)
	v_mfma_f32_16x16x32_bf16 v[124:127], v[136:139], v[214:217], v[124:127]
	v_mfma_f32_16x16x32_bf16 v[124:127], v[140:143], v[218:221], v[124:127]
	v_mfma_f32_16x16x32_bf16 v[120:123], v[172:175], v[214:217], v[120:123]
	v_mfma_f32_16x16x32_bf16 v[120:123], v[176:179], v[218:221], v[120:123]
	v_mfma_f32_16x16x32_bf16 v[108:111], v[136:139], v[222:225], v[108:111]
	v_mfma_f32_16x16x32_bf16 v[108:111], v[140:143], v[226:229], v[108:111]
	v_mfma_f32_16x16x32_bf16 v[104:107], v[172:175], v[222:225], v[104:107]
	v_mfma_f32_16x16x32_bf16 v[104:107], v[176:179], v[226:229], v[104:107]
	v_mfma_f32_16x16x32_bf16 v[96:99], v[136:139], v[230:233], v[96:99]
	v_mfma_f32_16x16x32_bf16 v[96:99], v[140:143], v[234:237], v[96:99]
	v_mfma_f32_16x16x32_bf16 v[88:91], v[172:175], v[230:233], v[88:91]
	v_mfma_f32_16x16x32_bf16 v[88:91], v[176:179], v[234:237], v[88:91]
	v_mfma_f32_16x16x32_bf16 v[80:83], v[136:139], v[238:241], v[80:83]
	v_mfma_f32_16x16x32_bf16 v[80:83], v[140:143], v[242:245], v[80:83]
	v_mfma_f32_16x16x32_bf16 v[72:75], v[172:175], v[238:241], v[72:75]
	v_mfma_f32_16x16x32_bf16 v[72:75], v[176:179], v[242:245], v[72:75]
	s_setprio 0
	s_setprio 1
	v_mfma_f32_16x16x32_bf16 v[116:119], v[180:183], v[214:217], v[116:119]
	v_mfma_f32_16x16x32_bf16 v[116:119], v[184:187], v[218:221], v[116:119]
	v_mfma_f32_16x16x32_bf16 v[112:115], v[206:209], v[214:217], v[112:115]
	v_mfma_f32_16x16x32_bf16 v[112:115], v[210:213], v[218:221], v[112:115]
	v_mfma_f32_16x16x32_bf16 v[100:103], v[180:183], v[222:225], v[100:103]
	v_mfma_f32_16x16x32_bf16 v[100:103], v[184:187], v[226:229], v[100:103]
	v_mfma_f32_16x16x32_bf16 v[92:95], v[206:209], v[222:225], v[92:95]
	v_mfma_f32_16x16x32_bf16 v[92:95], v[210:213], v[226:229], v[92:95]
	v_mfma_f32_16x16x32_bf16 v[84:87], v[180:183], v[230:233], v[84:87]
	v_mfma_f32_16x16x32_bf16 v[84:87], v[184:187], v[234:237], v[84:87]
	v_mfma_f32_16x16x32_bf16 v[76:79], v[206:209], v[230:233], v[76:79]
	v_mfma_f32_16x16x32_bf16 v[76:79], v[210:213], v[234:237], v[76:79]
	s_setprio 2
	s_barrier
	v_mfma_f32_16x16x32_bf16 v[68:71], v[180:183], v[238:241], v[68:71]
	v_mfma_f32_16x16x32_bf16 v[68:71], v[184:187], v[242:245], v[68:71]
	v_mfma_f32_16x16x32_bf16 v[64:67], v[206:209], v[238:241], v[64:67]
	v_mfma_f32_16x16x32_bf16 v[64:67], v[210:213], v[242:245], v[64:67]
	s_setprio 0
	s_add_i32 s44, s72, s39
	v_lshl_add_u64 v[200:201], s[28:29], 0, v[166:167]
	s_mov_b32 m0, s44
	ds_read_b128 v[214:217], v158 offset:16384
	ds_read_b128 v[218:221], v158 offset:17408
	ds_read_b128 v[222:225], v158 offset:18432
	ds_read_b128 v[226:229], v158 offset:19456
	ds_read_b128 v[230:233], v158 offset:20480
	ds_read_b128 v[234:237], v158 offset:21504
	ds_read_b128 v[238:241], v158 offset:22528
	ds_read_b128 v[242:245], v158 offset:23552
	global_load_lds_dwordx4 v[200:201], off
	s_add_i32 m0, s44, 0x2000
	s_add_u32 s80, s28, 0x80000
	v_lshl_add_u64 v[246:247], s[28:29], 0, v[170:171]
	s_addc_u32 s81, s29, 0
	s_add_i32 s44, s73, s39
	global_load_lds_dwordx4 v[246:247], off
	v_lshl_add_u64 v[248:249], s[80:81], 0, v[166:167]
	s_mov_b32 m0, s44
	v_lshl_add_u64 v[250:251], s[48:49], 0, v[168:169]
	global_load_lds_dwordx4 v[248:249], off
	v_lshl_add_u64 v[248:249], s[80:81], 0, v[170:171]
	s_add_i32 m0, s44, 0x2000
	s_nop 0
	global_load_lds_dwordx4 v[248:249], off
	v_lshl_add_u64 v[248:249], s[48:49], 0, v[164:165]
	s_mov_b32 m0, s15
	s_nop 0
	global_load_lds_dwordx4 v[248:249], off
	s_mov_b32 m0, s41
	s_nop 0
	global_load_lds_dwordx4 v[250:251], off
	s_waitcnt vmcnt(8)
	s_waitcnt lgkmcnt(0)
	s_barrier
; #define PG8_STAGE(bufoff, gbase, voff) do { _Pragma("unroll") for (int _i = 0; _i < 2; ++_i) \
;         __builtin_amdgcn_global_load_lds((const unsigned*)((const char*)(gbase) + (voff)[_i]), (PG8_LAS unsigned*)(lds + (bufoff) + ldsw + _i * 8192), 16, 0, 0); } while (0)
; #define PG8_LDA(dst, b, h) do { _Pragma("unroll") for (int m = 0; m < 4; ++m) _Pragma("unroll") for (int k = 0; k < 2; ++k) dst[m][k] = *(const PG8_LAS bf16x8*)(lds + PG8_SA(b, h) + aoff + m * 2048 + k * 1024); } while (0)
; #define PG8_LDB(dst, b, h) do { _Pragma("unroll") for (int n = 0; n < 2; ++n) _Pragma("unroll") for (int k = 0; k < 2; ++k) dst[n][k] = *(const PG8_LAS bf16x8*)(lds + PG8_SB(b, h) + boff + n * 2048 + k * 1024); } while (0)
; #define PG8_MMA(ai, bj, At, Bt) do { __builtin_amdgcn_s_setprio(1); _Pragma("unroll") for (int m = 0; m < 4; ++m) _Pragma("unroll") for (int n = 0; n < 2; ++n) _Pragma("unroll") for (int k = 0; k < 2; ++k) \
;         acc[ai][bj][m][n] = __builtin_amdgcn_mfma_f32_16x16x32_bf16(Bt[n][k], At[m][k], acc[ai][bj][m][n], 0, 0, 0); __builtin_amdgcn_s_setprio(0); } while (0)
; #define PG8_WAIT_V(n) asm volatile("s_waitcnt vmcnt(" #n ")" ::: "memory")
; #define PG8_WAIT_L(n) asm volatile("s_waitcnt lgkmcnt(" #n ")" ::: "memory")
; #define PG8_BAR __builtin_amdgcn_s_barrier()
; #define PG8_SCHED __builtin_amdgcn_sched_barrier(0)
; template <class Epi, class Sched, bool ALIGN_EPI = false, bool SP2 = false>
; __device__ __forceinline__ void gemm_phase(PG8_LAS unsigned char* lds, const Gemm g, const Sched& S, const Epi& E) {
;     ...
;             PG8_WAIT_V(8); PG8_WAIT_L(0); PG8_BAR; PG8_MMA(1, 0, At, B0); PG8_MMA(1, 1, At, B1); PG8_BAR; PG8_SCHED;
;             PG8_LDB(B0, 1, 0); PG8_LDB(B1, 1, 1); PG8_SCHED; PG8_LDA(At, 1, 0); PG8_STAGE(PG8_SA(0, 1), a2 + hstep, voffA);
;             PG8_WAIT_V(8); PG8_WAIT_L(0); PG8_BAR; PG8_MMA(0, 0, At, B0); PG8_MMA(0, 1, At, B1); PG8_BAR; PG8_SCHED;
	s_setprio 1
	s_waitcnt lgkmcnt(0)
	v_mfma_f32_16x16x32_bf16 v[60:63], v[136:139], v[214:217], v[60:63]
	v_mfma_f32_16x16x32_bf16 v[60:63], v[140:143], v[218:221], v[60:63]
	v_mfma_f32_16x16x32_bf16 v[56:59], v[172:175], v[214:217], v[56:59]
	v_mfma_f32_16x16x32_bf16 v[56:59], v[176:179], v[218:221], v[56:59]
	v_mfma_f32_16x16x32_bf16 v[48:51], v[136:139], v[222:225], v[48:51]
	v_mfma_f32_16x16x32_bf16 v[48:51], v[140:143], v[226:229], v[48:51]
	v_mfma_f32_16x16x32_bf16 v[40:43], v[172:175], v[222:225], v[40:43]
	v_mfma_f32_16x16x32_bf16 v[40:43], v[176:179], v[226:229], v[40:43]
	v_mfma_f32_16x16x32_bf16 v[32:35], v[136:139], v[230:233], v[32:35]
	v_mfma_f32_16x16x32_bf16 v[32:35], v[140:143], v[234:237], v[32:35]
	v_mfma_f32_16x16x32_bf16 v[24:27], v[172:175], v[230:233], v[24:27]
	v_mfma_f32_16x16x32_bf16 v[24:27], v[176:179], v[234:237], v[24:27]
	v_mfma_f32_16x16x32_bf16 v[12:15], v[136:139], v[238:241], v[12:15]
	v_mfma_f32_16x16x32_bf16 v[12:15], v[140:143], v[242:245], v[12:15]
	v_mfma_f32_16x16x32_bf16 v[8:11], v[172:175], v[238:241], v[8:11]
	v_mfma_f32_16x16x32_bf16 v[8:11], v[176:179], v[242:245], v[8:11]
	s_setprio 0
	s_setprio 1
	v_mfma_f32_16x16x32_bf16 v[52:55], v[180:183], v[214:217], v[52:55]
	v_mfma_f32_16x16x32_bf16 v[52:55], v[184:187], v[218:221], v[52:55]
	v_mfma_f32_16x16x32_bf16 v[44:47], v[206:209], v[214:217], v[44:47]
	v_mfma_f32_16x16x32_bf16 v[44:47], v[210:213], v[218:221], v[44:47]
	v_mfma_f32_16x16x32_bf16 v[36:39], v[180:183], v[222:225], v[36:39]
	v_mfma_f32_16x16x32_bf16 v[36:39], v[184:187], v[226:229], v[36:39]
	v_mfma_f32_16x16x32_bf16 v[28:31], v[206:209], v[222:225], v[28:31]
	v_mfma_f32_16x16x32_bf16 v[28:31], v[210:213], v[226:229], v[28:31]
	v_mfma_f32_16x16x32_bf16 v[20:23], v[180:183], v[230:233], v[20:23]
	v_mfma_f32_16x16x32_bf16 v[20:23], v[184:187], v[234:237], v[20:23]
	v_mfma_f32_16x16x32_bf16 v[16:19], v[206:209], v[230:233], v[16:19]
	v_mfma_f32_16x16x32_bf16 v[16:19], v[210:213], v[234:237], v[16:19]
	s_setprio 2
	s_barrier
	v_mfma_f32_16x16x32_bf16 v[4:7], v[180:183], v[238:241], v[4:7]
	v_mfma_f32_16x16x32_bf16 v[4:7], v[184:187], v[242:245], v[4:7]
	v_mfma_f32_16x16x32_bf16 v[0:3], v[206:209], v[238:241], v[0:3]
	v_mfma_f32_16x16x32_bf16 v[0:3], v[210:213], v[242:245], v[0:3]
	s_setprio 0
	s_add_i32 s44, 0, 0x18000
	v_add_u32_e32 v144, s44, v146
	s_add_i32 s45, 0, 0x1c000
	ds_read_b128 v[136:139], v144
	ds_read_b128 v[140:143], v144 offset:1024
	ds_read_b128 v[172:175], v144 offset:2048
	ds_read_b128 v[176:179], v144 offset:3072
	v_add_u32_e32 v144, s45, v146
	ds_read_b128 v[180:183], v144
	ds_read_b128 v[184:187], v144 offset:1024
	ds_read_b128 v[206:209], v144 offset:2048
	ds_read_b128 v[210:213], v144 offset:3072
	s_add_u32 s48, s48, 0x80000
	s_addc_u32 s49, s49, 0
	s_mov_b32 m0, s56
	v_lshl_add_u64 v[252:253], s[48:49], 0, v[164:165]
	ds_read_b128 v[214:217], v158 offset:32768
	ds_read_b128 v[218:221], v158 offset:33792
	ds_read_b128 v[222:225], v158 offset:34816
	ds_read_b128 v[226:229], v158 offset:35840
	ds_read_b128 v[230:233], v158 offset:36864
	ds_read_b128 v[234:237], v158 offset:37888
	ds_read_b128 v[238:241], v158 offset:38912
	ds_read_b128 v[242:245], v158 offset:39936
	global_load_lds_dwordx4 v[252:253], off
	v_lshl_add_u64 v[252:253], s[48:49], 0, v[168:169]
	s_mov_b32 m0, s57
	s_nop 0
	global_load_lds_dwordx4 v[252:253], off
	s_waitcnt vmcnt(8)
	s_waitcnt lgkmcnt(0)
	s_barrier
	s_setprio 1
	s_waitcnt lgkmcnt(0)
	v_mfma_f32_16x16x32_bf16 v[124:127], v[136:139], v[214:217], v[124:127]
	v_mfma_f32_16x16x32_bf16 v[124:127], v[140:143], v[218:221], v[124:127]
	v_mfma_f32_16x16x32_bf16 v[120:123], v[172:175], v[214:217], v[120:123]
	v_mfma_f32_16x16x32_bf16 v[120:123], v[176:179], v[218:221], v[120:123]
	v_mfma_f32_16x16x32_bf16 v[108:111], v[136:139], v[222:225], v[108:111]
	v_mfma_f32_16x16x32_bf16 v[108:111], v[140:143], v[226:229], v[108:111]
	v_mfma_f32_16x16x32_bf16 v[104:107], v[172:175], v[222:225], v[104:107]
	v_mfma_f32_16x16x32_bf16 v[104:107], v[176:179], v[226:229], v[104:107]
	v_mfma_f32_16x16x32_bf16 v[96:99], v[136:139], v[230:233], v[96:99]
	v_mfma_f32_16x16x32_bf16 v[96:99], v[140:143], v[234:237], v[96:99]
	v_mfma_f32_16x16x32_bf16 v[88:91], v[172:175], v[230:233], v[88:91]
	v_mfma_f32_16x16x32_bf16 v[88:91], v[176:179], v[234:237], v[88:91]
	v_mfma_f32_16x16x32_bf16 v[80:83], v[136:139], v[238:241], v[80:83]
	v_mfma_f32_16x16x32_bf16 v[80:83], v[140:143], v[242:245], v[80:83]
	v_mfma_f32_16x16x32_bf16 v[72:75], v[172:175], v[238:241], v[72:75]
	v_mfma_f32_16x16x32_bf16 v[72:75], v[176:179], v[242:245], v[72:75]
	s_setprio 0
	s_setprio 1
	v_mfma_f32_16x16x32_bf16 v[116:119], v[180:183], v[214:217], v[116:119]
	v_mfma_f32_16x16x32_bf16 v[116:119], v[184:187], v[218:221], v[116:119]
	v_mfma_f32_16x16x32_bf16 v[112:115], v[206:209], v[214:217], v[112:115]
	v_mfma_f32_16x16x32_bf16 v[112:115], v[210:213], v[218:221], v[112:115]
	v_mfma_f32_16x16x32_bf16 v[100:103], v[180:183], v[222:225], v[100:103]
	v_mfma_f32_16x16x32_bf16 v[100:103], v[184:187], v[226:229], v[100:103]
	v_mfma_f32_16x16x32_bf16 v[92:95], v[206:209], v[222:225], v[92:95]
	v_mfma_f32_16x16x32_bf16 v[92:95], v[210:213], v[226:229], v[92:95]
	v_mfma_f32_16x16x32_bf16 v[84:87], v[180:183], v[230:233], v[84:87]
	v_mfma_f32_16x16x32_bf16 v[84:87], v[184:187], v[234:237], v[84:87]
	v_mfma_f32_16x16x32_bf16 v[76:79], v[206:209], v[230:233], v[76:79]
	v_mfma_f32_16x16x32_bf16 v[76:79], v[210:213], v[234:237], v[76:79]
	s_setprio 2
	s_barrier
; #define PG8_STAGE(bufoff, gbase, voff) do { _Pragma("unroll") for (int _i = 0; _i < 2; ++_i) \
;         __builtin_amdgcn_global_load_lds((const unsigned*)((const char*)(gbase) + (voff)[_i]), (PG8_LAS unsigned*)(lds + (bufoff) + ldsw + _i * 8192), 16, 0, 0); } while (0)
; #define PG8_LDA(dst, b, h) do { _Pragma("unroll") for (int m = 0; m < 4; ++m) _Pragma("unroll") for (int k = 0; k < 2; ++k) dst[m][k] = *(const PG8_LAS bf16x8*)(lds + PG8_SA(b, h) + aoff + m * 2048 + k * 1024); } while (0)
; #define PG8_MMA(ai, bj, At, Bt) do { __builtin_amdgcn_s_setprio(1); _Pragma("unroll") for (int m = 0; m < 4; ++m) _Pragma("unroll") for (int n = 0; n < 2; ++n) _Pragma("unroll") for (int k = 0; k < 2; ++k) \
;         acc[ai][bj][m][n] = __builtin_amdgcn_mfma_f32_16x16x32_bf16(Bt[n][k], At[m][k], acc[ai][bj][m][n], 0, 0, 0); __builtin_amdgcn_s_setprio(0); } while (0)
; #define PG8_WAIT_V(n) asm volatile("s_waitcnt vmcnt(" #n ")" ::: "memory")
; #define PG8_WAIT_L(n) asm volatile("s_waitcnt lgkmcnt(" #n ")" ::: "memory")
; #define PG8_BAR __builtin_amdgcn_s_barrier()
; #define PG8_SCHED __builtin_amdgcn_sched_barrier(0)
; template <class Epi, class Sched, bool ALIGN_EPI = false, bool SP2 = false>
; __device__ __forceinline__ void gemm_phase(PG8_LAS unsigned char* lds, const Gemm g, const Sched& S, const Epi& E) {
;     ...
;             PG8_LDA(At, 1, 1); PG8_STAGE(PG8_SB(1, 0), b3, voffB); PG8_STAGE(PG8_SB(1, 1), b3 + hstep, voffB); PG8_STAGE(PG8_SA(1, 0), a3, voffA);
;             PG8_WAIT_V(8); PG8_WAIT_L(0); PG8_BAR; PG8_MMA(1, 0, At, B0); PG8_MMA(1, 1, At, B1); PG8_BAR; PG8_SCHED;
;     ...
;         if constexpr (ALIGN_EPI) { if (wr == 0) PG8_BAR; }
	v_mfma_f32_16x16x32_bf16 v[68:71], v[180:183], v[238:241], v[68:71]
	v_mfma_f32_16x16x32_bf16 v[68:71], v[184:187], v[242:245], v[68:71]
	v_mfma_f32_16x16x32_bf16 v[64:67], v[206:209], v[238:241], v[64:67]
	v_mfma_f32_16x16x32_bf16 v[64:67], v[210:213], v[242:245], v[64:67]
	s_setprio 0
	s_add_i32 s44, s44, s39
	v_lshl_add_u64 v[200:201], v[200:201], 0, s[18:19]
	s_mov_b32 m0, s44
	ds_read_b128 v[214:217], v158 offset:49152
	ds_read_b128 v[218:221], v158 offset:50176
	ds_read_b128 v[222:225], v158 offset:51200
	ds_read_b128 v[226:229], v158 offset:52224
	ds_read_b128 v[230:233], v158 offset:53248
	ds_read_b128 v[234:237], v158 offset:54272
	ds_read_b128 v[238:241], v158 offset:55296
	ds_read_b128 v[242:245], v158 offset:56320
	global_load_lds_dwordx4 v[200:201], off
	s_add_i32 m0, s44, 0x2000
	s_add_u32 s28, s28, 0x80080
	v_lshl_add_u64 v[200:201], v[246:247], 0, s[18:19]
	s_addc_u32 s29, s29, 0
	s_add_i32 s44, s45, s39
	global_load_lds_dwordx4 v[200:201], off
	v_lshl_add_u64 v[200:201], s[28:29], 0, v[166:167]
	s_mov_b32 m0, s44
	s_nop 0
	global_load_lds_dwordx4 v[200:201], off
	v_lshl_add_u64 v[200:201], s[28:29], 0, v[170:171]
	s_add_i32 m0, s44, 0x2000
	s_nop 0
	global_load_lds_dwordx4 v[200:201], off
	v_lshl_add_u64 v[200:201], v[248:249], 0, s[18:19]
	s_mov_b32 m0, s70
	s_nop 0
	global_load_lds_dwordx4 v[200:201], off
	v_lshl_add_u64 v[200:201], v[250:251], 0, s[18:19]
	s_mov_b32 m0, s71
	s_nop 0
	global_load_lds_dwordx4 v[200:201], off
	s_waitcnt vmcnt(8)
	s_waitcnt lgkmcnt(0)
	s_barrier
	s_setprio 1
	s_waitcnt lgkmcnt(0)
	v_mfma_f32_16x16x32_bf16 v[60:63], v[136:139], v[214:217], v[60:63]
	v_mfma_f32_16x16x32_bf16 v[60:63], v[140:143], v[218:221], v[60:63]
	v_mfma_f32_16x16x32_bf16 v[56:59], v[172:175], v[214:217], v[56:59]
	v_mfma_f32_16x16x32_bf16 v[56:59], v[176:179], v[218:221], v[56:59]
	v_mfma_f32_16x16x32_bf16 v[48:51], v[136:139], v[222:225], v[48:51]
	v_mfma_f32_16x16x32_bf16 v[48:51], v[140:143], v[226:229], v[48:51]
	v_mfma_f32_16x16x32_bf16 v[40:43], v[172:175], v[222:225], v[40:43]
	v_mfma_f32_16x16x32_bf16 v[40:43], v[176:179], v[226:229], v[40:43]
	v_mfma_f32_16x16x32_bf16 v[32:35], v[136:139], v[230:233], v[32:35]
	v_mfma_f32_16x16x32_bf16 v[32:35], v[140:143], v[234:237], v[32:35]
	v_mfma_f32_16x16x32_bf16 v[24:27], v[172:175], v[230:233], v[24:27]
	v_mfma_f32_16x16x32_bf16 v[24:27], v[176:179], v[234:237], v[24:27]
	v_mfma_f32_16x16x32_bf16 v[12:15], v[136:139], v[238:241], v[12:15]
	v_mfma_f32_16x16x32_bf16 v[12:15], v[140:143], v[242:245], v[12:15]
	v_mfma_f32_16x16x32_bf16 v[8:11], v[172:175], v[238:241], v[8:11]
	v_mfma_f32_16x16x32_bf16 v[8:11], v[176:179], v[242:245], v[8:11]
	s_setprio 0
	s_setprio 1
	v_mfma_f32_16x16x32_bf16 v[52:55], v[180:183], v[214:217], v[52:55]
	v_mfma_f32_16x16x32_bf16 v[52:55], v[184:187], v[218:221], v[52:55]
	v_mfma_f32_16x16x32_bf16 v[44:47], v[206:209], v[214:217], v[44:47]
	v_mfma_f32_16x16x32_bf16 v[44:47], v[210:213], v[218:221], v[44:47]
	v_mfma_f32_16x16x32_bf16 v[36:39], v[180:183], v[222:225], v[36:39]
	v_mfma_f32_16x16x32_bf16 v[36:39], v[184:187], v[226:229], v[36:39]
	v_mfma_f32_16x16x32_bf16 v[28:31], v[206:209], v[222:225], v[28:31]
	v_mfma_f32_16x16x32_bf16 v[28:31], v[210:213], v[226:229], v[28:31]
	v_mfma_f32_16x16x32_bf16 v[20:23], v[180:183], v[230:233], v[20:23]
	v_mfma_f32_16x16x32_bf16 v[20:23], v[184:187], v[234:237], v[20:23]
	v_mfma_f32_16x16x32_bf16 v[16:19], v[206:209], v[230:233], v[16:19]
	v_mfma_f32_16x16x32_bf16 v[16:19], v[210:213], v[234:237], v[16:19]
	s_setprio 2
	s_barrier
	v_mfma_f32_16x16x32_bf16 v[4:7], v[180:183], v[238:241], v[4:7]
	v_mfma_f32_16x16x32_bf16 v[4:7], v[184:187], v[242:245], v[4:7]
	v_mfma_f32_16x16x32_bf16 v[0:3], v[206:209], v[238:241], v[0:3]
	v_mfma_f32_16x16x32_bf16 v[0:3], v[210:213], v[242:245], v[0:3]
	s_setprio 0
	s_add_i32 s79, s79, 2
	s_add_u32 s68, s68, 0x100
	s_addc_u32 s69, s69, 0
	s_add_u32 s77, s77, 0x100
	s_addc_u32 s78, s78, 0
	s_cmp_gt_u32 s79, 29
	s_cbranch_scc0 .LBB0_416
	s_and_b64 vcc, exec, s[20:21]
	s_cbranch_vccz .LBB0_419
	s_barrier

; #define PG8_STAGE(bufoff, gbase, voff) do { _Pragma("unroll") for (int _i = 0; _i < 2; ++_i) \
;         __builtin_amdgcn_global_load_lds((const unsigned*)((const char*)(gbase) + (voff)[_i]), (PG8_LAS unsigned*)(lds + (bufoff) + ldsw + _i * 8192), 16, 0, 0); } while (0)
; #define PG8_LDA(dst, b, h) do { _Pragma("unroll") for (int m = 0; m < 4; ++m) _Pragma("unroll") for (int k = 0; k < 2; ++k) dst[m][k] = *(const PG8_LAS bf16x8*)(lds + PG8_SA(b, h) + aoff + m * 2048 + k * 1024); } while (0)
; #define PG8_LDB(dst, b, h) do { _Pragma("unroll") for (int n = 0; n < 2; ++n) _Pragma("unroll") for (int k = 0; k < 2; ++k) dst[n][k] = *(const PG8_LAS bf16x8*)(lds + PG8_SB(b, h) + boff + n * 2048 + k * 1024); } while (0)
; #define PG8_MMA(ai, bj, At, Bt) do { __builtin_amdgcn_s_setprio(1); _Pragma("unroll") for (int m = 0; m < 4; ++m) _Pragma("unroll") for (int n = 0; n < 2; ++n) _Pragma("unroll") for (int k = 0; k < 2; ++k) \
;         acc[ai][bj][m][n] = __builtin_amdgcn_mfma_f32_16x16x32_bf16(Bt[n][k], At[m][k], acc[ai][bj][m][n], 0, 0, 0); __builtin_amdgcn_s_setprio(0); } while (0)
; #define PG8_WAIT_V(n) asm volatile("s_waitcnt vmcnt(" #n ")" ::: "memory")
; #define PG8_WAIT_L(n) asm volatile("s_waitcnt lgkmcnt(" #n ")" ::: "memory")
; #define PG8_BAR __builtin_amdgcn_s_barrier()
; #define PG8_SCHED __builtin_amdgcn_sched_barrier(0)
; template <class Epi, class Sched, bool ALIGN_EPI = false, bool SP2 = false>
; __device__ __forceinline__ void gemm_phase(PG8_LAS unsigned char* lds, const Gemm g, const Sched& S, const Epi& E) {
;     ...
;             const char* a1 = cA + (size_t)(t + 1) * kstep;
;             const char* a2 = last ? nA : cA + (size_t)(t + 2) * kstep; const char* b2 = last ? nB : cB + (size_t)(t + 2) * kstep;
;             const char* a3 = a2 + kstep; const char* b3 = b2 + kstep;
;             if (last && has_next) S.a_ready(nxt);
;             if constexpr (SP2) {
;             PG8_LDB(B0, 0, 0); PG8_LDB(B1, 0, 1); PG8_SCHED; PG8_LDA(At, 0, 0); PG8_STAGE(PG8_SA(1, 1), a1 + hstep, voffA);
;             PG8_WAIT_V(8); PG8_WAIT_L(0); PG8_BAR; PG8_MMA(0, 0, At, B0); PG8_MMA(0, 1, At, B1); PG8_BAR; PG8_SCHED;
;             PG8_LDA(At, 0, 1); PG8_STAGE(PG8_SB(0, 0), b2, voffB); PG8_STAGE(PG8_SB(0, 1), b2 + hstep, voffB); PG8_STAGE(PG8_SA(0, 0), a2, voffA);
.LBB0_482:
	ds_read_b128 v[76:79], v171
	ds_read_b128 v[84:87], v171 offset:1024
	ds_read_b128 v[92:95], v171 offset:2048
	ds_read_b128 v[96:99], v171 offset:3072
	ds_read_b128 v[144:147], v186
	ds_read_b128 v[148:151], v186 offset:1024
	ds_read_b128 v[152:155], v186 offset:2048
	ds_read_b128 v[156:159], v186 offset:3072
	s_add_u32 s28, s64, 0xffea0080
	s_addc_u32 s29, s65, -1
	s_cmpk_eq_i32 s77, 0x54
	s_cselect_b32 s49, s39, s29
	s_cselect_b32 s48, s38, s28
	s_cselect_b32 s29, s63, s35
	s_cselect_b32 s28, s62, s34
	v_lshl_add_u64 v[200:201], s[64:65], 0, v[172:173]
	s_add_i32 m0, s56, 0xc000
	ds_read_b128 v[178:181], v187
	ds_read_b128 v[182:185], v187 offset:1024
	ds_read_b128 v[206:209], v187 offset:2048
	ds_read_b128 v[210:213], v187 offset:3072
	ds_read_b128 v[214:217], v187 offset:4096
	ds_read_b128 v[218:221], v187 offset:5120
	ds_read_b128 v[222:225], v187 offset:6144
	ds_read_b128 v[226:229], v187 offset:7168
	global_load_lds_dwordx4 v[200:201], off
	v_lshl_add_u64 v[200:201], s[64:65], 0, v[174:175]
	s_add_i32 m0, s56, 0xe000
	s_nop 0
	global_load_lds_dwordx4 v[200:201], off
	s_waitcnt vmcnt(8)
	s_waitcnt lgkmcnt(0)
	s_barrier
	s_setprio 1
	s_waitcnt lgkmcnt(0)
	v_mfma_f32_16x16x32_bf16 v[140:143], v[76:79], v[178:181], v[140:143]
	v_mfma_f32_16x16x32_bf16 v[140:143], v[84:87], v[182:185], v[140:143]
	v_mfma_f32_16x16x32_bf16 v[136:139], v[92:95], v[178:181], v[136:139]
	v_mfma_f32_16x16x32_bf16 v[136:139], v[96:99], v[182:185], v[136:139]
	v_mfma_f32_16x16x32_bf16 v[124:127], v[76:79], v[206:209], v[124:127]
	v_mfma_f32_16x16x32_bf16 v[124:127], v[84:87], v[210:213], v[124:127]
	v_mfma_f32_16x16x32_bf16 v[120:123], v[92:95], v[206:209], v[120:123]
	v_mfma_f32_16x16x32_bf16 v[120:123], v[96:99], v[210:213], v[120:123]
	v_mfma_f32_16x16x32_bf16 v[108:111], v[76:79], v[214:217], v[108:111]
	v_mfma_f32_16x16x32_bf16 v[108:111], v[84:87], v[218:221], v[108:111]
	v_mfma_f32_16x16x32_bf16 v[104:107], v[92:95], v[214:217], v[104:107]
	v_mfma_f32_16x16x32_bf16 v[104:107], v[96:99], v[218:221], v[104:107]
	v_mfma_f32_16x16x32_bf16 v[80:83], v[76:79], v[222:225], v[80:83]
	v_mfma_f32_16x16x32_bf16 v[80:83], v[84:87], v[226:229], v[80:83]
	v_mfma_f32_16x16x32_bf16 v[72:75], v[92:95], v[222:225], v[72:75]
	v_mfma_f32_16x16x32_bf16 v[72:75], v[96:99], v[226:229], v[72:75]
	s_setprio 0
	s_setprio 1
	v_mfma_f32_16x16x32_bf16 v[132:135], v[144:147], v[178:181], v[132:135]
	v_mfma_f32_16x16x32_bf16 v[132:135], v[148:151], v[182:185], v[132:135]
	v_mfma_f32_16x16x32_bf16 v[128:131], v[152:155], v[178:181], v[128:131]
	v_mfma_f32_16x16x32_bf16 v[128:131], v[156:159], v[182:185], v[128:131]
	v_mfma_f32_16x16x32_bf16 v[116:119], v[144:147], v[206:209], v[116:119]
	v_mfma_f32_16x16x32_bf16 v[116:119], v[148:151], v[210:213], v[116:119]
	v_mfma_f32_16x16x32_bf16 v[112:115], v[152:155], v[206:209], v[112:115]
	v_mfma_f32_16x16x32_bf16 v[112:115], v[156:159], v[210:213], v[112:115]
	v_mfma_f32_16x16x32_bf16 v[100:103], v[144:147], v[214:217], v[100:103]
	v_mfma_f32_16x16x32_bf16 v[100:103], v[148:151], v[218:221], v[100:103]
	v_mfma_f32_16x16x32_bf16 v[88:91], v[152:155], v[214:217], v[88:91]
	v_mfma_f32_16x16x32_bf16 v[88:91], v[156:159], v[218:221], v[88:91]
	s_setprio 2
	s_barrier
	v_mfma_f32_16x16x32_bf16 v[68:71], v[144:147], v[222:225], v[68:71]
	v_mfma_f32_16x16x32_bf16 v[68:71], v[148:151], v[226:229], v[68:71]
	v_mfma_f32_16x16x32_bf16 v[64:67], v[152:155], v[222:225], v[64:67]
	v_mfma_f32_16x16x32_bf16 v[64:67], v[156:159], v[226:229], v[64:67]
	s_setprio 0
	s_add_i32 s44, s70, s41
	v_lshl_add_u64 v[200:201], s[28:29], 0, v[160:161]
	s_mov_b32 m0, s44
	ds_read_b128 v[178:181], v187 offset:16384
	ds_read_b128 v[182:185], v187 offset:17408
	ds_read_b128 v[206:209], v187 offset:18432
	ds_read_b128 v[210:213], v187 offset:19456
	ds_read_b128 v[214:217], v187 offset:20480
	ds_read_b128 v[218:221], v187 offset:21504
	ds_read_b128 v[222:225], v187 offset:22528
	ds_read_b128 v[226:229], v187 offset:23552
	global_load_lds_dwordx4 v[200:201], off
	s_add_i32 m0, s44, 0x2000
	s_add_u32 s78, s28, 0x160000
	v_lshl_add_u64 v[230:231], s[28:29], 0, v[162:163]
	s_addc_u32 s79, s29, 0
	s_add_i32 s44, s71, s41
	global_load_lds_dwordx4 v[230:231], off
	v_lshl_add_u64 v[232:233], s[78:79], 0, v[160:161]
	s_mov_b32 m0, s44
	v_lshl_add_u64 v[234:235], s[48:49], 0, v[162:163]
	global_load_lds_dwordx4 v[232:233], off
	v_lshl_add_u64 v[232:233], s[78:79], 0, v[162:163]
	s_add_i32 m0, s44, 0x2000
	s_nop 0
	global_load_lds_dwordx4 v[232:233], off
	v_lshl_add_u64 v[232:233], s[48:49], 0, v[160:161]
	s_mov_b32 m0, s56
	s_nop 0
	global_load_lds_dwordx4 v[232:233], off
	s_mov_b32 m0, s57
	s_nop 0
	global_load_lds_dwordx4 v[234:235], off
	s_waitcnt vmcnt(8)
	s_waitcnt lgkmcnt(0)
	s_barrier
; #define PG8_STAGE(bufoff, gbase, voff) do { _Pragma("unroll") for (int _i = 0; _i < 2; ++_i) \
;         __builtin_amdgcn_global_load_lds((const unsigned*)((const char*)(gbase) + (voff)[_i]), (PG8_LAS unsigned*)(lds + (bufoff) + ldsw + _i * 8192), 16, 0, 0); } while (0)
; #define PG8_LDA(dst, b, h) do { _Pragma("unroll") for (int m = 0; m < 4; ++m) _Pragma("unroll") for (int k = 0; k < 2; ++k) dst[m][k] = *(const PG8_LAS bf16x8*)(lds + PG8_SA(b, h) + aoff + m * 2048 + k * 1024); } while (0)
; #define PG8_LDB(dst, b, h) do { _Pragma("unroll") for (int n = 0; n < 2; ++n) _Pragma("unroll") for (int k = 0; k < 2; ++k) dst[n][k] = *(const PG8_LAS bf16x8*)(lds + PG8_SB(b, h) + boff + n * 2048 + k * 1024); } while (0)
; #define PG8_MMA(ai, bj, At, Bt) do { __builtin_amdgcn_s_setprio(1); _Pragma("unroll") for (int m = 0; m < 4; ++m) _Pragma("unroll") for (int n = 0; n < 2; ++n) _Pragma("unroll") for (int k = 0; k < 2; ++k) \
;         acc[ai][bj][m][n] = __builtin_amdgcn_mfma_f32_16x16x32_bf16(Bt[n][k], At[m][k], acc[ai][bj][m][n], 0, 0, 0); __builtin_amdgcn_s_setprio(0); } while (0)
; #define PG8_WAIT_V(n) asm volatile("s_waitcnt vmcnt(" #n ")" ::: "memory")
; #define PG8_WAIT_L(n) asm volatile("s_waitcnt lgkmcnt(" #n ")" ::: "memory")
; #define PG8_BAR __builtin_amdgcn_s_barrier()
; #define PG8_SCHED __builtin_amdgcn_sched_barrier(0)
; template <class Epi, class Sched, bool ALIGN_EPI = false, bool SP2 = false>
; __device__ __forceinline__ void gemm_phase(PG8_LAS unsigned char* lds, const Gemm g, const Sched& S, const Epi& E) {
;     ...
;             PG8_WAIT_V(8); PG8_WAIT_L(0); PG8_BAR; PG8_MMA(1, 0, At, B0); PG8_MMA(1, 1, At, B1); PG8_BAR; PG8_SCHED;
;             PG8_LDB(B0, 1, 0); PG8_LDB(B1, 1, 1); PG8_SCHED; PG8_LDA(At, 1, 0); PG8_STAGE(PG8_SA(0, 1), a2 + hstep, voffA);
;             PG8_WAIT_V(8); PG8_WAIT_L(0); PG8_BAR; PG8_MMA(0, 0, At, B0); PG8_MMA(0, 1, At, B1); PG8_BAR; PG8_SCHED;
	s_setprio 1
	s_waitcnt lgkmcnt(0)
	v_mfma_f32_16x16x32_bf16 v[60:63], v[76:79], v[178:181], v[60:63]
	v_mfma_f32_16x16x32_bf16 v[60:63], v[84:87], v[182:185], v[60:63]
	v_mfma_f32_16x16x32_bf16 v[56:59], v[92:95], v[178:181], v[56:59]
	v_mfma_f32_16x16x32_bf16 v[56:59], v[96:99], v[182:185], v[56:59]
	v_mfma_f32_16x16x32_bf16 v[44:47], v[76:79], v[206:209], v[44:47]
	v_mfma_f32_16x16x32_bf16 v[44:47], v[84:87], v[210:213], v[44:47]
	v_mfma_f32_16x16x32_bf16 v[40:43], v[92:95], v[206:209], v[40:43]
	v_mfma_f32_16x16x32_bf16 v[40:43], v[96:99], v[210:213], v[40:43]
	v_mfma_f32_16x16x32_bf16 v[28:31], v[76:79], v[214:217], v[28:31]
	v_mfma_f32_16x16x32_bf16 v[28:31], v[84:87], v[218:221], v[28:31]
	v_mfma_f32_16x16x32_bf16 v[24:27], v[92:95], v[214:217], v[24:27]
	v_mfma_f32_16x16x32_bf16 v[24:27], v[96:99], v[218:221], v[24:27]
	v_mfma_f32_16x16x32_bf16 v[12:15], v[76:79], v[222:225], v[12:15]
	v_mfma_f32_16x16x32_bf16 v[12:15], v[84:87], v[226:229], v[12:15]
	v_mfma_f32_16x16x32_bf16 v[8:11], v[92:95], v[222:225], v[8:11]
	v_mfma_f32_16x16x32_bf16 v[8:11], v[96:99], v[226:229], v[8:11]
	s_setprio 0
	s_setprio 1
	v_mfma_f32_16x16x32_bf16 v[52:55], v[144:147], v[178:181], v[52:55]
	v_mfma_f32_16x16x32_bf16 v[52:55], v[148:151], v[182:185], v[52:55]
	v_mfma_f32_16x16x32_bf16 v[48:51], v[152:155], v[178:181], v[48:51]
	v_mfma_f32_16x16x32_bf16 v[48:51], v[156:159], v[182:185], v[48:51]
	v_mfma_f32_16x16x32_bf16 v[36:39], v[144:147], v[206:209], v[36:39]
	v_mfma_f32_16x16x32_bf16 v[36:39], v[148:151], v[210:213], v[36:39]
	v_mfma_f32_16x16x32_bf16 v[32:35], v[152:155], v[206:209], v[32:35]
	v_mfma_f32_16x16x32_bf16 v[32:35], v[156:159], v[210:213], v[32:35]
	v_mfma_f32_16x16x32_bf16 v[20:23], v[144:147], v[214:217], v[20:23]
	v_mfma_f32_16x16x32_bf16 v[20:23], v[148:151], v[218:221], v[20:23]
	v_mfma_f32_16x16x32_bf16 v[16:19], v[152:155], v[214:217], v[16:19]
	v_mfma_f32_16x16x32_bf16 v[16:19], v[156:159], v[218:221], v[16:19]
	s_setprio 2
	s_barrier
	v_mfma_f32_16x16x32_bf16 v[4:7], v[144:147], v[222:225], v[4:7]
	v_mfma_f32_16x16x32_bf16 v[4:7], v[148:151], v[226:229], v[4:7]
	v_mfma_f32_16x16x32_bf16 v[0:3], v[152:155], v[222:225], v[0:3]
	v_mfma_f32_16x16x32_bf16 v[0:3], v[156:159], v[226:229], v[0:3]
	s_setprio 0
	s_add_i32 s44, 0, 0x18000
	s_add_i32 s45, 0, 0x1c000
	v_add_u32_e32 v96, s44, v167
	v_add_u32_e32 v156, s45, v167
	ds_read_b128 v[76:79], v96
	ds_read_b128 v[84:87], v96 offset:1024
	ds_read_b128 v[92:95], v96 offset:2048
	ds_read_b128 v[96:99], v96 offset:3072
	ds_read_b128 v[144:147], v156
	ds_read_b128 v[148:151], v156 offset:1024
	ds_read_b128 v[152:155], v156 offset:2048
	ds_read_b128 v[156:159], v156 offset:3072
	s_add_u32 s48, s48, 0x160000
	s_addc_u32 s49, s49, 0
	s_mov_b32 m0, s61
	v_lshl_add_u64 v[236:237], s[48:49], 0, v[160:161]
	ds_read_b128 v[178:181], v187 offset:32768
	ds_read_b128 v[182:185], v187 offset:33792
	ds_read_b128 v[206:209], v187 offset:34816
	ds_read_b128 v[210:213], v187 offset:35840
	ds_read_b128 v[214:217], v187 offset:36864
	ds_read_b128 v[218:221], v187 offset:37888
	ds_read_b128 v[222:225], v187 offset:38912
	ds_read_b128 v[226:229], v187 offset:39936
	global_load_lds_dwordx4 v[236:237], off
	v_lshl_add_u64 v[236:237], s[48:49], 0, v[162:163]
	s_mov_b32 m0, s66
	s_nop 0
	global_load_lds_dwordx4 v[236:237], off
	s_waitcnt vmcnt(8)
	s_waitcnt lgkmcnt(0)
	s_barrier
	s_setprio 1
	s_waitcnt lgkmcnt(0)
	v_mfma_f32_16x16x32_bf16 v[140:143], v[76:79], v[178:181], v[140:143]
	v_mfma_f32_16x16x32_bf16 v[140:143], v[84:87], v[182:185], v[140:143]
	v_mfma_f32_16x16x32_bf16 v[136:139], v[92:95], v[178:181], v[136:139]
	v_mfma_f32_16x16x32_bf16 v[136:139], v[96:99], v[182:185], v[136:139]
	v_mfma_f32_16x16x32_bf16 v[124:127], v[76:79], v[206:209], v[124:127]
	v_mfma_f32_16x16x32_bf16 v[124:127], v[84:87], v[210:213], v[124:127]
	v_mfma_f32_16x16x32_bf16 v[120:123], v[92:95], v[206:209], v[120:123]
	v_mfma_f32_16x16x32_bf16 v[120:123], v[96:99], v[210:213], v[120:123]
	v_mfma_f32_16x16x32_bf16 v[108:111], v[76:79], v[214:217], v[108:111]
	v_mfma_f32_16x16x32_bf16 v[108:111], v[84:87], v[218:221], v[108:111]
	v_mfma_f32_16x16x32_bf16 v[104:107], v[92:95], v[214:217], v[104:107]
	v_mfma_f32_16x16x32_bf16 v[104:107], v[96:99], v[218:221], v[104:107]
	v_mfma_f32_16x16x32_bf16 v[80:83], v[76:79], v[222:225], v[80:83]
	v_mfma_f32_16x16x32_bf16 v[80:83], v[84:87], v[226:229], v[80:83]
	v_mfma_f32_16x16x32_bf16 v[72:75], v[92:95], v[222:225], v[72:75]
	v_mfma_f32_16x16x32_bf16 v[72:75], v[96:99], v[226:229], v[72:75]
	s_setprio 0
	s_setprio 1
	v_mfma_f32_16x16x32_bf16 v[132:135], v[144:147], v[178:181], v[132:135]
	v_mfma_f32_16x16x32_bf16 v[132:135], v[148:151], v[182:185], v[132:135]
	v_mfma_f32_16x16x32_bf16 v[128:131], v[152:155], v[178:181], v[128:131]
	v_mfma_f32_16x16x32_bf16 v[128:131], v[156:159], v[182:185], v[128:131]
	v_mfma_f32_16x16x32_bf16 v[116:119], v[144:147], v[206:209], v[116:119]
	v_mfma_f32_16x16x32_bf16 v[116:119], v[148:151], v[210:213], v[116:119]
	v_mfma_f32_16x16x32_bf16 v[112:115], v[152:155], v[206:209], v[112:115]
	v_mfma_f32_16x16x32_bf16 v[112:115], v[156:159], v[210:213], v[112:115]
	v_mfma_f32_16x16x32_bf16 v[100:103], v[144:147], v[214:217], v[100:103]
	v_mfma_f32_16x16x32_bf16 v[100:103], v[148:151], v[218:221], v[100:103]
	v_mfma_f32_16x16x32_bf16 v[88:91], v[152:155], v[214:217], v[88:91]
	v_mfma_f32_16x16x32_bf16 v[88:91], v[156:159], v[218:221], v[88:91]
	s_setprio 2
	s_barrier
; #define PG8_STAGE(bufoff, gbase, voff) do { _Pragma("unroll") for (int _i = 0; _i < 2; ++_i) \
;         __builtin_amdgcn_global_load_lds((const unsigned*)((const char*)(gbase) + (voff)[_i]), (PG8_LAS unsigned*)(lds + (bufoff) + ldsw + _i * 8192), 16, 0, 0); } while (0)
; #define PG8_LDA(dst, b, h) do { _Pragma("unroll") for (int m = 0; m < 4; ++m) _Pragma("unroll") for (int k = 0; k < 2; ++k) dst[m][k] = *(const PG8_LAS bf16x8*)(lds + PG8_SA(b, h) + aoff + m * 2048 + k * 1024); } while (0)
; #define PG8_MMA(ai, bj, At, Bt) do { __builtin_amdgcn_s_setprio(1); _Pragma("unroll") for (int m = 0; m < 4; ++m) _Pragma("unroll") for (int n = 0; n < 2; ++n) _Pragma("unroll") for (int k = 0; k < 2; ++k) \
;         acc[ai][bj][m][n] = __builtin_amdgcn_mfma_f32_16x16x32_bf16(Bt[n][k], At[m][k], acc[ai][bj][m][n], 0, 0, 0); __builtin_amdgcn_s_setprio(0); } while (0)
; #define PG8_WAIT_V(n) asm volatile("s_waitcnt vmcnt(" #n ")" ::: "memory")
; #define PG8_WAIT_L(n) asm volatile("s_waitcnt lgkmcnt(" #n ")" ::: "memory")
; #define PG8_BAR __builtin_amdgcn_s_barrier()
; #define PG8_SCHED __builtin_amdgcn_sched_barrier(0)
; template <class Epi, class Sched, bool ALIGN_EPI = false, bool SP2 = false>
; __device__ __forceinline__ void gemm_phase(PG8_LAS unsigned char* lds, const Gemm g, const Sched& S, const Epi& E) {
;     ...
;             PG8_LDA(At, 1, 1); PG8_STAGE(PG8_SB(1, 0), b3, voffB); PG8_STAGE(PG8_SB(1, 1), b3 + hstep, voffB); PG8_STAGE(PG8_SA(1, 0), a3, voffA);
;             PG8_WAIT_V(8); PG8_WAIT_L(0); PG8_BAR; PG8_MMA(1, 0, At, B0); PG8_MMA(1, 1, At, B1); PG8_BAR; PG8_SCHED;
;     ...
;         if constexpr (ALIGN_EPI) { if (wr == 0) PG8_BAR; }
	v_mfma_f32_16x16x32_bf16 v[68:71], v[144:147], v[222:225], v[68:71]
	v_mfma_f32_16x16x32_bf16 v[68:71], v[148:151], v[226:229], v[68:71]
	v_mfma_f32_16x16x32_bf16 v[64:67], v[152:155], v[222:225], v[64:67]
	v_mfma_f32_16x16x32_bf16 v[64:67], v[156:159], v[226:229], v[64:67]
	s_setprio 0
	s_add_i32 s44, s44, s41
	v_lshl_add_u64 v[200:201], v[200:201], 0, s[20:21]
	s_mov_b32 m0, s44
	ds_read_b128 v[178:181], v187 offset:49152
	ds_read_b128 v[182:185], v187 offset:50176
	ds_read_b128 v[206:209], v187 offset:51200
	ds_read_b128 v[210:213], v187 offset:52224
	ds_read_b128 v[214:217], v187 offset:53248
	ds_read_b128 v[218:221], v187 offset:54272
	ds_read_b128 v[222:225], v187 offset:55296
	ds_read_b128 v[226:229], v187 offset:56320
	global_load_lds_dwordx4 v[200:201], off
	s_add_i32 m0, s44, 0x2000
	s_add_u32 s28, s28, 0x160080
	v_lshl_add_u64 v[200:201], v[230:231], 0, s[20:21]
	s_addc_u32 s29, s29, 0
	s_add_i32 s44, s45, s41
	global_load_lds_dwordx4 v[200:201], off
	v_lshl_add_u64 v[200:201], s[28:29], 0, v[160:161]
	s_mov_b32 m0, s44
	s_nop 0
	global_load_lds_dwordx4 v[200:201], off
	v_lshl_add_u64 v[200:201], s[28:29], 0, v[162:163]
	s_add_i32 m0, s44, 0x2000
	s_nop 0
	global_load_lds_dwordx4 v[200:201], off
	v_lshl_add_u64 v[200:201], v[232:233], 0, s[20:21]
	s_mov_b32 m0, s67
	s_nop 0
	global_load_lds_dwordx4 v[200:201], off
	v_lshl_add_u64 v[200:201], v[234:235], 0, s[20:21]
	s_mov_b32 m0, s68
	s_nop 0
	global_load_lds_dwordx4 v[200:201], off
	s_waitcnt vmcnt(8)
	s_waitcnt lgkmcnt(0)
	s_barrier
	s_setprio 1
	s_waitcnt lgkmcnt(0)
	v_mfma_f32_16x16x32_bf16 v[60:63], v[76:79], v[178:181], v[60:63]
	v_mfma_f32_16x16x32_bf16 v[60:63], v[84:87], v[182:185], v[60:63]
	v_mfma_f32_16x16x32_bf16 v[56:59], v[92:95], v[178:181], v[56:59]
	v_mfma_f32_16x16x32_bf16 v[56:59], v[96:99], v[182:185], v[56:59]
	v_mfma_f32_16x16x32_bf16 v[44:47], v[76:79], v[206:209], v[44:47]
	v_mfma_f32_16x16x32_bf16 v[44:47], v[84:87], v[210:213], v[44:47]
	v_mfma_f32_16x16x32_bf16 v[40:43], v[92:95], v[206:209], v[40:43]
	v_mfma_f32_16x16x32_bf16 v[40:43], v[96:99], v[210:213], v[40:43]
	v_mfma_f32_16x16x32_bf16 v[28:31], v[76:79], v[214:217], v[28:31]
	v_mfma_f32_16x16x32_bf16 v[28:31], v[84:87], v[218:221], v[28:31]
	v_mfma_f32_16x16x32_bf16 v[24:27], v[92:95], v[214:217], v[24:27]
	v_mfma_f32_16x16x32_bf16 v[24:27], v[96:99], v[218:221], v[24:27]
	v_mfma_f32_16x16x32_bf16 v[12:15], v[76:79], v[222:225], v[12:15]
	v_mfma_f32_16x16x32_bf16 v[12:15], v[84:87], v[226:229], v[12:15]
	v_mfma_f32_16x16x32_bf16 v[8:11], v[92:95], v[222:225], v[8:11]
	v_mfma_f32_16x16x32_bf16 v[8:11], v[96:99], v[226:229], v[8:11]
	s_setprio 0
	s_setprio 1
	v_mfma_f32_16x16x32_bf16 v[52:55], v[144:147], v[178:181], v[52:55]
	v_mfma_f32_16x16x32_bf16 v[52:55], v[148:151], v[182:185], v[52:55]
	v_mfma_f32_16x16x32_bf16 v[48:51], v[152:155], v[178:181], v[48:51]
	v_mfma_f32_16x16x32_bf16 v[48:51], v[156:159], v[182:185], v[48:51]
	v_mfma_f32_16x16x32_bf16 v[36:39], v[144:147], v[206:209], v[36:39]
	v_mfma_f32_16x16x32_bf16 v[36:39], v[148:151], v[210:213], v[36:39]
	v_mfma_f32_16x16x32_bf16 v[32:35], v[152:155], v[206:209], v[32:35]
	v_mfma_f32_16x16x32_bf16 v[32:35], v[156:159], v[210:213], v[32:35]
	v_mfma_f32_16x16x32_bf16 v[20:23], v[144:147], v[214:217], v[20:23]
	v_mfma_f32_16x16x32_bf16 v[20:23], v[148:151], v[218:221], v[20:23]
	v_mfma_f32_16x16x32_bf16 v[16:19], v[152:155], v[214:217], v[16:19]
	v_mfma_f32_16x16x32_bf16 v[16:19], v[156:159], v[218:221], v[16:19]
	s_setprio 2
	s_barrier
	v_mfma_f32_16x16x32_bf16 v[4:7], v[144:147], v[222:225], v[4:7]
	v_mfma_f32_16x16x32_bf16 v[4:7], v[148:151], v[226:229], v[4:7]
	v_mfma_f32_16x16x32_bf16 v[0:3], v[152:155], v[222:225], v[0:3]
	v_mfma_f32_16x16x32_bf16 v[0:3], v[156:159], v[226:229], v[0:3]
	s_setprio 0
	s_add_i32 s77, s77, 2
	s_add_u32 s64, s64, 0x100
	s_addc_u32 s65, s65, 0
	s_add_u32 s34, s34, 0x100
	s_addc_u32 s35, s35, 0
	s_cmpk_gt_u32 s77, 0x55
	s_cbranch_scc0 .LBB0_482
	s_and_b64 vcc, exec, s[22:23]
	s_cbranch_vccz .LBB0_485
	s_barrier

; #define PG8_STAGE(bufoff, gbase, voff) do { _Pragma("unroll") for (int _i = 0; _i < 2; ++_i) \
;         __builtin_amdgcn_global_load_lds((const unsigned*)((const char*)(gbase) + (voff)[_i]), (PG8_LAS unsigned*)(lds + (bufoff) + ldsw + _i * 8192), 16, 0, 0); } while (0)
; #define PG8_LDA(dst, b, h) do { _Pragma("unroll") for (int m = 0; m < 4; ++m) _Pragma("unroll") for (int k = 0; k < 2; ++k) dst[m][k] = *(const PG8_LAS bf16x8*)(lds + PG8_SA(b, h) + aoff + m * 2048 + k * 1024); } while (0)
; #define PG8_LDB(dst, b, h) do { _Pragma("unroll") for (int n = 0; n < 2; ++n) _Pragma("unroll") for (int k = 0; k < 2; ++k) dst[n][k] = *(const PG8_LAS bf16x8*)(lds + PG8_SB(b, h) + boff + n * 2048 + k * 1024); } while (0)
; #define PG8_MMA(ai, bj, At, Bt) do { __builtin_amdgcn_s_setprio(1); _Pragma("unroll") for (int m = 0; m < 4; ++m) _Pragma("unroll") for (int n = 0; n < 2; ++n) _Pragma("unroll") for (int k = 0; k < 2; ++k) \
;         acc[ai][bj][m][n] = __builtin_amdgcn_mfma_f32_16x16x32_bf16(Bt[n][k], At[m][k], acc[ai][bj][m][n], 0, 0, 0); __builtin_amdgcn_s_setprio(0); } while (0)
; #define PG8_WAIT_V(n) asm volatile("s_waitcnt vmcnt(" #n ")" ::: "memory")
; #define PG8_WAIT_L(n) asm volatile("s_waitcnt lgkmcnt(" #n ")" ::: "memory")
; #define PG8_BAR __builtin_amdgcn_s_barrier()
; #define PG8_SCHED __builtin_amdgcn_sched_barrier(0)
; template <class Epi, class Sched, bool ALIGN_EPI = false, bool SP2 = false>
; __device__ __forceinline__ void gemm_phase(PG8_LAS unsigned char* lds, const Gemm g, const Sched& S, const Epi& E) {
;     ...
;             const char* a1 = cA + (size_t)(t + 1) * kstep;
;             const char* a2 = last ? nA : cA + (size_t)(t + 2) * kstep; const char* b2 = last ? nB : cB + (size_t)(t + 2) * kstep;
;             const char* a3 = a2 + kstep; const char* b3 = b2 + kstep;
;             if (last && has_next) S.a_ready(nxt);
;             if constexpr (SP2) {
;             PG8_LDB(B0, 0, 0); PG8_LDB(B1, 0, 1); PG8_SCHED; PG8_LDA(At, 0, 0); PG8_STAGE(PG8_SA(1, 1), a1 + hstep, voffA);
;             PG8_WAIT_V(8); PG8_WAIT_L(0); PG8_BAR; PG8_MMA(0, 0, At, B0); PG8_MMA(0, 1, At, B1); PG8_BAR; PG8_SCHED;
;             PG8_LDA(At, 0, 1); PG8_STAGE(PG8_SB(0, 0), b2, voffB); PG8_STAGE(PG8_SB(0, 1), b2 + hstep, voffB); PG8_STAGE(PG8_SA(0, 0), a2, voffA);
.LBB0_536:
	ds_read_b128 v[136:139], v156
	ds_read_b128 v[140:143], v156 offset:1024
	ds_read_b128 v[172:175], v156 offset:2048
	ds_read_b128 v[176:179], v156 offset:3072
	ds_read_b128 v[180:183], v157
	ds_read_b128 v[184:187], v157 offset:1024
	ds_read_b128 v[206:209], v157 offset:2048
	ds_read_b128 v[210:213], v157 offset:3072
	s_add_u32 s28, s66, 0xfff80080
	s_addc_u32 s29, s67, -1
	s_cmp_eq_u32 s79, 28
	s_cselect_b32 s49, s34, s29
	s_cselect_b32 s48, s35, s28
	s_cselect_b32 s29, s23, s78
	s_cselect_b32 s28, s39, s77
	v_lshl_add_u64 v[200:201], s[66:67], 0, v[128:129]
	s_add_i32 m0, s11, 0xc000
	ds_read_b128 v[214:217], v158
	ds_read_b128 v[218:221], v158 offset:1024
	ds_read_b128 v[222:225], v158 offset:2048
	ds_read_b128 v[226:229], v158 offset:3072
	ds_read_b128 v[230:233], v158 offset:4096
	ds_read_b128 v[234:237], v158 offset:5120
	ds_read_b128 v[238:241], v158 offset:6144
	ds_read_b128 v[242:245], v158 offset:7168
	global_load_lds_dwordx4 v[200:201], off
	v_lshl_add_u64 v[200:201], s[66:67], 0, v[130:131]
	s_add_i32 m0, s11, 0xe000
	s_nop 0
	global_load_lds_dwordx4 v[200:201], off
	s_waitcnt vmcnt(8)
	s_waitcnt lgkmcnt(0)
	s_barrier
	s_setprio 1
	s_waitcnt lgkmcnt(0)
	v_mfma_f32_16x16x32_bf16 v[124:127], v[136:139], v[214:217], v[124:127]
	v_mfma_f32_16x16x32_bf16 v[124:127], v[140:143], v[218:221], v[124:127]
	v_mfma_f32_16x16x32_bf16 v[120:123], v[172:175], v[214:217], v[120:123]
	v_mfma_f32_16x16x32_bf16 v[120:123], v[176:179], v[218:221], v[120:123]
	v_mfma_f32_16x16x32_bf16 v[108:111], v[136:139], v[222:225], v[108:111]
	v_mfma_f32_16x16x32_bf16 v[108:111], v[140:143], v[226:229], v[108:111]
	v_mfma_f32_16x16x32_bf16 v[104:107], v[172:175], v[222:225], v[104:107]
	v_mfma_f32_16x16x32_bf16 v[104:107], v[176:179], v[226:229], v[104:107]
	v_mfma_f32_16x16x32_bf16 v[96:99], v[136:139], v[230:233], v[96:99]
	v_mfma_f32_16x16x32_bf16 v[96:99], v[140:143], v[234:237], v[96:99]
	v_mfma_f32_16x16x32_bf16 v[88:91], v[172:175], v[230:233], v[88:91]
	v_mfma_f32_16x16x32_bf16 v[88:91], v[176:179], v[234:237], v[88:91]
	v_mfma_f32_16x16x32_bf16 v[80:83], v[136:139], v[238:241], v[80:83]
	v_mfma_f32_16x16x32_bf16 v[80:83], v[140:143], v[242:245], v[80:83]
	v_mfma_f32_16x16x32_bf16 v[72:75], v[172:175], v[238:241], v[72:75]
	v_mfma_f32_16x16x32_bf16 v[72:75], v[176:179], v[242:245], v[72:75]
	s_setprio 0
	s_setprio 1
	v_mfma_f32_16x16x32_bf16 v[116:119], v[180:183], v[214:217], v[116:119]
	v_mfma_f32_16x16x32_bf16 v[116:119], v[184:187], v[218:221], v[116:119]
	v_mfma_f32_16x16x32_bf16 v[112:115], v[206:209], v[214:217], v[112:115]
	v_mfma_f32_16x16x32_bf16 v[112:115], v[210:213], v[218:221], v[112:115]
	v_mfma_f32_16x16x32_bf16 v[100:103], v[180:183], v[222:225], v[100:103]
	v_mfma_f32_16x16x32_bf16 v[100:103], v[184:187], v[226:229], v[100:103]
	v_mfma_f32_16x16x32_bf16 v[92:95], v[206:209], v[222:225], v[92:95]
	v_mfma_f32_16x16x32_bf16 v[92:95], v[210:213], v[226:229], v[92:95]
	v_mfma_f32_16x16x32_bf16 v[84:87], v[180:183], v[230:233], v[84:87]
	v_mfma_f32_16x16x32_bf16 v[84:87], v[184:187], v[234:237], v[84:87]
	v_mfma_f32_16x16x32_bf16 v[76:79], v[206:209], v[230:233], v[76:79]
	v_mfma_f32_16x16x32_bf16 v[76:79], v[210:213], v[234:237], v[76:79]
	s_setprio 2
	s_barrier
	v_mfma_f32_16x16x32_bf16 v[68:71], v[180:183], v[238:241], v[68:71]
	v_mfma_f32_16x16x32_bf16 v[68:71], v[184:187], v[242:245], v[68:71]
	v_mfma_f32_16x16x32_bf16 v[64:67], v[206:209], v[238:241], v[64:67]
	v_mfma_f32_16x16x32_bf16 v[64:67], v[210:213], v[242:245], v[64:67]
	s_setprio 0
	s_add_i32 s44, s72, s41
	v_lshl_add_u64 v[200:201], s[28:29], 0, v[166:167]
	s_mov_b32 m0, s44
	ds_read_b128 v[214:217], v158 offset:16384
	ds_read_b128 v[218:221], v158 offset:17408
	ds_read_b128 v[222:225], v158 offset:18432
	ds_read_b128 v[226:229], v158 offset:19456
	ds_read_b128 v[230:233], v158 offset:20480
	ds_read_b128 v[234:237], v158 offset:21504
	ds_read_b128 v[238:241], v158 offset:22528
	ds_read_b128 v[242:245], v158 offset:23552
	global_load_lds_dwordx4 v[200:201], off
	s_add_i32 m0, s44, 0x2000
	s_add_u32 s80, s28, 0x80000
	v_lshl_add_u64 v[246:247], s[28:29], 0, v[170:171]
	s_addc_u32 s81, s29, 0
	s_add_i32 s44, s73, s41
	global_load_lds_dwordx4 v[246:247], off
	v_lshl_add_u64 v[248:249], s[80:81], 0, v[166:167]
	s_mov_b32 m0, s44
	v_lshl_add_u64 v[250:251], s[48:49], 0, v[168:169]
	global_load_lds_dwordx4 v[248:249], off
	v_lshl_add_u64 v[248:249], s[80:81], 0, v[170:171]
	s_add_i32 m0, s44, 0x2000
	s_nop 0
	global_load_lds_dwordx4 v[248:249], off
	v_lshl_add_u64 v[248:249], s[48:49], 0, v[164:165]
	s_mov_b32 m0, s11
	s_nop 0
	global_load_lds_dwordx4 v[248:249], off
	s_mov_b32 m0, s57
	s_nop 0
	global_load_lds_dwordx4 v[250:251], off
	s_waitcnt vmcnt(8)
	s_waitcnt lgkmcnt(0)
	s_barrier
; #define PG8_STAGE(bufoff, gbase, voff) do { _Pragma("unroll") for (int _i = 0; _i < 2; ++_i) \
;         __builtin_amdgcn_global_load_lds((const unsigned*)((const char*)(gbase) + (voff)[_i]), (PG8_LAS unsigned*)(lds + (bufoff) + ldsw + _i * 8192), 16, 0, 0); } while (0)
; #define PG8_LDA(dst, b, h) do { _Pragma("unroll") for (int m = 0; m < 4; ++m) _Pragma("unroll") for (int k = 0; k < 2; ++k) dst[m][k] = *(const PG8_LAS bf16x8*)(lds + PG8_SA(b, h) + aoff + m * 2048 + k * 1024); } while (0)
; #define PG8_LDB(dst, b, h) do { _Pragma("unroll") for (int n = 0; n < 2; ++n) _Pragma("unroll") for (int k = 0; k < 2; ++k) dst[n][k] = *(const PG8_LAS bf16x8*)(lds + PG8_SB(b, h) + boff + n * 2048 + k * 1024); } while (0)
; #define PG8_MMA(ai, bj, At, Bt) do { __builtin_amdgcn_s_setprio(1); _Pragma("unroll") for (int m = 0; m < 4; ++m) _Pragma("unroll") for (int n = 0; n < 2; ++n) _Pragma("unroll") for (int k = 0; k < 2; ++k) \
;         acc[ai][bj][m][n] = __builtin_amdgcn_mfma_f32_16x16x32_bf16(Bt[n][k], At[m][k], acc[ai][bj][m][n], 0, 0, 0); __builtin_amdgcn_s_setprio(0); } while (0)
; #define PG8_WAIT_V(n) asm volatile("s_waitcnt vmcnt(" #n ")" ::: "memory")
; #define PG8_WAIT_L(n) asm volatile("s_waitcnt lgkmcnt(" #n ")" ::: "memory")
; #define PG8_BAR __builtin_amdgcn_s_barrier()
; #define PG8_SCHED __builtin_amdgcn_sched_barrier(0)
; template <class Epi, class Sched, bool ALIGN_EPI = false, bool SP2 = false>
; __device__ __forceinline__ void gemm_phase(PG8_LAS unsigned char* lds, const Gemm g, const Sched& S, const Epi& E) {
;     ...
;             PG8_WAIT_V(8); PG8_WAIT_L(0); PG8_BAR; PG8_MMA(1, 0, At, B0); PG8_MMA(1, 1, At, B1); PG8_BAR; PG8_SCHED;
;             PG8_LDB(B0, 1, 0); PG8_LDB(B1, 1, 1); PG8_SCHED; PG8_LDA(At, 1, 0); PG8_STAGE(PG8_SA(0, 1), a2 + hstep, voffA);
;             PG8_WAIT_V(8); PG8_WAIT_L(0); PG8_BAR; PG8_MMA(0, 0, At, B0); PG8_MMA(0, 1, At, B1); PG8_BAR; PG8_SCHED;
	s_setprio 1
	s_waitcnt lgkmcnt(0)
	v_mfma_f32_16x16x32_bf16 v[60:63], v[136:139], v[214:217], v[60:63]
	v_mfma_f32_16x16x32_bf16 v[60:63], v[140:143], v[218:221], v[60:63]
	v_mfma_f32_16x16x32_bf16 v[56:59], v[172:175], v[214:217], v[56:59]
	v_mfma_f32_16x16x32_bf16 v[56:59], v[176:179], v[218:221], v[56:59]
	v_mfma_f32_16x16x32_bf16 v[48:51], v[136:139], v[222:225], v[48:51]
	v_mfma_f32_16x16x32_bf16 v[48:51], v[140:143], v[226:229], v[48:51]
	v_mfma_f32_16x16x32_bf16 v[40:43], v[172:175], v[222:225], v[40:43]
	v_mfma_f32_16x16x32_bf16 v[40:43], v[176:179], v[226:229], v[40:43]
	v_mfma_f32_16x16x32_bf16 v[32:35], v[136:139], v[230:233], v[32:35]
	v_mfma_f32_16x16x32_bf16 v[32:35], v[140:143], v[234:237], v[32:35]
	v_mfma_f32_16x16x32_bf16 v[24:27], v[172:175], v[230:233], v[24:27]
	v_mfma_f32_16x16x32_bf16 v[24:27], v[176:179], v[234:237], v[24:27]
	v_mfma_f32_16x16x32_bf16 v[12:15], v[136:139], v[238:241], v[12:15]
	v_mfma_f32_16x16x32_bf16 v[12:15], v[140:143], v[242:245], v[12:15]
	v_mfma_f32_16x16x32_bf16 v[8:11], v[172:175], v[238:241], v[8:11]
	v_mfma_f32_16x16x32_bf16 v[8:11], v[176:179], v[242:245], v[8:11]
	s_setprio 0
	s_setprio 1
	v_mfma_f32_16x16x32_bf16 v[52:55], v[180:183], v[214:217], v[52:55]
	v_mfma_f32_16x16x32_bf16 v[52:55], v[184:187], v[218:221], v[52:55]
	v_mfma_f32_16x16x32_bf16 v[44:47], v[206:209], v[214:217], v[44:47]
	v_mfma_f32_16x16x32_bf16 v[44:47], v[210:213], v[218:221], v[44:47]
	v_mfma_f32_16x16x32_bf16 v[36:39], v[180:183], v[222:225], v[36:39]
	v_mfma_f32_16x16x32_bf16 v[36:39], v[184:187], v[226:229], v[36:39]
	v_mfma_f32_16x16x32_bf16 v[28:31], v[206:209], v[222:225], v[28:31]
	v_mfma_f32_16x16x32_bf16 v[28:31], v[210:213], v[226:229], v[28:31]
	v_mfma_f32_16x16x32_bf16 v[20:23], v[180:183], v[230:233], v[20:23]
	v_mfma_f32_16x16x32_bf16 v[20:23], v[184:187], v[234:237], v[20:23]
	v_mfma_f32_16x16x32_bf16 v[16:19], v[206:209], v[230:233], v[16:19]
	v_mfma_f32_16x16x32_bf16 v[16:19], v[210:213], v[234:237], v[16:19]
	s_setprio 2
	s_barrier
	v_mfma_f32_16x16x32_bf16 v[4:7], v[180:183], v[238:241], v[4:7]
	v_mfma_f32_16x16x32_bf16 v[4:7], v[184:187], v[242:245], v[4:7]
	v_mfma_f32_16x16x32_bf16 v[0:3], v[206:209], v[238:241], v[0:3]
	v_mfma_f32_16x16x32_bf16 v[0:3], v[210:213], v[242:245], v[0:3]
	s_setprio 0
	s_add_i32 s44, 0, 0x18000
	v_add_u32_e32 v144, s44, v146
	s_add_i32 s45, 0, 0x1c000
	ds_read_b128 v[136:139], v144
	ds_read_b128 v[140:143], v144 offset:1024
	ds_read_b128 v[172:175], v144 offset:2048
	ds_read_b128 v[176:179], v144 offset:3072
	v_add_u32_e32 v144, s45, v146
	ds_read_b128 v[180:183], v144
	ds_read_b128 v[184:187], v144 offset:1024
	ds_read_b128 v[206:209], v144 offset:2048
	ds_read_b128 v[210:213], v144 offset:3072
	s_add_u32 s48, s48, 0x80000
	s_addc_u32 s49, s49, 0
	s_mov_b32 m0, s61
	v_lshl_add_u64 v[252:253], s[48:49], 0, v[164:165]
	ds_read_b128 v[214:217], v158 offset:32768
	ds_read_b128 v[218:221], v158 offset:33792
	ds_read_b128 v[222:225], v158 offset:34816
	ds_read_b128 v[226:229], v158 offset:35840
	ds_read_b128 v[230:233], v158 offset:36864
	ds_read_b128 v[234:237], v158 offset:37888
	ds_read_b128 v[238:241], v158 offset:38912
	ds_read_b128 v[242:245], v158 offset:39936
	global_load_lds_dwordx4 v[252:253], off
	v_lshl_add_u64 v[252:253], s[48:49], 0, v[168:169]
	s_mov_b32 m0, s68
	s_nop 0
	global_load_lds_dwordx4 v[252:253], off
	s_waitcnt vmcnt(8)
	s_waitcnt lgkmcnt(0)
	s_barrier
	s_setprio 1
	s_waitcnt lgkmcnt(0)
	v_mfma_f32_16x16x32_bf16 v[124:127], v[136:139], v[214:217], v[124:127]
	v_mfma_f32_16x16x32_bf16 v[124:127], v[140:143], v[218:221], v[124:127]
	v_mfma_f32_16x16x32_bf16 v[120:123], v[172:175], v[214:217], v[120:123]
	v_mfma_f32_16x16x32_bf16 v[120:123], v[176:179], v[218:221], v[120:123]
	v_mfma_f32_16x16x32_bf16 v[108:111], v[136:139], v[222:225], v[108:111]
	v_mfma_f32_16x16x32_bf16 v[108:111], v[140:143], v[226:229], v[108:111]
	v_mfma_f32_16x16x32_bf16 v[104:107], v[172:175], v[222:225], v[104:107]
	v_mfma_f32_16x16x32_bf16 v[104:107], v[176:179], v[226:229], v[104:107]
	v_mfma_f32_16x16x32_bf16 v[96:99], v[136:139], v[230:233], v[96:99]
	v_mfma_f32_16x16x32_bf16 v[96:99], v[140:143], v[234:237], v[96:99]
	v_mfma_f32_16x16x32_bf16 v[88:91], v[172:175], v[230:233], v[88:91]
	v_mfma_f32_16x16x32_bf16 v[88:91], v[176:179], v[234:237], v[88:91]
	v_mfma_f32_16x16x32_bf16 v[80:83], v[136:139], v[238:241], v[80:83]
	v_mfma_f32_16x16x32_bf16 v[80:83], v[140:143], v[242:245], v[80:83]
	v_mfma_f32_16x16x32_bf16 v[72:75], v[172:175], v[238:241], v[72:75]
	v_mfma_f32_16x16x32_bf16 v[72:75], v[176:179], v[242:245], v[72:75]
	s_setprio 0
	s_setprio 1
	v_mfma_f32_16x16x32_bf16 v[116:119], v[180:183], v[214:217], v[116:119]
	v_mfma_f32_16x16x32_bf16 v[116:119], v[184:187], v[218:221], v[116:119]
	v_mfma_f32_16x16x32_bf16 v[112:115], v[206:209], v[214:217], v[112:115]
	v_mfma_f32_16x16x32_bf16 v[112:115], v[210:213], v[218:221], v[112:115]
	v_mfma_f32_16x16x32_bf16 v[100:103], v[180:183], v[222:225], v[100:103]
	v_mfma_f32_16x16x32_bf16 v[100:103], v[184:187], v[226:229], v[100:103]
	v_mfma_f32_16x16x32_bf16 v[92:95], v[206:209], v[222:225], v[92:95]
	v_mfma_f32_16x16x32_bf16 v[92:95], v[210:213], v[226:229], v[92:95]
	v_mfma_f32_16x16x32_bf16 v[84:87], v[180:183], v[230:233], v[84:87]
	v_mfma_f32_16x16x32_bf16 v[84:87], v[184:187], v[234:237], v[84:87]
	v_mfma_f32_16x16x32_bf16 v[76:79], v[206:209], v[230:233], v[76:79]
	v_mfma_f32_16x16x32_bf16 v[76:79], v[210:213], v[234:237], v[76:79]
	s_setprio 2
	s_barrier
; #define PG8_STAGE(bufoff, gbase, voff) do { _Pragma("unroll") for (int _i = 0; _i < 2; ++_i) \
;         __builtin_amdgcn_global_load_lds((const unsigned*)((const char*)(gbase) + (voff)[_i]), (PG8_LAS unsigned*)(lds + (bufoff) + ldsw + _i * 8192), 16, 0, 0); } while (0)
; #define PG8_LDA(dst, b, h) do { _Pragma("unroll") for (int m = 0; m < 4; ++m) _Pragma("unroll") for (int k = 0; k < 2; ++k) dst[m][k] = *(const PG8_LAS bf16x8*)(lds + PG8_SA(b, h) + aoff + m * 2048 + k * 1024); } while (0)
; #define PG8_MMA(ai, bj, At, Bt) do { __builtin_amdgcn_s_setprio(1); _Pragma("unroll") for (int m = 0; m < 4; ++m) _Pragma("unroll") for (int n = 0; n < 2; ++n) _Pragma("unroll") for (int k = 0; k < 2; ++k) \
;         acc[ai][bj][m][n] = __builtin_amdgcn_mfma_f32_16x16x32_bf16(Bt[n][k], At[m][k], acc[ai][bj][m][n], 0, 0, 0); __builtin_amdgcn_s_setprio(0); } while (0)
; #define PG8_WAIT_V(n) asm volatile("s_waitcnt vmcnt(" #n ")" ::: "memory")
; #define PG8_WAIT_L(n) asm volatile("s_waitcnt lgkmcnt(" #n ")" ::: "memory")
; #define PG8_BAR __builtin_amdgcn_s_barrier()
; #define PG8_SCHED __builtin_amdgcn_sched_barrier(0)
; template <class Epi, class Sched, bool ALIGN_EPI = false, bool SP2 = false>
; __device__ __forceinline__ void gemm_phase(PG8_LAS unsigned char* lds, const Gemm g, const Sched& S, const Epi& E) {
;     ...
;             PG8_WAIT_V(8); PG8_WAIT_L(0); PG8_BAR; PG8_MMA(0, 0, At, B0); PG8_MMA(0, 1, At, B1); PG8_BAR; PG8_SCHED;
;             PG8_LDA(At, 1, 1); PG8_STAGE(PG8_SB(1, 0), b3, voffB); PG8_STAGE(PG8_SB(1, 1), b3 + hstep, voffB); PG8_STAGE(PG8_SA(1, 0), a3, voffA);
;             PG8_WAIT_V(8); PG8_WAIT_L(0); PG8_BAR; PG8_MMA(1, 0, At, B0); PG8_MMA(1, 1, At, B1); PG8_BAR; PG8_SCHED;
	v_mfma_f32_16x16x32_bf16 v[68:71], v[180:183], v[238:241], v[68:71]
	v_mfma_f32_16x16x32_bf16 v[68:71], v[184:187], v[242:245], v[68:71]
	v_mfma_f32_16x16x32_bf16 v[64:67], v[206:209], v[238:241], v[64:67]
	v_mfma_f32_16x16x32_bf16 v[64:67], v[210:213], v[242:245], v[64:67]
	s_setprio 0
	s_add_i32 s44, s44, s41
	v_lshl_add_u64 v[200:201], v[200:201], 0, s[18:19]
	s_mov_b32 m0, s44
	ds_read_b128 v[214:217], v158 offset:49152
	ds_read_b128 v[218:221], v158 offset:50176
	ds_read_b128 v[222:225], v158 offset:51200
	ds_read_b128 v[226:229], v158 offset:52224
	ds_read_b128 v[230:233], v158 offset:53248
	ds_read_b128 v[234:237], v158 offset:54272
	ds_read_b128 v[238:241], v158 offset:55296
	ds_read_b128 v[242:245], v158 offset:56320
	global_load_lds_dwordx4 v[200:201], off
	s_add_i32 m0, s44, 0x2000
	s_add_u32 s28, s28, 0x80080
	v_lshl_add_u64 v[200:201], v[246:247], 0, s[18:19]
	s_addc_u32 s29, s29, 0
	s_add_i32 s44, s45, s41
	global_load_lds_dwordx4 v[200:201], off
	v_lshl_add_u64 v[200:201], s[28:29], 0, v[166:167]
	s_mov_b32 m0, s44
	s_nop 0
	global_load_lds_dwordx4 v[200:201], off
	v_lshl_add_u64 v[200:201], s[28:29], 0, v[170:171]
	s_add_i32 m0, s44, 0x2000
	s_nop 0
	global_load_lds_dwordx4 v[200:201], off
	v_lshl_add_u64 v[200:201], v[248:249], 0, s[18:19]
	s_mov_b32 m0, s70
	s_nop 0
	global_load_lds_dwordx4 v[200:201], off
	v_lshl_add_u64 v[200:201], v[250:251], 0, s[18:19]
	s_mov_b32 m0, s71
	s_nop 0
	global_load_lds_dwordx4 v[200:201], off
	s_waitcnt vmcnt(8)
	s_waitcnt lgkmcnt(0)
	s_barrier
	s_setprio 1
	s_waitcnt lgkmcnt(0)
	v_mfma_f32_16x16x32_bf16 v[60:63], v[136:139], v[214:217], v[60:63]
	v_mfma_f32_16x16x32_bf16 v[60:63], v[140:143], v[218:221], v[60:63]
	v_mfma_f32_16x16x32_bf16 v[56:59], v[172:175], v[214:217], v[56:59]
	v_mfma_f32_16x16x32_bf16 v[56:59], v[176:179], v[218:221], v[56:59]
	v_mfma_f32_16x16x32_bf16 v[48:51], v[136:139], v[222:225], v[48:51]
	v_mfma_f32_16x16x32_bf16 v[48:51], v[140:143], v[226:229], v[48:51]
	v_mfma_f32_16x16x32_bf16 v[40:43], v[172:175], v[222:225], v[40:43]
	v_mfma_f32_16x16x32_bf16 v[40:43], v[176:179], v[226:229], v[40:43]
	v_mfma_f32_16x16x32_bf16 v[32:35], v[136:139], v[230:233], v[32:35]
	v_mfma_f32_16x16x32_bf16 v[32:35], v[140:143], v[234:237], v[32:35]
	v_mfma_f32_16x16x32_bf16 v[24:27], v[172:175], v[230:233], v[24:27]
	v_mfma_f32_16x16x32_bf16 v[24:27], v[176:179], v[234:237], v[24:27]
	v_mfma_f32_16x16x32_bf16 v[12:15], v[136:139], v[238:241], v[12:15]
	v_mfma_f32_16x16x32_bf16 v[12:15], v[140:143], v[242:245], v[12:15]
	v_mfma_f32_16x16x32_bf16 v[8:11], v[172:175], v[238:241], v[8:11]
	v_mfma_f32_16x16x32_bf16 v[8:11], v[176:179], v[242:245], v[8:11]
	s_setprio 0
	s_setprio 1
	v_mfma_f32_16x16x32_bf16 v[52:55], v[180:183], v[214:217], v[52:55]
	v_mfma_f32_16x16x32_bf16 v[52:55], v[184:187], v[218:221], v[52:55]
	v_mfma_f32_16x16x32_bf16 v[44:47], v[206:209], v[214:217], v[44:47]
	v_mfma_f32_16x16x32_bf16 v[44:47], v[210:213], v[218:221], v[44:47]
	v_mfma_f32_16x16x32_bf16 v[36:39], v[180:183], v[222:225], v[36:39]
	v_mfma_f32_16x16x32_bf16 v[36:39], v[184:187], v[226:229], v[36:39]
	v_mfma_f32_16x16x32_bf16 v[28:31], v[206:209], v[222:225], v[28:31]
	v_mfma_f32_16x16x32_bf16 v[28:31], v[210:213], v[226:229], v[28:31]
	v_mfma_f32_16x16x32_bf16 v[20:23], v[180:183], v[230:233], v[20:23]
	v_mfma_f32_16x16x32_bf16 v[20:23], v[184:187], v[234:237], v[20:23]
	v_mfma_f32_16x16x32_bf16 v[16:19], v[206:209], v[230:233], v[16:19]
	v_mfma_f32_16x16x32_bf16 v[16:19], v[210:213], v[234:237], v[16:19]
	s_setprio 2
	s_barrier
	v_mfma_f32_16x16x32_bf16 v[4:7], v[180:183], v[238:241], v[4:7]
	v_mfma_f32_16x16x32_bf16 v[4:7], v[184:187], v[242:245], v[4:7]
	v_mfma_f32_16x16x32_bf16 v[0:3], v[206:209], v[238:241], v[0:3]
	v_mfma_f32_16x16x32_bf16 v[0:3], v[210:213], v[242:245], v[0:3]
	s_setprio 0
	s_add_i32 s79, s79, 2
	s_add_u32 s66, s66, 0x100
	s_addc_u32 s67, s67, 0
	s_add_u32 s77, s77, 0x100
	s_addc_u32 s78, s78, 0
	s_cmp_gt_u32 s79, 29
	s_cbranch_scc0 .LBB0_536
	s_and_b64 vcc, exec, s[20:21]
	s_cbranch_vccz .LBB0_539
	s_barrier

; #define PG8_STAGE(bufoff, gbase, voff) do { _Pragma("unroll") for (int _i = 0; _i < 2; ++_i) \
;         __builtin_amdgcn_global_load_lds((const unsigned*)((const char*)(gbase) + (voff)[_i]), (PG8_LAS unsigned*)(lds + (bufoff) + ldsw + _i * 8192), 16, 0, 0); } while (0)
; #define PG8_LDA(dst, b, h) do { _Pragma("unroll") for (int m = 0; m < 4; ++m) _Pragma("unroll") for (int k = 0; k < 2; ++k) dst[m][k] = *(const PG8_LAS bf16x8*)(lds + PG8_SA(b, h) + aoff + m * 2048 + k * 1024); } while (0)
; #define PG8_LDB(dst, b, h) do { _Pragma("unroll") for (int n = 0; n < 2; ++n) _Pragma("unroll") for (int k = 0; k < 2; ++k) dst[n][k] = *(const PG8_LAS bf16x8*)(lds + PG8_SB(b, h) + boff + n * 2048 + k * 1024); } while (0)
; #define PG8_MMA(ai, bj, At, Bt) do { __builtin_amdgcn_s_setprio(1); _Pragma("unroll") for (int m = 0; m < 4; ++m) _Pragma("unroll") for (int n = 0; n < 2; ++n) _Pragma("unroll") for (int k = 0; k < 2; ++k) \
;         acc[ai][bj][m][n] = __builtin_amdgcn_mfma_f32_16x16x32_bf16(Bt[n][k], At[m][k], acc[ai][bj][m][n], 0, 0, 0); __builtin_amdgcn_s_setprio(0); } while (0)
; #define PG8_WAIT_V(n) asm volatile("s_waitcnt vmcnt(" #n ")" ::: "memory")
; #define PG8_WAIT_L(n) asm volatile("s_waitcnt lgkmcnt(" #n ")" ::: "memory")
; #define PG8_BAR __builtin_amdgcn_s_barrier()
; template <class Epi, class Sched, bool ALIGN_EPI = false, bool SP2 = false>
; __device__ __forceinline__ void gemm_phase(PG8_LAS unsigned char* lds, const Gemm g, const Sched& S, const Epi& E) {
;     ...
;             const char* a1 = cA + (size_t)(t + 1) * kstep;
;             const char* a2 = last ? nA : cA + (size_t)(t + 2) * kstep; const char* b2 = last ? nB : cB + (size_t)(t + 2) * kstep;
;             const char* a3 = a2 + kstep; const char* b3 = b2 + kstep;
;             if (last && has_next) S.a_ready(nxt);
;             if constexpr (SP2) {
;             PG8_LDB(B0, 0, 0); PG8_LDB(B1, 0, 1); PG8_SCHED; PG8_LDA(At, 0, 0); PG8_STAGE(PG8_SA(1, 1), a1 + hstep, voffA);
;             PG8_WAIT_V(8); PG8_WAIT_L(0); PG8_BAR; PG8_MMA(0, 0, At, B0); PG8_MMA(0, 1, At, B1); PG8_BAR; PG8_SCHED;
;             PG8_LDA(At, 0, 1); PG8_STAGE(PG8_SB(0, 0), b2, voffB); PG8_STAGE(PG8_SB(0, 1), b2 + hstep, voffB); PG8_STAGE(PG8_SA(0, 0), a2, voffA);
;             PG8_WAIT_V(8); PG8_WAIT_L(0); PG8_BAR; PG8_MMA(1, 0, At, B0); PG8_MMA(1, 1, At, B1); PG8_BAR; PG8_SCHED;
.LBB0_602:
	ds_read_b128 v[76:79], v171
	ds_read_b128 v[84:87], v171 offset:1024
	ds_read_b128 v[92:95], v171 offset:2048
	ds_read_b128 v[96:99], v171 offset:3072
	ds_read_b128 v[144:147], v186
	ds_read_b128 v[148:151], v186 offset:1024
	ds_read_b128 v[152:155], v186 offset:2048
	ds_read_b128 v[156:159], v186 offset:3072
	s_add_u32 s28, s62, 0xffea0080
	s_addc_u32 s29, s63, -1
	s_cmpk_eq_i32 s77, 0x54
	s_cselect_b32 s49, s39, s29
	s_cselect_b32 s48, s38, s28
	s_cselect_b32 s29, s41, s35
	s_cselect_b32 s28, s40, s34
	v_lshl_add_u64 v[200:201], s[62:63], 0, v[172:173]
	s_add_i32 m0, s61, 0xc000
	ds_read_b128 v[178:181], v187
	ds_read_b128 v[182:185], v187 offset:1024
	ds_read_b128 v[206:209], v187 offset:2048
	ds_read_b128 v[210:213], v187 offset:3072
	ds_read_b128 v[214:217], v187 offset:4096
	ds_read_b128 v[218:221], v187 offset:5120
	ds_read_b128 v[222:225], v187 offset:6144
	ds_read_b128 v[226:229], v187 offset:7168
	global_load_lds_dwordx4 v[200:201], off
	v_lshl_add_u64 v[200:201], s[62:63], 0, v[174:175]
	s_add_i32 m0, s61, 0xe000
	s_nop 0
	global_load_lds_dwordx4 v[200:201], off
	s_waitcnt vmcnt(8)
	s_waitcnt lgkmcnt(0)
	s_barrier
	s_setprio 1
	s_waitcnt lgkmcnt(0)
	v_mfma_f32_16x16x32_bf16 v[140:143], v[76:79], v[178:181], v[140:143]
	v_mfma_f32_16x16x32_bf16 v[140:143], v[84:87], v[182:185], v[140:143]
	v_mfma_f32_16x16x32_bf16 v[136:139], v[92:95], v[178:181], v[136:139]
	v_mfma_f32_16x16x32_bf16 v[136:139], v[96:99], v[182:185], v[136:139]
	v_mfma_f32_16x16x32_bf16 v[124:127], v[76:79], v[206:209], v[124:127]
	v_mfma_f32_16x16x32_bf16 v[124:127], v[84:87], v[210:213], v[124:127]
	v_mfma_f32_16x16x32_bf16 v[120:123], v[92:95], v[206:209], v[120:123]
	v_mfma_f32_16x16x32_bf16 v[120:123], v[96:99], v[210:213], v[120:123]
	v_mfma_f32_16x16x32_bf16 v[108:111], v[76:79], v[214:217], v[108:111]
	v_mfma_f32_16x16x32_bf16 v[108:111], v[84:87], v[218:221], v[108:111]
	v_mfma_f32_16x16x32_bf16 v[104:107], v[92:95], v[214:217], v[104:107]
	v_mfma_f32_16x16x32_bf16 v[104:107], v[96:99], v[218:221], v[104:107]
	v_mfma_f32_16x16x32_bf16 v[80:83], v[76:79], v[222:225], v[80:83]
	v_mfma_f32_16x16x32_bf16 v[80:83], v[84:87], v[226:229], v[80:83]
	v_mfma_f32_16x16x32_bf16 v[72:75], v[92:95], v[222:225], v[72:75]
	v_mfma_f32_16x16x32_bf16 v[72:75], v[96:99], v[226:229], v[72:75]
	s_setprio 0
	s_setprio 1
	v_mfma_f32_16x16x32_bf16 v[132:135], v[144:147], v[178:181], v[132:135]
	v_mfma_f32_16x16x32_bf16 v[132:135], v[148:151], v[182:185], v[132:135]
	v_mfma_f32_16x16x32_bf16 v[128:131], v[152:155], v[178:181], v[128:131]
	v_mfma_f32_16x16x32_bf16 v[128:131], v[156:159], v[182:185], v[128:131]
	v_mfma_f32_16x16x32_bf16 v[116:119], v[144:147], v[206:209], v[116:119]
	v_mfma_f32_16x16x32_bf16 v[116:119], v[148:151], v[210:213], v[116:119]
	v_mfma_f32_16x16x32_bf16 v[112:115], v[152:155], v[206:209], v[112:115]
	v_mfma_f32_16x16x32_bf16 v[112:115], v[156:159], v[210:213], v[112:115]
	v_mfma_f32_16x16x32_bf16 v[100:103], v[144:147], v[214:217], v[100:103]
	v_mfma_f32_16x16x32_bf16 v[100:103], v[148:151], v[218:221], v[100:103]
	v_mfma_f32_16x16x32_bf16 v[88:91], v[152:155], v[214:217], v[88:91]
	v_mfma_f32_16x16x32_bf16 v[88:91], v[156:159], v[218:221], v[88:91]
	s_setprio 2
	s_barrier
	v_mfma_f32_16x16x32_bf16 v[68:71], v[144:147], v[222:225], v[68:71]
	v_mfma_f32_16x16x32_bf16 v[68:71], v[148:151], v[226:229], v[68:71]
	v_mfma_f32_16x16x32_bf16 v[64:67], v[152:155], v[222:225], v[64:67]
	v_mfma_f32_16x16x32_bf16 v[64:67], v[156:159], v[226:229], v[64:67]
	s_setprio 0
	s_add_i32 s44, s70, s57
	v_lshl_add_u64 v[200:201], s[28:29], 0, v[160:161]
	s_mov_b32 m0, s44
	ds_read_b128 v[178:181], v187 offset:16384
	ds_read_b128 v[182:185], v187 offset:17408
	ds_read_b128 v[206:209], v187 offset:18432
	ds_read_b128 v[210:213], v187 offset:19456
	ds_read_b128 v[214:217], v187 offset:20480
	ds_read_b128 v[218:221], v187 offset:21504
	ds_read_b128 v[222:225], v187 offset:22528
	ds_read_b128 v[226:229], v187 offset:23552
	global_load_lds_dwordx4 v[200:201], off
	s_add_i32 m0, s44, 0x2000
	s_add_u32 s78, s28, 0x160000
	v_lshl_add_u64 v[230:231], s[28:29], 0, v[162:163]
	s_addc_u32 s79, s29, 0
	s_add_i32 s44, s71, s57
	global_load_lds_dwordx4 v[230:231], off
	v_lshl_add_u64 v[232:233], s[78:79], 0, v[160:161]
	s_mov_b32 m0, s44
	v_lshl_add_u64 v[234:235], s[48:49], 0, v[162:163]
	global_load_lds_dwordx4 v[232:233], off
	v_lshl_add_u64 v[232:233], s[78:79], 0, v[162:163]
	s_add_i32 m0, s44, 0x2000
	s_nop 0
	global_load_lds_dwordx4 v[232:233], off
	v_lshl_add_u64 v[232:233], s[48:49], 0, v[160:161]
	s_mov_b32 m0, s61
	s_nop 0
	global_load_lds_dwordx4 v[232:233], off
	s_mov_b32 m0, s64
	s_nop 0
	global_load_lds_dwordx4 v[234:235], off
	s_waitcnt vmcnt(8)
	s_waitcnt lgkmcnt(0)
	s_barrier
; #define PG8_STAGE(bufoff, gbase, voff) do { _Pragma("unroll") for (int _i = 0; _i < 2; ++_i) \
;         __builtin_amdgcn_global_load_lds((const unsigned*)((const char*)(gbase) + (voff)[_i]), (PG8_LAS unsigned*)(lds + (bufoff) + ldsw + _i * 8192), 16, 0, 0); } while (0)
; #define PG8_LDA(dst, b, h) do { _Pragma("unroll") for (int m = 0; m < 4; ++m) _Pragma("unroll") for (int k = 0; k < 2; ++k) dst[m][k] = *(const PG8_LAS bf16x8*)(lds + PG8_SA(b, h) + aoff + m * 2048 + k * 1024); } while (0)
; #define PG8_LDB(dst, b, h) do { _Pragma("unroll") for (int n = 0; n < 2; ++n) _Pragma("unroll") for (int k = 0; k < 2; ++k) dst[n][k] = *(const PG8_LAS bf16x8*)(lds + PG8_SB(b, h) + boff + n * 2048 + k * 1024); } while (0)
; #define PG8_MMA(ai, bj, At, Bt) do { __builtin_amdgcn_s_setprio(1); _Pragma("unroll") for (int m = 0; m < 4; ++m) _Pragma("unroll") for (int n = 0; n < 2; ++n) _Pragma("unroll") for (int k = 0; k < 2; ++k) \
;         acc[ai][bj][m][n] = __builtin_amdgcn_mfma_f32_16x16x32_bf16(Bt[n][k], At[m][k], acc[ai][bj][m][n], 0, 0, 0); __builtin_amdgcn_s_setprio(0); } while (0)
; #define PG8_WAIT_V(n) asm volatile("s_waitcnt vmcnt(" #n ")" ::: "memory")
; #define PG8_WAIT_L(n) asm volatile("s_waitcnt lgkmcnt(" #n ")" ::: "memory")
; #define PG8_BAR __builtin_amdgcn_s_barrier()
; #define PG8_SCHED __builtin_amdgcn_sched_barrier(0)
; template <class Epi, class Sched, bool ALIGN_EPI = false, bool SP2 = false>
; __device__ __forceinline__ void gemm_phase(PG8_LAS unsigned char* lds, const Gemm g, const Sched& S, const Epi& E) {
;     ...
;             PG8_WAIT_V(8); PG8_WAIT_L(0); PG8_BAR; PG8_MMA(1, 0, At, B0); PG8_MMA(1, 1, At, B1); PG8_BAR; PG8_SCHED;
;             PG8_LDB(B0, 1, 0); PG8_LDB(B1, 1, 1); PG8_SCHED; PG8_LDA(At, 1, 0); PG8_STAGE(PG8_SA(0, 1), a2 + hstep, voffA);
;             PG8_WAIT_V(8); PG8_WAIT_L(0); PG8_BAR; PG8_MMA(0, 0, At, B0); PG8_MMA(0, 1, At, B1); PG8_BAR; PG8_SCHED;
	s_setprio 1
	s_waitcnt lgkmcnt(0)
	v_mfma_f32_16x16x32_bf16 v[60:63], v[76:79], v[178:181], v[60:63]
	v_mfma_f32_16x16x32_bf16 v[60:63], v[84:87], v[182:185], v[60:63]
	v_mfma_f32_16x16x32_bf16 v[56:59], v[92:95], v[178:181], v[56:59]
	v_mfma_f32_16x16x32_bf16 v[56:59], v[96:99], v[182:185], v[56:59]
	v_mfma_f32_16x16x32_bf16 v[44:47], v[76:79], v[206:209], v[44:47]
	v_mfma_f32_16x16x32_bf16 v[44:47], v[84:87], v[210:213], v[44:47]
	v_mfma_f32_16x16x32_bf16 v[40:43], v[92:95], v[206:209], v[40:43]
	v_mfma_f32_16x16x32_bf16 v[40:43], v[96:99], v[210:213], v[40:43]
	v_mfma_f32_16x16x32_bf16 v[28:31], v[76:79], v[214:217], v[28:31]
	v_mfma_f32_16x16x32_bf16 v[28:31], v[84:87], v[218:221], v[28:31]
	v_mfma_f32_16x16x32_bf16 v[24:27], v[92:95], v[214:217], v[24:27]
	v_mfma_f32_16x16x32_bf16 v[24:27], v[96:99], v[218:221], v[24:27]
	v_mfma_f32_16x16x32_bf16 v[12:15], v[76:79], v[222:225], v[12:15]
	v_mfma_f32_16x16x32_bf16 v[12:15], v[84:87], v[226:229], v[12:15]
	v_mfma_f32_16x16x32_bf16 v[8:11], v[92:95], v[222:225], v[8:11]
	v_mfma_f32_16x16x32_bf16 v[8:11], v[96:99], v[226:229], v[8:11]
	s_setprio 0
	s_setprio 1
	v_mfma_f32_16x16x32_bf16 v[52:55], v[144:147], v[178:181], v[52:55]
	v_mfma_f32_16x16x32_bf16 v[52:55], v[148:151], v[182:185], v[52:55]
	v_mfma_f32_16x16x32_bf16 v[48:51], v[152:155], v[178:181], v[48:51]
	v_mfma_f32_16x16x32_bf16 v[48:51], v[156:159], v[182:185], v[48:51]
	v_mfma_f32_16x16x32_bf16 v[36:39], v[144:147], v[206:209], v[36:39]
	v_mfma_f32_16x16x32_bf16 v[36:39], v[148:151], v[210:213], v[36:39]
	v_mfma_f32_16x16x32_bf16 v[32:35], v[152:155], v[206:209], v[32:35]
	v_mfma_f32_16x16x32_bf16 v[32:35], v[156:159], v[210:213], v[32:35]
	v_mfma_f32_16x16x32_bf16 v[20:23], v[144:147], v[214:217], v[20:23]
	v_mfma_f32_16x16x32_bf16 v[20:23], v[148:151], v[218:221], v[20:23]
	v_mfma_f32_16x16x32_bf16 v[16:19], v[152:155], v[214:217], v[16:19]
	v_mfma_f32_16x16x32_bf16 v[16:19], v[156:159], v[218:221], v[16:19]
	s_setprio 2
	s_barrier
	v_mfma_f32_16x16x32_bf16 v[4:7], v[144:147], v[222:225], v[4:7]
	v_mfma_f32_16x16x32_bf16 v[4:7], v[148:151], v[226:229], v[4:7]
	v_mfma_f32_16x16x32_bf16 v[0:3], v[152:155], v[222:225], v[0:3]
	v_mfma_f32_16x16x32_bf16 v[0:3], v[156:159], v[226:229], v[0:3]
	s_setprio 0
	s_add_i32 s44, 0, 0x18000
	s_add_i32 s45, 0, 0x1c000
	v_add_u32_e32 v96, s44, v167
	v_add_u32_e32 v156, s45, v167
	ds_read_b128 v[76:79], v96
	ds_read_b128 v[84:87], v96 offset:1024
	ds_read_b128 v[92:95], v96 offset:2048
	ds_read_b128 v[96:99], v96 offset:3072
	ds_read_b128 v[144:147], v156
	ds_read_b128 v[148:151], v156 offset:1024
	ds_read_b128 v[152:155], v156 offset:2048
	ds_read_b128 v[156:159], v156 offset:3072
	s_add_u32 s48, s48, 0x160000
	s_addc_u32 s49, s49, 0
	s_mov_b32 m0, s65
	v_lshl_add_u64 v[236:237], s[48:49], 0, v[160:161]
	ds_read_b128 v[178:181], v187 offset:32768
	ds_read_b128 v[182:185], v187 offset:33792
	ds_read_b128 v[206:209], v187 offset:34816
	ds_read_b128 v[210:213], v187 offset:35840
	ds_read_b128 v[214:217], v187 offset:36864
	ds_read_b128 v[218:221], v187 offset:37888
	ds_read_b128 v[222:225], v187 offset:38912
	ds_read_b128 v[226:229], v187 offset:39936
	global_load_lds_dwordx4 v[236:237], off
	v_lshl_add_u64 v[236:237], s[48:49], 0, v[162:163]
	s_mov_b32 m0, s66
	s_nop 0
	global_load_lds_dwordx4 v[236:237], off
	s_waitcnt vmcnt(8)
	s_waitcnt lgkmcnt(0)
	s_barrier
	s_setprio 1
	s_waitcnt lgkmcnt(0)
	v_mfma_f32_16x16x32_bf16 v[140:143], v[76:79], v[178:181], v[140:143]
	v_mfma_f32_16x16x32_bf16 v[140:143], v[84:87], v[182:185], v[140:143]
	v_mfma_f32_16x16x32_bf16 v[136:139], v[92:95], v[178:181], v[136:139]
	v_mfma_f32_16x16x32_bf16 v[136:139], v[96:99], v[182:185], v[136:139]
	v_mfma_f32_16x16x32_bf16 v[124:127], v[76:79], v[206:209], v[124:127]
	v_mfma_f32_16x16x32_bf16 v[124:127], v[84:87], v[210:213], v[124:127]
	v_mfma_f32_16x16x32_bf16 v[120:123], v[92:95], v[206:209], v[120:123]
	v_mfma_f32_16x16x32_bf16 v[120:123], v[96:99], v[210:213], v[120:123]
	v_mfma_f32_16x16x32_bf16 v[108:111], v[76:79], v[214:217], v[108:111]
	v_mfma_f32_16x16x32_bf16 v[108:111], v[84:87], v[218:221], v[108:111]
	v_mfma_f32_16x16x32_bf16 v[104:107], v[92:95], v[214:217], v[104:107]
	v_mfma_f32_16x16x32_bf16 v[104:107], v[96:99], v[218:221], v[104:107]
	v_mfma_f32_16x16x32_bf16 v[80:83], v[76:79], v[222:225], v[80:83]
	v_mfma_f32_16x16x32_bf16 v[80:83], v[84:87], v[226:229], v[80:83]
	v_mfma_f32_16x16x32_bf16 v[72:75], v[92:95], v[222:225], v[72:75]
	v_mfma_f32_16x16x32_bf16 v[72:75], v[96:99], v[226:229], v[72:75]
	s_setprio 0
	s_setprio 1
	v_mfma_f32_16x16x32_bf16 v[132:135], v[144:147], v[178:181], v[132:135]
	v_mfma_f32_16x16x32_bf16 v[132:135], v[148:151], v[182:185], v[132:135]
	v_mfma_f32_16x16x32_bf16 v[128:131], v[152:155], v[178:181], v[128:131]
	v_mfma_f32_16x16x32_bf16 v[128:131], v[156:159], v[182:185], v[128:131]
	v_mfma_f32_16x16x32_bf16 v[116:119], v[144:147], v[206:209], v[116:119]
	v_mfma_f32_16x16x32_bf16 v[116:119], v[148:151], v[210:213], v[116:119]
	v_mfma_f32_16x16x32_bf16 v[112:115], v[152:155], v[206:209], v[112:115]
	v_mfma_f32_16x16x32_bf16 v[112:115], v[156:159], v[210:213], v[112:115]
	v_mfma_f32_16x16x32_bf16 v[100:103], v[144:147], v[214:217], v[100:103]
	v_mfma_f32_16x16x32_bf16 v[100:103], v[148:151], v[218:221], v[100:103]
	v_mfma_f32_16x16x32_bf16 v[88:91], v[152:155], v[214:217], v[88:91]
	v_mfma_f32_16x16x32_bf16 v[88:91], v[156:159], v[218:221], v[88:91]
	s_setprio 2
	s_barrier
; #define PG8_STAGE(bufoff, gbase, voff) do { _Pragma("unroll") for (int _i = 0; _i < 2; ++_i) \
;         __builtin_amdgcn_global_load_lds((const unsigned*)((const char*)(gbase) + (voff)[_i]), (PG8_LAS unsigned*)(lds + (bufoff) + ldsw + _i * 8192), 16, 0, 0); } while (0)
; #define PG8_LDA(dst, b, h) do { _Pragma("unroll") for (int m = 0; m < 4; ++m) _Pragma("unroll") for (int k = 0; k < 2; ++k) dst[m][k] = *(const PG8_LAS bf16x8*)(lds + PG8_SA(b, h) + aoff + m * 2048 + k * 1024); } while (0)
; #define PG8_MMA(ai, bj, At, Bt) do { __builtin_amdgcn_s_setprio(1); _Pragma("unroll") for (int m = 0; m < 4; ++m) _Pragma("unroll") for (int n = 0; n < 2; ++n) _Pragma("unroll") for (int k = 0; k < 2; ++k) \
;         acc[ai][bj][m][n] = __builtin_amdgcn_mfma_f32_16x16x32_bf16(Bt[n][k], At[m][k], acc[ai][bj][m][n], 0, 0, 0); __builtin_amdgcn_s_setprio(0); } while (0)
; #define PG8_WAIT_V(n) asm volatile("s_waitcnt vmcnt(" #n ")" ::: "memory")
; #define PG8_WAIT_L(n) asm volatile("s_waitcnt lgkmcnt(" #n ")" ::: "memory")
; #define PG8_BAR __builtin_amdgcn_s_barrier()
; #define PG8_SCHED __builtin_amdgcn_sched_barrier(0)
; template <class Epi, class Sched, bool ALIGN_EPI = false, bool SP2 = false>
; __device__ __forceinline__ void gemm_phase(PG8_LAS unsigned char* lds, const Gemm g, const Sched& S, const Epi& E) {
;     ...
;             PG8_WAIT_V(8); PG8_WAIT_L(0); PG8_BAR; PG8_MMA(0, 0, At, B0); PG8_MMA(0, 1, At, B1); PG8_BAR; PG8_SCHED;
;             PG8_LDA(At, 1, 1); PG8_STAGE(PG8_SB(1, 0), b3, voffB); PG8_STAGE(PG8_SB(1, 1), b3 + hstep, voffB); PG8_STAGE(PG8_SA(1, 0), a3, voffA);
;             PG8_WAIT_V(8); PG8_WAIT_L(0); PG8_BAR; PG8_MMA(1, 0, At, B0); PG8_MMA(1, 1, At, B1); PG8_BAR; PG8_SCHED;
	v_mfma_f32_16x16x32_bf16 v[68:71], v[144:147], v[222:225], v[68:71]
	v_mfma_f32_16x16x32_bf16 v[68:71], v[148:151], v[226:229], v[68:71]
	v_mfma_f32_16x16x32_bf16 v[64:67], v[152:155], v[222:225], v[64:67]
	v_mfma_f32_16x16x32_bf16 v[64:67], v[156:159], v[226:229], v[64:67]
	s_setprio 0
	s_add_i32 s44, s44, s57
	v_lshl_add_u64 v[200:201], v[200:201], 0, s[20:21]
	s_mov_b32 m0, s44
	ds_read_b128 v[178:181], v187 offset:49152
	ds_read_b128 v[182:185], v187 offset:50176
	ds_read_b128 v[206:209], v187 offset:51200
	ds_read_b128 v[210:213], v187 offset:52224
	ds_read_b128 v[214:217], v187 offset:53248
	ds_read_b128 v[218:221], v187 offset:54272
	ds_read_b128 v[222:225], v187 offset:55296
	ds_read_b128 v[226:229], v187 offset:56320
	global_load_lds_dwordx4 v[200:201], off
	s_add_i32 m0, s44, 0x2000
	s_add_u32 s28, s28, 0x160080
	v_lshl_add_u64 v[200:201], v[230:231], 0, s[20:21]
	s_addc_u32 s29, s29, 0
	s_add_i32 s44, s45, s57
	global_load_lds_dwordx4 v[200:201], off
	v_lshl_add_u64 v[200:201], s[28:29], 0, v[160:161]
	s_mov_b32 m0, s44
	s_nop 0
	global_load_lds_dwordx4 v[200:201], off
	v_lshl_add_u64 v[200:201], s[28:29], 0, v[162:163]
	s_add_i32 m0, s44, 0x2000
	s_nop 0
	global_load_lds_dwordx4 v[200:201], off
	v_lshl_add_u64 v[200:201], v[232:233], 0, s[20:21]
	s_mov_b32 m0, s67
	s_nop 0
	global_load_lds_dwordx4 v[200:201], off
	v_lshl_add_u64 v[200:201], v[234:235], 0, s[20:21]
	s_mov_b32 m0, s68
	s_nop 0
	global_load_lds_dwordx4 v[200:201], off
	s_waitcnt vmcnt(8)
	s_waitcnt lgkmcnt(0)
	s_barrier
	s_setprio 1
	s_waitcnt lgkmcnt(0)
	v_mfma_f32_16x16x32_bf16 v[60:63], v[76:79], v[178:181], v[60:63]
	v_mfma_f32_16x16x32_bf16 v[60:63], v[84:87], v[182:185], v[60:63]
	v_mfma_f32_16x16x32_bf16 v[56:59], v[92:95], v[178:181], v[56:59]
	v_mfma_f32_16x16x32_bf16 v[56:59], v[96:99], v[182:185], v[56:59]
	v_mfma_f32_16x16x32_bf16 v[44:47], v[76:79], v[206:209], v[44:47]
	v_mfma_f32_16x16x32_bf16 v[44:47], v[84:87], v[210:213], v[44:47]
	v_mfma_f32_16x16x32_bf16 v[40:43], v[92:95], v[206:209], v[40:43]
	v_mfma_f32_16x16x32_bf16 v[40:43], v[96:99], v[210:213], v[40:43]
	v_mfma_f32_16x16x32_bf16 v[28:31], v[76:79], v[214:217], v[28:31]
	v_mfma_f32_16x16x32_bf16 v[28:31], v[84:87], v[218:221], v[28:31]
	v_mfma_f32_16x16x32_bf16 v[24:27], v[92:95], v[214:217], v[24:27]
	v_mfma_f32_16x16x32_bf16 v[24:27], v[96:99], v[218:221], v[24:27]
	v_mfma_f32_16x16x32_bf16 v[12:15], v[76:79], v[222:225], v[12:15]
	v_mfma_f32_16x16x32_bf16 v[12:15], v[84:87], v[226:229], v[12:15]
	v_mfma_f32_16x16x32_bf16 v[8:11], v[92:95], v[222:225], v[8:11]
	v_mfma_f32_16x16x32_bf16 v[8:11], v[96:99], v[226:229], v[8:11]
	s_setprio 0
	s_setprio 1
	v_mfma_f32_16x16x32_bf16 v[52:55], v[144:147], v[178:181], v[52:55]
	v_mfma_f32_16x16x32_bf16 v[52:55], v[148:151], v[182:185], v[52:55]
	v_mfma_f32_16x16x32_bf16 v[48:51], v[152:155], v[178:181], v[48:51]
	v_mfma_f32_16x16x32_bf16 v[48:51], v[156:159], v[182:185], v[48:51]
	v_mfma_f32_16x16x32_bf16 v[36:39], v[144:147], v[206:209], v[36:39]
	v_mfma_f32_16x16x32_bf16 v[36:39], v[148:151], v[210:213], v[36:39]
	v_mfma_f32_16x16x32_bf16 v[32:35], v[152:155], v[206:209], v[32:35]
	v_mfma_f32_16x16x32_bf16 v[32:35], v[156:159], v[210:213], v[32:35]
	v_mfma_f32_16x16x32_bf16 v[20:23], v[144:147], v[214:217], v[20:23]
	v_mfma_f32_16x16x32_bf16 v[20:23], v[148:151], v[218:221], v[20:23]
	v_mfma_f32_16x16x32_bf16 v[16:19], v[152:155], v[214:217], v[16:19]
	v_mfma_f32_16x16x32_bf16 v[16:19], v[156:159], v[218:221], v[16:19]
	s_setprio 2
	s_barrier
	v_mfma_f32_16x16x32_bf16 v[4:7], v[144:147], v[222:225], v[4:7]
	v_mfma_f32_16x16x32_bf16 v[4:7], v[148:151], v[226:229], v[4:7]
	v_mfma_f32_16x16x32_bf16 v[0:3], v[152:155], v[222:225], v[0:3]
	v_mfma_f32_16x16x32_bf16 v[0:3], v[156:159], v[226:229], v[0:3]
	s_setprio 0
	s_add_i32 s77, s77, 2
	s_add_u32 s62, s62, 0x100
	s_addc_u32 s63, s63, 0
	s_add_u32 s34, s34, 0x100
	s_addc_u32 s35, s35, 0
	s_cmpk_gt_u32 s77, 0x55
	s_cbranch_scc0 .LBB0_602
	s_and_b64 vcc, exec, s[22:23]
	s_cbranch_vccz .LBB0_605
	s_barrier

; #define PG8_STAGE(bufoff, gbase, voff) do { _Pragma("unroll") for (int _i = 0; _i < 2; ++_i) \
;         __builtin_amdgcn_global_load_lds((const unsigned*)((const char*)(gbase) + (voff)[_i]), (PG8_LAS unsigned*)(lds + (bufoff) + ldsw + _i * 8192), 16, 0, 0); } while (0)
; #define PG8_LDA(dst, b, h) do { _Pragma("unroll") for (int m = 0; m < 4; ++m) _Pragma("unroll") for (int k = 0; k < 2; ++k) dst[m][k] = *(const PG8_LAS bf16x8*)(lds + PG8_SA(b, h) + aoff + m * 2048 + k * 1024); } while (0)
; #define PG8_LDB(dst, b, h) do { _Pragma("unroll") for (int n = 0; n < 2; ++n) _Pragma("unroll") for (int k = 0; k < 2; ++k) dst[n][k] = *(const PG8_LAS bf16x8*)(lds + PG8_SB(b, h) + boff + n * 2048 + k * 1024); } while (0)
; #define PG8_MMA(ai, bj, At, Bt) do { __builtin_amdgcn_s_setprio(1); _Pragma("unroll") for (int m = 0; m < 4; ++m) _Pragma("unroll") for (int n = 0; n < 2; ++n) _Pragma("unroll") for (int k = 0; k < 2; ++k) \
;         acc[ai][bj][m][n] = __builtin_amdgcn_mfma_f32_16x16x32_bf16(Bt[n][k], At[m][k], acc[ai][bj][m][n], 0, 0, 0); __builtin_amdgcn_s_setprio(0); } while (0)
; #define PG8_WAIT_V(n) asm volatile("s_waitcnt vmcnt(" #n ")" ::: "memory")
; #define PG8_WAIT_L(n) asm volatile("s_waitcnt lgkmcnt(" #n ")" ::: "memory")
; #define PG8_BAR __builtin_amdgcn_s_barrier()
; template <class Epi, class Sched, bool ALIGN_EPI = false, bool SP2 = false>
; __device__ __forceinline__ void gemm_phase(PG8_LAS unsigned char* lds, const Gemm g, const Sched& S, const Epi& E) {
;     ...
;             const char* a1 = cA + (size_t)(t + 1) * kstep;
;             const char* a2 = last ? nA : cA + (size_t)(t + 2) * kstep; const char* b2 = last ? nB : cB + (size_t)(t + 2) * kstep;
;             const char* a3 = a2 + kstep; const char* b3 = b2 + kstep;
;             if (last && has_next) S.a_ready(nxt);
;             if constexpr (SP2) {
;             PG8_LDB(B0, 0, 0); PG8_LDB(B1, 0, 1); PG8_SCHED; PG8_LDA(At, 0, 0); PG8_STAGE(PG8_SA(1, 1), a1 + hstep, voffA);
;             PG8_WAIT_V(8); PG8_WAIT_L(0); PG8_BAR; PG8_MMA(0, 0, At, B0); PG8_MMA(0, 1, At, B1); PG8_BAR; PG8_SCHED;
;             PG8_LDA(At, 0, 1); PG8_STAGE(PG8_SB(0, 0), b2, voffB); PG8_STAGE(PG8_SB(0, 1), b2 + hstep, voffB); PG8_STAGE(PG8_SA(0, 0), a2, voffA);
;             PG8_WAIT_V(8); PG8_WAIT_L(0); PG8_BAR; PG8_MMA(1, 0, At, B0); PG8_MMA(1, 1, At, B1); PG8_BAR; PG8_SCHED;
.LBB0_719:
	ds_read_b128 v[88:91], v208
	ds_read_b128 v[96:99], v208 offset:1024
	ds_read_b128 v[136:139], v208 offset:2048
	ds_read_b128 v[140:143], v208 offset:3072
	ds_read_b128 v[144:147], v209
	ds_read_b128 v[148:151], v209 offset:1024
	ds_read_b128 v[152:155], v209 offset:2048
	ds_read_b128 v[156:159], v209 offset:3072
	s_add_u32 s44, s62, 0xfff80080
	s_addc_u32 s45, s63, -1
	s_cmp_eq_u32 s76, 28
	s_cselect_b32 s59, s29, s45
	s_cselect_b32 s58, s34, s44
	s_cselect_b32 s57, s23, s75
	s_cselect_b32 s56, s35, s74
	v_lshl_add_u64 v[200:201], s[62:63], 0, v[172:173]
	s_add_i32 m0, s49, 0xc000
	ds_read_b128 v[178:181], v210
	ds_read_b128 v[182:185], v210 offset:1024
	ds_read_b128 v[186:189], v210 offset:2048
	ds_read_b128 v[212:215], v210 offset:3072
	ds_read_b128 v[216:219], v210 offset:4096
	ds_read_b128 v[220:223], v210 offset:5120
	ds_read_b128 v[224:227], v210 offset:6144
	ds_read_b128 v[228:231], v210 offset:7168
	global_load_lds_dwordx4 v[200:201], off
	v_lshl_add_u64 v[200:201], s[62:63], 0, v[174:175]
	s_add_i32 m0, s49, 0xe000
	s_nop 0
	global_load_lds_dwordx4 v[200:201], off
	s_waitcnt vmcnt(8)
	s_waitcnt lgkmcnt(0)
	s_barrier
	s_setprio 1
	s_waitcnt lgkmcnt(0)
	v_mfma_f32_16x16x32_bf16 v[128:131], v[88:91], v[178:181], v[128:131]
	v_mfma_f32_16x16x32_bf16 v[128:131], v[96:99], v[182:185], v[128:131]
	v_mfma_f32_16x16x32_bf16 v[120:123], v[136:139], v[178:181], v[120:123]
	v_mfma_f32_16x16x32_bf16 v[120:123], v[140:143], v[182:185], v[120:123]
	v_mfma_f32_16x16x32_bf16 v[116:119], v[88:91], v[186:189], v[116:119]
	v_mfma_f32_16x16x32_bf16 v[116:119], v[96:99], v[212:215], v[116:119]
	v_mfma_f32_16x16x32_bf16 v[108:111], v[136:139], v[186:189], v[108:111]
	v_mfma_f32_16x16x32_bf16 v[108:111], v[140:143], v[212:215], v[108:111]
	v_mfma_f32_16x16x32_bf16 v[100:103], v[88:91], v[216:219], v[100:103]
	v_mfma_f32_16x16x32_bf16 v[100:103], v[96:99], v[220:223], v[100:103]
	v_mfma_f32_16x16x32_bf16 v[84:87], v[136:139], v[216:219], v[84:87]
	v_mfma_f32_16x16x32_bf16 v[84:87], v[140:143], v[220:223], v[84:87]
	v_mfma_f32_16x16x32_bf16 v[76:79], v[88:91], v[224:227], v[76:79]
	v_mfma_f32_16x16x32_bf16 v[76:79], v[96:99], v[228:231], v[76:79]
	v_mfma_f32_16x16x32_bf16 v[68:71], v[136:139], v[224:227], v[68:71]
	v_mfma_f32_16x16x32_bf16 v[68:71], v[140:143], v[228:231], v[68:71]
	s_setprio 0
	s_setprio 1
	v_mfma_f32_16x16x32_bf16 v[132:135], v[144:147], v[178:181], v[132:135]
	v_mfma_f32_16x16x32_bf16 v[132:135], v[148:151], v[182:185], v[132:135]
	v_mfma_f32_16x16x32_bf16 v[124:127], v[152:155], v[178:181], v[124:127]
	v_mfma_f32_16x16x32_bf16 v[124:127], v[156:159], v[182:185], v[124:127]
	v_mfma_f32_16x16x32_bf16 v[112:115], v[144:147], v[186:189], v[112:115]
	v_mfma_f32_16x16x32_bf16 v[112:115], v[148:151], v[212:215], v[112:115]
	v_mfma_f32_16x16x32_bf16 v[104:107], v[152:155], v[186:189], v[104:107]
	v_mfma_f32_16x16x32_bf16 v[104:107], v[156:159], v[212:215], v[104:107]
	v_mfma_f32_16x16x32_bf16 v[92:95], v[144:147], v[216:219], v[92:95]
	v_mfma_f32_16x16x32_bf16 v[92:95], v[148:151], v[220:223], v[92:95]
	v_mfma_f32_16x16x32_bf16 v[80:83], v[152:155], v[216:219], v[80:83]
	v_mfma_f32_16x16x32_bf16 v[80:83], v[156:159], v[220:223], v[80:83]
	s_setprio 2
	s_barrier
	v_mfma_f32_16x16x32_bf16 v[72:75], v[144:147], v[224:227], v[72:75]
	v_mfma_f32_16x16x32_bf16 v[72:75], v[148:151], v[228:231], v[72:75]
	v_mfma_f32_16x16x32_bf16 v[64:67], v[152:155], v[224:227], v[64:67]
	v_mfma_f32_16x16x32_bf16 v[64:67], v[156:159], v[228:231], v[64:67]
	s_setprio 0
	s_add_i32 s44, s71, s65
	v_lshl_add_u64 v[200:201], s[56:57], 0, v[164:165]
	s_mov_b32 m0, s44
	ds_read_b128 v[178:181], v210 offset:16384
	ds_read_b128 v[182:185], v210 offset:17408
	ds_read_b128 v[186:189], v210 offset:18432
	ds_read_b128 v[212:215], v210 offset:19456
	ds_read_b128 v[216:219], v210 offset:20480
	ds_read_b128 v[220:223], v210 offset:21504
	ds_read_b128 v[224:227], v210 offset:22528
	ds_read_b128 v[228:231], v210 offset:23552
	global_load_lds_dwordx4 v[200:201], off
	s_add_i32 m0, s44, 0x2000
	s_add_u32 s78, s56, 0x80000
	v_lshl_add_u64 v[232:233], s[56:57], 0, v[168:169]
	s_addc_u32 s79, s57, 0
	s_add_i32 s44, s72, s65
	global_load_lds_dwordx4 v[232:233], off
	v_lshl_add_u64 v[234:235], s[78:79], 0, v[164:165]
	s_mov_b32 m0, s44
	v_lshl_add_u64 v[236:237], s[58:59], 0, v[168:169]
	global_load_lds_dwordx4 v[234:235], off
	v_lshl_add_u64 v[234:235], s[78:79], 0, v[168:169]
	s_add_i32 m0, s44, 0x2000
	s_nop 0
	global_load_lds_dwordx4 v[234:235], off
	v_lshl_add_u64 v[234:235], s[58:59], 0, v[164:165]
	s_mov_b32 m0, s49
	s_nop 0
	global_load_lds_dwordx4 v[234:235], off
	s_mov_b32 m0, s61
	s_nop 0
	global_load_lds_dwordx4 v[236:237], off
	s_waitcnt vmcnt(8)
	s_waitcnt lgkmcnt(0)
	s_barrier
; #define PG8_STAGE(bufoff, gbase, voff) do { _Pragma("unroll") for (int _i = 0; _i < 2; ++_i) \
;         __builtin_amdgcn_global_load_lds((const unsigned*)((const char*)(gbase) + (voff)[_i]), (PG8_LAS unsigned*)(lds + (bufoff) + ldsw + _i * 8192), 16, 0, 0); } while (0)
; #define PG8_LDA(dst, b, h) do { _Pragma("unroll") for (int m = 0; m < 4; ++m) _Pragma("unroll") for (int k = 0; k < 2; ++k) dst[m][k] = *(const PG8_LAS bf16x8*)(lds + PG8_SA(b, h) + aoff + m * 2048 + k * 1024); } while (0)
; #define PG8_LDB(dst, b, h) do { _Pragma("unroll") for (int n = 0; n < 2; ++n) _Pragma("unroll") for (int k = 0; k < 2; ++k) dst[n][k] = *(const PG8_LAS bf16x8*)(lds + PG8_SB(b, h) + boff + n * 2048 + k * 1024); } while (0)
; #define PG8_MMA(ai, bj, At, Bt) do { __builtin_amdgcn_s_setprio(1); _Pragma("unroll") for (int m = 0; m < 4; ++m) _Pragma("unroll") for (int n = 0; n < 2; ++n) _Pragma("unroll") for (int k = 0; k < 2; ++k) \
;         acc[ai][bj][m][n] = __builtin_amdgcn_mfma_f32_16x16x32_bf16(Bt[n][k], At[m][k], acc[ai][bj][m][n], 0, 0, 0); __builtin_amdgcn_s_setprio(0); } while (0)
; #define PG8_WAIT_V(n) asm volatile("s_waitcnt vmcnt(" #n ")" ::: "memory")
; #define PG8_WAIT_L(n) asm volatile("s_waitcnt lgkmcnt(" #n ")" ::: "memory")
; #define PG8_BAR __builtin_amdgcn_s_barrier()
; #define PG8_SCHED __builtin_amdgcn_sched_barrier(0)
; template <class Epi, class Sched, bool ALIGN_EPI = false, bool SP2 = false>
; __device__ __forceinline__ void gemm_phase(PG8_LAS unsigned char* lds, const Gemm g, const Sched& S, const Epi& E) {
;     ...
;             PG8_WAIT_V(8); PG8_WAIT_L(0); PG8_BAR; PG8_MMA(1, 0, At, B0); PG8_MMA(1, 1, At, B1); PG8_BAR; PG8_SCHED;
;             PG8_LDB(B0, 1, 0); PG8_LDB(B1, 1, 1); PG8_SCHED; PG8_LDA(At, 1, 0); PG8_STAGE(PG8_SA(0, 1), a2 + hstep, voffA);
;             PG8_WAIT_V(8); PG8_WAIT_L(0); PG8_BAR; PG8_MMA(0, 0, At, B0); PG8_MMA(0, 1, At, B1); PG8_BAR; PG8_SCHED;
	s_setprio 1
	s_waitcnt lgkmcnt(0)
	v_mfma_f32_16x16x32_bf16 v[56:59], v[88:91], v[178:181], v[56:59]
	v_mfma_f32_16x16x32_bf16 v[56:59], v[96:99], v[182:185], v[56:59]
	v_mfma_f32_16x16x32_bf16 v[48:51], v[136:139], v[178:181], v[48:51]
	v_mfma_f32_16x16x32_bf16 v[48:51], v[140:143], v[182:185], v[48:51]
	v_mfma_f32_16x16x32_bf16 v[44:47], v[88:91], v[186:189], v[44:47]
	v_mfma_f32_16x16x32_bf16 v[44:47], v[96:99], v[212:215], v[44:47]
	v_mfma_f32_16x16x32_bf16 v[36:39], v[136:139], v[186:189], v[36:39]
	v_mfma_f32_16x16x32_bf16 v[36:39], v[140:143], v[212:215], v[36:39]
	v_mfma_f32_16x16x32_bf16 v[28:31], v[88:91], v[216:219], v[28:31]
	v_mfma_f32_16x16x32_bf16 v[28:31], v[96:99], v[220:223], v[28:31]
	v_mfma_f32_16x16x32_bf16 v[20:23], v[136:139], v[216:219], v[20:23]
	v_mfma_f32_16x16x32_bf16 v[20:23], v[140:143], v[220:223], v[20:23]
	v_mfma_f32_16x16x32_bf16 v[12:15], v[88:91], v[224:227], v[12:15]
	v_mfma_f32_16x16x32_bf16 v[12:15], v[96:99], v[228:231], v[12:15]
	v_mfma_f32_16x16x32_bf16 v[4:7], v[136:139], v[224:227], v[4:7]
	v_mfma_f32_16x16x32_bf16 v[4:7], v[140:143], v[228:231], v[4:7]
	s_setprio 0
	s_setprio 1
	v_mfma_f32_16x16x32_bf16 v[60:63], v[144:147], v[178:181], v[60:63]
	v_mfma_f32_16x16x32_bf16 v[60:63], v[148:151], v[182:185], v[60:63]
	v_mfma_f32_16x16x32_bf16 v[52:55], v[152:155], v[178:181], v[52:55]
	v_mfma_f32_16x16x32_bf16 v[52:55], v[156:159], v[182:185], v[52:55]
	v_mfma_f32_16x16x32_bf16 v[40:43], v[144:147], v[186:189], v[40:43]
	v_mfma_f32_16x16x32_bf16 v[40:43], v[148:151], v[212:215], v[40:43]
	v_mfma_f32_16x16x32_bf16 v[32:35], v[152:155], v[186:189], v[32:35]
	v_mfma_f32_16x16x32_bf16 v[32:35], v[156:159], v[212:215], v[32:35]
	v_mfma_f32_16x16x32_bf16 v[24:27], v[144:147], v[216:219], v[24:27]
	v_mfma_f32_16x16x32_bf16 v[24:27], v[148:151], v[220:223], v[24:27]
	v_mfma_f32_16x16x32_bf16 v[16:19], v[152:155], v[216:219], v[16:19]
	v_mfma_f32_16x16x32_bf16 v[16:19], v[156:159], v[220:223], v[16:19]
	s_setprio 2
	s_barrier
	v_mfma_f32_16x16x32_bf16 v[8:11], v[144:147], v[224:227], v[8:11]
	v_mfma_f32_16x16x32_bf16 v[8:11], v[148:151], v[228:231], v[8:11]
	v_mfma_f32_16x16x32_bf16 v[0:3], v[152:155], v[224:227], v[0:3]
	v_mfma_f32_16x16x32_bf16 v[0:3], v[156:159], v[228:231], v[0:3]
	s_setprio 0
	s_add_i32 s44, 0, 0x18000
	s_add_i32 s45, 0, 0x1c000
	v_add_u32_e32 v140, s44, v163
	v_add_u32_e32 v156, s45, v163
	ds_read_b128 v[88:91], v140
	ds_read_b128 v[96:99], v140 offset:1024
	ds_read_b128 v[136:139], v140 offset:2048
	ds_read_b128 v[140:143], v140 offset:3072
	ds_read_b128 v[144:147], v156
	ds_read_b128 v[148:151], v156 offset:1024
	ds_read_b128 v[152:155], v156 offset:2048
	ds_read_b128 v[156:159], v156 offset:3072
	s_add_u32 s58, s58, 0x80000
	s_addc_u32 s59, s59, 0
	s_mov_b32 m0, s66
	v_lshl_add_u64 v[238:239], s[58:59], 0, v[164:165]
	ds_read_b128 v[178:181], v210 offset:32768
	ds_read_b128 v[182:185], v210 offset:33792
	ds_read_b128 v[186:189], v210 offset:34816
	ds_read_b128 v[212:215], v210 offset:35840
	ds_read_b128 v[216:219], v210 offset:36864
	ds_read_b128 v[220:223], v210 offset:37888
	ds_read_b128 v[224:227], v210 offset:38912
	ds_read_b128 v[228:231], v210 offset:39936
	global_load_lds_dwordx4 v[238:239], off
	v_lshl_add_u64 v[238:239], s[58:59], 0, v[168:169]
	s_mov_b32 m0, s67
	s_nop 0
	global_load_lds_dwordx4 v[238:239], off
	s_waitcnt vmcnt(8)
	s_waitcnt lgkmcnt(0)
	s_barrier
	s_setprio 1
	s_waitcnt lgkmcnt(0)
	v_mfma_f32_16x16x32_bf16 v[128:131], v[88:91], v[178:181], v[128:131]
	v_mfma_f32_16x16x32_bf16 v[128:131], v[96:99], v[182:185], v[128:131]
	v_mfma_f32_16x16x32_bf16 v[120:123], v[136:139], v[178:181], v[120:123]
	v_mfma_f32_16x16x32_bf16 v[120:123], v[140:143], v[182:185], v[120:123]
	v_mfma_f32_16x16x32_bf16 v[116:119], v[88:91], v[186:189], v[116:119]
	v_mfma_f32_16x16x32_bf16 v[116:119], v[96:99], v[212:215], v[116:119]
	v_mfma_f32_16x16x32_bf16 v[108:111], v[136:139], v[186:189], v[108:111]
	v_mfma_f32_16x16x32_bf16 v[108:111], v[140:143], v[212:215], v[108:111]
	v_mfma_f32_16x16x32_bf16 v[100:103], v[88:91], v[216:219], v[100:103]
	v_mfma_f32_16x16x32_bf16 v[100:103], v[96:99], v[220:223], v[100:103]
	v_mfma_f32_16x16x32_bf16 v[84:87], v[136:139], v[216:219], v[84:87]
	v_mfma_f32_16x16x32_bf16 v[84:87], v[140:143], v[220:223], v[84:87]
	v_mfma_f32_16x16x32_bf16 v[76:79], v[88:91], v[224:227], v[76:79]
	v_mfma_f32_16x16x32_bf16 v[76:79], v[96:99], v[228:231], v[76:79]
	v_mfma_f32_16x16x32_bf16 v[68:71], v[136:139], v[224:227], v[68:71]
	v_mfma_f32_16x16x32_bf16 v[68:71], v[140:143], v[228:231], v[68:71]
	s_setprio 0
	s_setprio 1
	v_mfma_f32_16x16x32_bf16 v[132:135], v[144:147], v[178:181], v[132:135]
	v_mfma_f32_16x16x32_bf16 v[132:135], v[148:151], v[182:185], v[132:135]
	v_mfma_f32_16x16x32_bf16 v[124:127], v[152:155], v[178:181], v[124:127]
	v_mfma_f32_16x16x32_bf16 v[124:127], v[156:159], v[182:185], v[124:127]
	v_mfma_f32_16x16x32_bf16 v[112:115], v[144:147], v[186:189], v[112:115]
	v_mfma_f32_16x16x32_bf16 v[112:115], v[148:151], v[212:215], v[112:115]
	v_mfma_f32_16x16x32_bf16 v[104:107], v[152:155], v[186:189], v[104:107]
	v_mfma_f32_16x16x32_bf16 v[104:107], v[156:159], v[212:215], v[104:107]
	v_mfma_f32_16x16x32_bf16 v[92:95], v[144:147], v[216:219], v[92:95]
	v_mfma_f32_16x16x32_bf16 v[92:95], v[148:151], v[220:223], v[92:95]
	v_mfma_f32_16x16x32_bf16 v[80:83], v[152:155], v[216:219], v[80:83]
	v_mfma_f32_16x16x32_bf16 v[80:83], v[156:159], v[220:223], v[80:83]
	s_setprio 2
	s_barrier
; #define PG8_STAGE(bufoff, gbase, voff) do { _Pragma("unroll") for (int _i = 0; _i < 2; ++_i) \
;         __builtin_amdgcn_global_load_lds((const unsigned*)((const char*)(gbase) + (voff)[_i]), (PG8_LAS unsigned*)(lds + (bufoff) + ldsw + _i * 8192), 16, 0, 0); } while (0)
; #define PG8_LDA(dst, b, h) do { _Pragma("unroll") for (int m = 0; m < 4; ++m) _Pragma("unroll") for (int k = 0; k < 2; ++k) dst[m][k] = *(const PG8_LAS bf16x8*)(lds + PG8_SA(b, h) + aoff + m * 2048 + k * 1024); } while (0)
; #define PG8_MMA(ai, bj, At, Bt) do { __builtin_amdgcn_s_setprio(1); _Pragma("unroll") for (int m = 0; m < 4; ++m) _Pragma("unroll") for (int n = 0; n < 2; ++n) _Pragma("unroll") for (int k = 0; k < 2; ++k) \
;         acc[ai][bj][m][n] = __builtin_amdgcn_mfma_f32_16x16x32_bf16(Bt[n][k], At[m][k], acc[ai][bj][m][n], 0, 0, 0); __builtin_amdgcn_s_setprio(0); } while (0)
; #define PG8_WAIT_V(n) asm volatile("s_waitcnt vmcnt(" #n ")" ::: "memory")
; #define PG8_WAIT_L(n) asm volatile("s_waitcnt lgkmcnt(" #n ")" ::: "memory")
; #define PG8_BAR __builtin_amdgcn_s_barrier()
; #define PG8_SCHED __builtin_amdgcn_sched_barrier(0)
; template <class Epi, class Sched, bool ALIGN_EPI = false, bool SP2 = false>
; __device__ __forceinline__ void gemm_phase(PG8_LAS unsigned char* lds, const Gemm g, const Sched& S, const Epi& E) {
;     ...
;             PG8_WAIT_V(8); PG8_WAIT_L(0); PG8_BAR; PG8_MMA(0, 0, At, B0); PG8_MMA(0, 1, At, B1); PG8_BAR; PG8_SCHED;
;             PG8_LDA(At, 1, 1); PG8_STAGE(PG8_SB(1, 0), b3, voffB); PG8_STAGE(PG8_SB(1, 1), b3 + hstep, voffB); PG8_STAGE(PG8_SA(1, 0), a3, voffA);
;             PG8_WAIT_V(8); PG8_WAIT_L(0); PG8_BAR; PG8_MMA(1, 0, At, B0); PG8_MMA(1, 1, At, B1); PG8_BAR; PG8_SCHED;
	v_mfma_f32_16x16x32_bf16 v[72:75], v[144:147], v[224:227], v[72:75]
	v_mfma_f32_16x16x32_bf16 v[72:75], v[148:151], v[228:231], v[72:75]
	v_mfma_f32_16x16x32_bf16 v[64:67], v[152:155], v[224:227], v[64:67]
	v_mfma_f32_16x16x32_bf16 v[64:67], v[156:159], v[228:231], v[64:67]
	s_setprio 0
	s_add_i32 s44, s44, s65
	v_lshl_add_u64 v[200:201], v[200:201], 0, s[18:19]
	s_mov_b32 m0, s44
	ds_read_b128 v[178:181], v210 offset:49152
	ds_read_b128 v[182:185], v210 offset:50176
	ds_read_b128 v[186:189], v210 offset:51200
	ds_read_b128 v[212:215], v210 offset:52224
	ds_read_b128 v[216:219], v210 offset:53248
	ds_read_b128 v[220:223], v210 offset:54272
	ds_read_b128 v[224:227], v210 offset:55296
	ds_read_b128 v[228:231], v210 offset:56320
	global_load_lds_dwordx4 v[200:201], off
	s_add_i32 m0, s44, 0x2000
	s_add_u32 s56, s56, 0x80080
	v_lshl_add_u64 v[200:201], v[232:233], 0, s[18:19]
	s_addc_u32 s57, s57, 0
	s_add_i32 s44, s45, s65
	global_load_lds_dwordx4 v[200:201], off
	v_lshl_add_u64 v[200:201], s[56:57], 0, v[164:165]
	s_mov_b32 m0, s44
	s_nop 0
	global_load_lds_dwordx4 v[200:201], off
	v_lshl_add_u64 v[200:201], s[56:57], 0, v[168:169]
	s_add_i32 m0, s44, 0x2000
	s_nop 0
	global_load_lds_dwordx4 v[200:201], off
	v_lshl_add_u64 v[200:201], v[234:235], 0, s[18:19]
	s_mov_b32 m0, s68
	s_nop 0
	global_load_lds_dwordx4 v[200:201], off
	v_lshl_add_u64 v[200:201], v[236:237], 0, s[18:19]
	s_mov_b32 m0, s69
	s_nop 0
	global_load_lds_dwordx4 v[200:201], off
	s_waitcnt vmcnt(8)
	s_waitcnt lgkmcnt(0)
	s_barrier
	s_setprio 1
	s_waitcnt lgkmcnt(0)
	v_mfma_f32_16x16x32_bf16 v[56:59], v[88:91], v[178:181], v[56:59]
	v_mfma_f32_16x16x32_bf16 v[56:59], v[96:99], v[182:185], v[56:59]
	v_mfma_f32_16x16x32_bf16 v[48:51], v[136:139], v[178:181], v[48:51]
	v_mfma_f32_16x16x32_bf16 v[48:51], v[140:143], v[182:185], v[48:51]
	v_mfma_f32_16x16x32_bf16 v[44:47], v[88:91], v[186:189], v[44:47]
	v_mfma_f32_16x16x32_bf16 v[44:47], v[96:99], v[212:215], v[44:47]
	v_mfma_f32_16x16x32_bf16 v[36:39], v[136:139], v[186:189], v[36:39]
	v_mfma_f32_16x16x32_bf16 v[36:39], v[140:143], v[212:215], v[36:39]
	v_mfma_f32_16x16x32_bf16 v[28:31], v[88:91], v[216:219], v[28:31]
	v_mfma_f32_16x16x32_bf16 v[28:31], v[96:99], v[220:223], v[28:31]
	v_mfma_f32_16x16x32_bf16 v[20:23], v[136:139], v[216:219], v[20:23]
	v_mfma_f32_16x16x32_bf16 v[20:23], v[140:143], v[220:223], v[20:23]
	v_mfma_f32_16x16x32_bf16 v[12:15], v[88:91], v[224:227], v[12:15]
	v_mfma_f32_16x16x32_bf16 v[12:15], v[96:99], v[228:231], v[12:15]
	v_mfma_f32_16x16x32_bf16 v[4:7], v[136:139], v[224:227], v[4:7]
	v_mfma_f32_16x16x32_bf16 v[4:7], v[140:143], v[228:231], v[4:7]
	s_setprio 0
	s_setprio 1
	v_mfma_f32_16x16x32_bf16 v[60:63], v[144:147], v[178:181], v[60:63]
	v_mfma_f32_16x16x32_bf16 v[60:63], v[148:151], v[182:185], v[60:63]
	v_mfma_f32_16x16x32_bf16 v[52:55], v[152:155], v[178:181], v[52:55]
	v_mfma_f32_16x16x32_bf16 v[52:55], v[156:159], v[182:185], v[52:55]
	v_mfma_f32_16x16x32_bf16 v[40:43], v[144:147], v[186:189], v[40:43]
	v_mfma_f32_16x16x32_bf16 v[40:43], v[148:151], v[212:215], v[40:43]
	v_mfma_f32_16x16x32_bf16 v[32:35], v[152:155], v[186:189], v[32:35]
	v_mfma_f32_16x16x32_bf16 v[32:35], v[156:159], v[212:215], v[32:35]
	v_mfma_f32_16x16x32_bf16 v[24:27], v[144:147], v[216:219], v[24:27]
	v_mfma_f32_16x16x32_bf16 v[24:27], v[148:151], v[220:223], v[24:27]
	v_mfma_f32_16x16x32_bf16 v[16:19], v[152:155], v[216:219], v[16:19]
	v_mfma_f32_16x16x32_bf16 v[16:19], v[156:159], v[220:223], v[16:19]
	s_setprio 2
	s_barrier
	v_mfma_f32_16x16x32_bf16 v[8:11], v[144:147], v[224:227], v[8:11]
	v_mfma_f32_16x16x32_bf16 v[8:11], v[148:151], v[228:231], v[8:11]
	v_mfma_f32_16x16x32_bf16 v[0:3], v[152:155], v[224:227], v[0:3]
	v_mfma_f32_16x16x32_bf16 v[0:3], v[156:159], v[228:231], v[0:3]
	s_setprio 0
	s_add_i32 s76, s76, 2
	s_add_u32 s62, s62, 0x100
	s_addc_u32 s63, s63, 0
	s_add_u32 s74, s74, 0x100
	s_addc_u32 s75, s75, 0
	s_cmp_gt_u32 s76, 29
	s_cbranch_scc0 .LBB0_719
	s_and_b64 vcc, exec, s[20:21]
	s_cbranch_vccz .LBB0_722
	s_barrier

; #define PG8_STAGE(bufoff, gbase, voff) do { _Pragma("unroll") for (int _i = 0; _i < 2; ++_i) \
;         __builtin_amdgcn_global_load_lds((const unsigned*)((const char*)(gbase) + (voff)[_i]), (PG8_LAS unsigned*)(lds + (bufoff) + ldsw + _i * 8192), 16, 0, 0); } while (0)
; #define PG8_LDA(dst, b, h) do { _Pragma("unroll") for (int m = 0; m < 4; ++m) _Pragma("unroll") for (int k = 0; k < 2; ++k) dst[m][k] = *(const PG8_LAS bf16x8*)(lds + PG8_SA(b, h) + aoff + m * 2048 + k * 1024); } while (0)
; #define PG8_LDB(dst, b, h) do { _Pragma("unroll") for (int n = 0; n < 2; ++n) _Pragma("unroll") for (int k = 0; k < 2; ++k) dst[n][k] = *(const PG8_LAS bf16x8*)(lds + PG8_SB(b, h) + boff + n * 2048 + k * 1024); } while (0)
; #define PG8_MMA(ai, bj, At, Bt) do { __builtin_amdgcn_s_setprio(1); _Pragma("unroll") for (int m = 0; m < 4; ++m) _Pragma("unroll") for (int n = 0; n < 2; ++n) _Pragma("unroll") for (int k = 0; k < 2; ++k) \
;         acc[ai][bj][m][n] = __builtin_amdgcn_mfma_f32_16x16x32_bf16(Bt[n][k], At[m][k], acc[ai][bj][m][n], 0, 0, 0); __builtin_amdgcn_s_setprio(0); } while (0)
; #define PG8_WAIT_V(n) asm volatile("s_waitcnt vmcnt(" #n ")" ::: "memory")
; #define PG8_WAIT_L(n) asm volatile("s_waitcnt lgkmcnt(" #n ")" ::: "memory")
; #define PG8_BAR __builtin_amdgcn_s_barrier()
; template <class Epi, class Sched, bool ALIGN_EPI = false, bool SP2 = false>
; __device__ __forceinline__ void gemm_phase(PG8_LAS unsigned char* lds, const Gemm g, const Sched& S, const Epi& E) {
;     ...
;             const char* a1 = cA + (size_t)(t + 1) * kstep;
;             const char* a2 = last ? nA : cA + (size_t)(t + 2) * kstep; const char* b2 = last ? nB : cB + (size_t)(t + 2) * kstep;
;             const char* a3 = a2 + kstep; const char* b3 = b2 + kstep;
;             if (last && has_next) S.a_ready(nxt);
;             if constexpr (SP2) {
;             PG8_LDB(B0, 0, 0); PG8_LDB(B1, 0, 1); PG8_SCHED; PG8_LDA(At, 0, 0); PG8_STAGE(PG8_SA(1, 1), a1 + hstep, voffA);
;             PG8_WAIT_V(8); PG8_WAIT_L(0); PG8_BAR; PG8_MMA(0, 0, At, B0); PG8_MMA(0, 1, At, B1); PG8_BAR; PG8_SCHED;
;             PG8_LDA(At, 0, 1); PG8_STAGE(PG8_SB(0, 0), b2, voffB); PG8_STAGE(PG8_SB(0, 1), b2 + hstep, voffB); PG8_STAGE(PG8_SA(0, 0), a2, voffA);
;             PG8_WAIT_V(8); PG8_WAIT_L(0); PG8_BAR; PG8_MMA(1, 0, At, B0); PG8_MMA(1, 1, At, B1); PG8_BAR; PG8_SCHED;
.LBB0_774:
	ds_read_b128 v[136:139], v156
	ds_read_b128 v[140:143], v156 offset:1024
	ds_read_b128 v[172:175], v156 offset:2048
	ds_read_b128 v[176:179], v156 offset:3072
	ds_read_b128 v[180:183], v157
	ds_read_b128 v[184:187], v157 offset:1024
	ds_read_b128 v[208:211], v157 offset:2048
	ds_read_b128 v[212:215], v157 offset:3072
	s_add_u32 s42, s40, 0xfff80080
	s_addc_u32 s43, s41, -1
	s_cmp_eq_u32 s71, 28
	s_cselect_b32 s49, s23, s43
	s_cselect_b32 s48, s34, s42
	s_cselect_b32 s43, s21, s70
	s_cselect_b32 s42, s35, s69
	v_lshl_add_u64 v[188:189], s[40:41], 0, v[128:129]
	s_add_i32 m0, s11, 0xc000
	ds_read_b128 v[216:219], v158
	ds_read_b128 v[220:223], v158 offset:1024
	ds_read_b128 v[224:227], v158 offset:2048
	ds_read_b128 v[228:231], v158 offset:3072
	ds_read_b128 v[232:235], v158 offset:4096
	ds_read_b128 v[236:239], v158 offset:5120
	ds_read_b128 v[240:243], v158 offset:6144
	ds_read_b128 v[244:247], v158 offset:7168
	global_load_lds_dwordx4 v[188:189], off
	v_lshl_add_u64 v[188:189], s[40:41], 0, v[130:131]
	s_add_i32 m0, s11, 0xe000
	s_nop 0
	global_load_lds_dwordx4 v[188:189], off
	s_waitcnt vmcnt(8)
	s_waitcnt lgkmcnt(0)
	s_barrier
	s_setprio 1
	s_waitcnt lgkmcnt(0)
	v_mfma_f32_16x16x32_bf16 v[124:127], v[136:139], v[216:219], v[124:127]
	v_mfma_f32_16x16x32_bf16 v[124:127], v[140:143], v[220:223], v[124:127]
	v_mfma_f32_16x16x32_bf16 v[120:123], v[172:175], v[216:219], v[120:123]
	v_mfma_f32_16x16x32_bf16 v[120:123], v[176:179], v[220:223], v[120:123]
	v_mfma_f32_16x16x32_bf16 v[108:111], v[136:139], v[224:227], v[108:111]
	v_mfma_f32_16x16x32_bf16 v[108:111], v[140:143], v[228:231], v[108:111]
	v_mfma_f32_16x16x32_bf16 v[104:107], v[172:175], v[224:227], v[104:107]
	v_mfma_f32_16x16x32_bf16 v[104:107], v[176:179], v[228:231], v[104:107]
	v_mfma_f32_16x16x32_bf16 v[96:99], v[136:139], v[232:235], v[96:99]
	v_mfma_f32_16x16x32_bf16 v[96:99], v[140:143], v[236:239], v[96:99]
	v_mfma_f32_16x16x32_bf16 v[88:91], v[172:175], v[232:235], v[88:91]
	v_mfma_f32_16x16x32_bf16 v[88:91], v[176:179], v[236:239], v[88:91]
	v_mfma_f32_16x16x32_bf16 v[80:83], v[136:139], v[240:243], v[80:83]
	v_mfma_f32_16x16x32_bf16 v[80:83], v[140:143], v[244:247], v[80:83]
	v_mfma_f32_16x16x32_bf16 v[72:75], v[172:175], v[240:243], v[72:75]
	v_mfma_f32_16x16x32_bf16 v[72:75], v[176:179], v[244:247], v[72:75]
	s_setprio 0
	s_setprio 1
	v_mfma_f32_16x16x32_bf16 v[116:119], v[180:183], v[216:219], v[116:119]
	v_mfma_f32_16x16x32_bf16 v[116:119], v[184:187], v[220:223], v[116:119]
	v_mfma_f32_16x16x32_bf16 v[112:115], v[208:211], v[216:219], v[112:115]
	v_mfma_f32_16x16x32_bf16 v[112:115], v[212:215], v[220:223], v[112:115]
	v_mfma_f32_16x16x32_bf16 v[100:103], v[180:183], v[224:227], v[100:103]
	v_mfma_f32_16x16x32_bf16 v[100:103], v[184:187], v[228:231], v[100:103]
	v_mfma_f32_16x16x32_bf16 v[92:95], v[208:211], v[224:227], v[92:95]
	v_mfma_f32_16x16x32_bf16 v[92:95], v[212:215], v[228:231], v[92:95]
	v_mfma_f32_16x16x32_bf16 v[84:87], v[180:183], v[232:235], v[84:87]
	v_mfma_f32_16x16x32_bf16 v[84:87], v[184:187], v[236:239], v[84:87]
	v_mfma_f32_16x16x32_bf16 v[76:79], v[208:211], v[232:235], v[76:79]
	v_mfma_f32_16x16x32_bf16 v[76:79], v[212:215], v[236:239], v[76:79]
	s_setprio 2
	s_barrier
	v_mfma_f32_16x16x32_bf16 v[68:71], v[180:183], v[240:243], v[68:71]
	v_mfma_f32_16x16x32_bf16 v[68:71], v[184:187], v[244:247], v[68:71]
	v_mfma_f32_16x16x32_bf16 v[64:67], v[208:211], v[240:243], v[64:67]
	v_mfma_f32_16x16x32_bf16 v[64:67], v[212:215], v[244:247], v[64:67]
	s_setprio 0
	s_add_i32 s44, s64, s52
	v_lshl_add_u64 v[188:189], s[42:43], 0, v[166:167]
	s_mov_b32 m0, s44
	ds_read_b128 v[216:219], v158 offset:16384
	ds_read_b128 v[220:223], v158 offset:17408
	ds_read_b128 v[224:227], v158 offset:18432
	ds_read_b128 v[228:231], v158 offset:19456
	ds_read_b128 v[232:235], v158 offset:20480
	ds_read_b128 v[236:239], v158 offset:21504
	ds_read_b128 v[240:243], v158 offset:22528
	ds_read_b128 v[244:247], v158 offset:23552
	global_load_lds_dwordx4 v[188:189], off
	s_add_i32 m0, s44, 0x2000
	s_add_u32 s72, s42, 0x80000
	v_lshl_add_u64 v[200:201], s[42:43], 0, v[170:171]
	s_addc_u32 s73, s43, 0
	s_add_i32 s44, s65, s52
	global_load_lds_dwordx4 v[200:201], off
	v_lshl_add_u64 v[248:249], s[72:73], 0, v[166:167]
	s_mov_b32 m0, s44
	v_lshl_add_u64 v[250:251], s[48:49], 0, v[168:169]
	global_load_lds_dwordx4 v[248:249], off
	v_lshl_add_u64 v[248:249], s[72:73], 0, v[170:171]
	s_add_i32 m0, s44, 0x2000
	s_nop 0
	global_load_lds_dwordx4 v[248:249], off
	v_lshl_add_u64 v[248:249], s[48:49], 0, v[164:165]
	s_mov_b32 m0, s11
	s_nop 0
	global_load_lds_dwordx4 v[248:249], off
	s_mov_b32 m0, s58
	s_nop 0
	global_load_lds_dwordx4 v[250:251], off
	s_waitcnt vmcnt(8)
	s_waitcnt lgkmcnt(0)
	s_barrier
; #define PG8_STAGE(bufoff, gbase, voff) do { _Pragma("unroll") for (int _i = 0; _i < 2; ++_i) \
;         __builtin_amdgcn_global_load_lds((const unsigned*)((const char*)(gbase) + (voff)[_i]), (PG8_LAS unsigned*)(lds + (bufoff) + ldsw + _i * 8192), 16, 0, 0); } while (0)
; #define PG8_LDA(dst, b, h) do { _Pragma("unroll") for (int m = 0; m < 4; ++m) _Pragma("unroll") for (int k = 0; k < 2; ++k) dst[m][k] = *(const PG8_LAS bf16x8*)(lds + PG8_SA(b, h) + aoff + m * 2048 + k * 1024); } while (0)
; #define PG8_LDB(dst, b, h) do { _Pragma("unroll") for (int n = 0; n < 2; ++n) _Pragma("unroll") for (int k = 0; k < 2; ++k) dst[n][k] = *(const PG8_LAS bf16x8*)(lds + PG8_SB(b, h) + boff + n * 2048 + k * 1024); } while (0)
; #define PG8_MMA(ai, bj, At, Bt) do { __builtin_amdgcn_s_setprio(1); _Pragma("unroll") for (int m = 0; m < 4; ++m) _Pragma("unroll") for (int n = 0; n < 2; ++n) _Pragma("unroll") for (int k = 0; k < 2; ++k) \
;         acc[ai][bj][m][n] = __builtin_amdgcn_mfma_f32_16x16x32_bf16(Bt[n][k], At[m][k], acc[ai][bj][m][n], 0, 0, 0); __builtin_amdgcn_s_setprio(0); } while (0)
; #define PG8_WAIT_V(n) asm volatile("s_waitcnt vmcnt(" #n ")" ::: "memory")
; #define PG8_WAIT_L(n) asm volatile("s_waitcnt lgkmcnt(" #n ")" ::: "memory")
; #define PG8_BAR __builtin_amdgcn_s_barrier()
; #define PG8_SCHED __builtin_amdgcn_sched_barrier(0)
; template <class Epi, class Sched, bool ALIGN_EPI = false, bool SP2 = false>
; __device__ __forceinline__ void gemm_phase(PG8_LAS unsigned char* lds, const Gemm g, const Sched& S, const Epi& E) {
;     ...
;             PG8_WAIT_V(8); PG8_WAIT_L(0); PG8_BAR; PG8_MMA(1, 0, At, B0); PG8_MMA(1, 1, At, B1); PG8_BAR; PG8_SCHED;
;             PG8_LDB(B0, 1, 0); PG8_LDB(B1, 1, 1); PG8_SCHED; PG8_LDA(At, 1, 0); PG8_STAGE(PG8_SA(0, 1), a2 + hstep, voffA);
;             PG8_WAIT_V(8); PG8_WAIT_L(0); PG8_BAR; PG8_MMA(0, 0, At, B0); PG8_MMA(0, 1, At, B1); PG8_BAR; PG8_SCHED;
	s_setprio 1
	s_waitcnt lgkmcnt(0)
	v_mfma_f32_16x16x32_bf16 v[60:63], v[136:139], v[216:219], v[60:63]
	v_mfma_f32_16x16x32_bf16 v[60:63], v[140:143], v[220:223], v[60:63]
	v_mfma_f32_16x16x32_bf16 v[56:59], v[172:175], v[216:219], v[56:59]
	v_mfma_f32_16x16x32_bf16 v[56:59], v[176:179], v[220:223], v[56:59]
	v_mfma_f32_16x16x32_bf16 v[48:51], v[136:139], v[224:227], v[48:51]
	v_mfma_f32_16x16x32_bf16 v[48:51], v[140:143], v[228:231], v[48:51]
	v_mfma_f32_16x16x32_bf16 v[40:43], v[172:175], v[224:227], v[40:43]
	v_mfma_f32_16x16x32_bf16 v[40:43], v[176:179], v[228:231], v[40:43]
	v_mfma_f32_16x16x32_bf16 v[32:35], v[136:139], v[232:235], v[32:35]
	v_mfma_f32_16x16x32_bf16 v[32:35], v[140:143], v[236:239], v[32:35]
	v_mfma_f32_16x16x32_bf16 v[24:27], v[172:175], v[232:235], v[24:27]
	v_mfma_f32_16x16x32_bf16 v[24:27], v[176:179], v[236:239], v[24:27]
	v_mfma_f32_16x16x32_bf16 v[12:15], v[136:139], v[240:243], v[12:15]
	v_mfma_f32_16x16x32_bf16 v[12:15], v[140:143], v[244:247], v[12:15]
	v_mfma_f32_16x16x32_bf16 v[8:11], v[172:175], v[240:243], v[8:11]
	v_mfma_f32_16x16x32_bf16 v[8:11], v[176:179], v[244:247], v[8:11]
	s_setprio 0
	s_setprio 1
	v_mfma_f32_16x16x32_bf16 v[52:55], v[180:183], v[216:219], v[52:55]
	v_mfma_f32_16x16x32_bf16 v[52:55], v[184:187], v[220:223], v[52:55]
	v_mfma_f32_16x16x32_bf16 v[44:47], v[208:211], v[216:219], v[44:47]
	v_mfma_f32_16x16x32_bf16 v[44:47], v[212:215], v[220:223], v[44:47]
	v_mfma_f32_16x16x32_bf16 v[36:39], v[180:183], v[224:227], v[36:39]
	v_mfma_f32_16x16x32_bf16 v[36:39], v[184:187], v[228:231], v[36:39]
	v_mfma_f32_16x16x32_bf16 v[28:31], v[208:211], v[224:227], v[28:31]
	v_mfma_f32_16x16x32_bf16 v[28:31], v[212:215], v[228:231], v[28:31]
	v_mfma_f32_16x16x32_bf16 v[20:23], v[180:183], v[232:235], v[20:23]
	v_mfma_f32_16x16x32_bf16 v[20:23], v[184:187], v[236:239], v[20:23]
	v_mfma_f32_16x16x32_bf16 v[16:19], v[208:211], v[232:235], v[16:19]
	v_mfma_f32_16x16x32_bf16 v[16:19], v[212:215], v[236:239], v[16:19]
	s_setprio 2
	s_barrier
	v_mfma_f32_16x16x32_bf16 v[4:7], v[180:183], v[240:243], v[4:7]
	v_mfma_f32_16x16x32_bf16 v[4:7], v[184:187], v[244:247], v[4:7]
	v_mfma_f32_16x16x32_bf16 v[0:3], v[208:211], v[240:243], v[0:3]
	v_mfma_f32_16x16x32_bf16 v[0:3], v[212:215], v[244:247], v[0:3]
	s_setprio 0
	s_add_i32 s44, 0, 0x18000
	v_add_u32_e32 v144, s44, v146
	s_add_i32 s45, 0, 0x1c000
	ds_read_b128 v[136:139], v144
	ds_read_b128 v[140:143], v144 offset:1024
	ds_read_b128 v[172:175], v144 offset:2048
	ds_read_b128 v[176:179], v144 offset:3072
	v_add_u32_e32 v144, s45, v146
	ds_read_b128 v[180:183], v144
	ds_read_b128 v[184:187], v144 offset:1024
	ds_read_b128 v[208:211], v144 offset:2048
	ds_read_b128 v[212:215], v144 offset:3072
	s_add_u32 s48, s48, 0x80000
	s_addc_u32 s49, s49, 0
	s_mov_b32 m0, s59
	v_lshl_add_u64 v[252:253], s[48:49], 0, v[164:165]
	ds_read_b128 v[216:219], v158 offset:32768
	ds_read_b128 v[220:223], v158 offset:33792
	ds_read_b128 v[224:227], v158 offset:34816
	ds_read_b128 v[228:231], v158 offset:35840
	ds_read_b128 v[232:235], v158 offset:36864
	ds_read_b128 v[236:239], v158 offset:37888
	ds_read_b128 v[240:243], v158 offset:38912
	ds_read_b128 v[244:247], v158 offset:39936
	global_load_lds_dwordx4 v[252:253], off
	v_lshl_add_u64 v[252:253], s[48:49], 0, v[168:169]
	s_mov_b32 m0, s60
	s_nop 0
	global_load_lds_dwordx4 v[252:253], off
	s_waitcnt vmcnt(8)
	s_waitcnt lgkmcnt(0)
	s_barrier
	s_setprio 1
	s_waitcnt lgkmcnt(0)
	v_mfma_f32_16x16x32_bf16 v[124:127], v[136:139], v[216:219], v[124:127]
	v_mfma_f32_16x16x32_bf16 v[124:127], v[140:143], v[220:223], v[124:127]
	v_mfma_f32_16x16x32_bf16 v[120:123], v[172:175], v[216:219], v[120:123]
	v_mfma_f32_16x16x32_bf16 v[120:123], v[176:179], v[220:223], v[120:123]
	v_mfma_f32_16x16x32_bf16 v[108:111], v[136:139], v[224:227], v[108:111]
	v_mfma_f32_16x16x32_bf16 v[108:111], v[140:143], v[228:231], v[108:111]
	v_mfma_f32_16x16x32_bf16 v[104:107], v[172:175], v[224:227], v[104:107]
	v_mfma_f32_16x16x32_bf16 v[104:107], v[176:179], v[228:231], v[104:107]
	v_mfma_f32_16x16x32_bf16 v[96:99], v[136:139], v[232:235], v[96:99]
	v_mfma_f32_16x16x32_bf16 v[96:99], v[140:143], v[236:239], v[96:99]
	v_mfma_f32_16x16x32_bf16 v[88:91], v[172:175], v[232:235], v[88:91]
	v_mfma_f32_16x16x32_bf16 v[88:91], v[176:179], v[236:239], v[88:91]
	v_mfma_f32_16x16x32_bf16 v[80:83], v[136:139], v[240:243], v[80:83]
	v_mfma_f32_16x16x32_bf16 v[80:83], v[140:143], v[244:247], v[80:83]
	v_mfma_f32_16x16x32_bf16 v[72:75], v[172:175], v[240:243], v[72:75]
	v_mfma_f32_16x16x32_bf16 v[72:75], v[176:179], v[244:247], v[72:75]
	s_setprio 0
	s_setprio 1
	v_mfma_f32_16x16x32_bf16 v[116:119], v[180:183], v[216:219], v[116:119]
	v_mfma_f32_16x16x32_bf16 v[116:119], v[184:187], v[220:223], v[116:119]
	v_mfma_f32_16x16x32_bf16 v[112:115], v[208:211], v[216:219], v[112:115]
	v_mfma_f32_16x16x32_bf16 v[112:115], v[212:215], v[220:223], v[112:115]
	v_mfma_f32_16x16x32_bf16 v[100:103], v[180:183], v[224:227], v[100:103]
	v_mfma_f32_16x16x32_bf16 v[100:103], v[184:187], v[228:231], v[100:103]
	v_mfma_f32_16x16x32_bf16 v[92:95], v[208:211], v[224:227], v[92:95]
	v_mfma_f32_16x16x32_bf16 v[92:95], v[212:215], v[228:231], v[92:95]
	v_mfma_f32_16x16x32_bf16 v[84:87], v[180:183], v[232:235], v[84:87]
	v_mfma_f32_16x16x32_bf16 v[84:87], v[184:187], v[236:239], v[84:87]
	v_mfma_f32_16x16x32_bf16 v[76:79], v[208:211], v[232:235], v[76:79]
	v_mfma_f32_16x16x32_bf16 v[76:79], v[212:215], v[236:239], v[76:79]
	s_setprio 2
	s_barrier
; #define PG8_STAGE(bufoff, gbase, voff) do { _Pragma("unroll") for (int _i = 0; _i < 2; ++_i) \
;         __builtin_amdgcn_global_load_lds((const unsigned*)((const char*)(gbase) + (voff)[_i]), (PG8_LAS unsigned*)(lds + (bufoff) + ldsw + _i * 8192), 16, 0, 0); } while (0)
; #define PG8_LDA(dst, b, h) do { _Pragma("unroll") for (int m = 0; m < 4; ++m) _Pragma("unroll") for (int k = 0; k < 2; ++k) dst[m][k] = *(const PG8_LAS bf16x8*)(lds + PG8_SA(b, h) + aoff + m * 2048 + k * 1024); } while (0)
; #define PG8_MMA(ai, bj, At, Bt) do { __builtin_amdgcn_s_setprio(1); _Pragma("unroll") for (int m = 0; m < 4; ++m) _Pragma("unroll") for (int n = 0; n < 2; ++n) _Pragma("unroll") for (int k = 0; k < 2; ++k) \
;         acc[ai][bj][m][n] = __builtin_amdgcn_mfma_f32_16x16x32_bf16(Bt[n][k], At[m][k], acc[ai][bj][m][n], 0, 0, 0); __builtin_amdgcn_s_setprio(0); } while (0)
; #define PG8_WAIT_V(n) asm volatile("s_waitcnt vmcnt(" #n ")" ::: "memory")
; #define PG8_WAIT_L(n) asm volatile("s_waitcnt lgkmcnt(" #n ")" ::: "memory")
; #define PG8_BAR __builtin_amdgcn_s_barrier()
; #define PG8_SCHED __builtin_amdgcn_sched_barrier(0)
; template <class Epi, class Sched, bool ALIGN_EPI = false, bool SP2 = false>
; __device__ __forceinline__ void gemm_phase(PG8_LAS unsigned char* lds, const Gemm g, const Sched& S, const Epi& E) {
;     ...
;             PG8_WAIT_V(8); PG8_WAIT_L(0); PG8_BAR; PG8_MMA(0, 0, At, B0); PG8_MMA(0, 1, At, B1); PG8_BAR; PG8_SCHED;
;             PG8_LDA(At, 1, 1); PG8_STAGE(PG8_SB(1, 0), b3, voffB); PG8_STAGE(PG8_SB(1, 1), b3 + hstep, voffB); PG8_STAGE(PG8_SA(1, 0), a3, voffA);
;             PG8_WAIT_V(8); PG8_WAIT_L(0); PG8_BAR; PG8_MMA(1, 0, At, B0); PG8_MMA(1, 1, At, B1); PG8_BAR; PG8_SCHED;
	v_mfma_f32_16x16x32_bf16 v[68:71], v[180:183], v[240:243], v[68:71]
	v_mfma_f32_16x16x32_bf16 v[68:71], v[184:187], v[244:247], v[68:71]
	v_mfma_f32_16x16x32_bf16 v[64:67], v[208:211], v[240:243], v[64:67]
	v_mfma_f32_16x16x32_bf16 v[64:67], v[212:215], v[244:247], v[64:67]
	s_setprio 0
	s_add_i32 s44, s44, s52
	v_lshl_add_u64 v[188:189], v[188:189], 0, s[16:17]
	s_mov_b32 m0, s44
	ds_read_b128 v[216:219], v158 offset:49152
	ds_read_b128 v[220:223], v158 offset:50176
	ds_read_b128 v[224:227], v158 offset:51200
	ds_read_b128 v[228:231], v158 offset:52224
	ds_read_b128 v[232:235], v158 offset:53248
	ds_read_b128 v[236:239], v158 offset:54272
	ds_read_b128 v[240:243], v158 offset:55296
	ds_read_b128 v[244:247], v158 offset:56320
	global_load_lds_dwordx4 v[188:189], off
	s_add_i32 m0, s44, 0x2000
	s_add_u32 s42, s42, 0x80080
	v_lshl_add_u64 v[188:189], v[200:201], 0, s[16:17]
	s_addc_u32 s43, s43, 0
	s_add_i32 s44, s45, s52
	global_load_lds_dwordx4 v[188:189], off
	v_lshl_add_u64 v[188:189], s[42:43], 0, v[166:167]
	s_mov_b32 m0, s44
	s_nop 0
	global_load_lds_dwordx4 v[188:189], off
	v_lshl_add_u64 v[188:189], s[42:43], 0, v[170:171]
	s_add_i32 m0, s44, 0x2000
	s_nop 0
	global_load_lds_dwordx4 v[188:189], off
	v_lshl_add_u64 v[188:189], v[248:249], 0, s[16:17]
	s_mov_b32 m0, s62
	s_nop 0
	global_load_lds_dwordx4 v[188:189], off
	v_lshl_add_u64 v[188:189], v[250:251], 0, s[16:17]
	s_mov_b32 m0, s63
	s_nop 0
	global_load_lds_dwordx4 v[188:189], off
	s_waitcnt vmcnt(8)
	s_waitcnt lgkmcnt(0)
	s_barrier
	s_setprio 1
	s_waitcnt lgkmcnt(0)
	v_mfma_f32_16x16x32_bf16 v[60:63], v[136:139], v[216:219], v[60:63]
	v_mfma_f32_16x16x32_bf16 v[60:63], v[140:143], v[220:223], v[60:63]
	v_mfma_f32_16x16x32_bf16 v[56:59], v[172:175], v[216:219], v[56:59]
	v_mfma_f32_16x16x32_bf16 v[56:59], v[176:179], v[220:223], v[56:59]
	v_mfma_f32_16x16x32_bf16 v[48:51], v[136:139], v[224:227], v[48:51]
	v_mfma_f32_16x16x32_bf16 v[48:51], v[140:143], v[228:231], v[48:51]
	v_mfma_f32_16x16x32_bf16 v[40:43], v[172:175], v[224:227], v[40:43]
	v_mfma_f32_16x16x32_bf16 v[40:43], v[176:179], v[228:231], v[40:43]
	v_mfma_f32_16x16x32_bf16 v[32:35], v[136:139], v[232:235], v[32:35]
	v_mfma_f32_16x16x32_bf16 v[32:35], v[140:143], v[236:239], v[32:35]
	v_mfma_f32_16x16x32_bf16 v[24:27], v[172:175], v[232:235], v[24:27]
	v_mfma_f32_16x16x32_bf16 v[24:27], v[176:179], v[236:239], v[24:27]
	v_mfma_f32_16x16x32_bf16 v[12:15], v[136:139], v[240:243], v[12:15]
	v_mfma_f32_16x16x32_bf16 v[12:15], v[140:143], v[244:247], v[12:15]
	v_mfma_f32_16x16x32_bf16 v[8:11], v[172:175], v[240:243], v[8:11]
	v_mfma_f32_16x16x32_bf16 v[8:11], v[176:179], v[244:247], v[8:11]
	s_setprio 0
	s_setprio 1
	v_mfma_f32_16x16x32_bf16 v[52:55], v[180:183], v[216:219], v[52:55]
	v_mfma_f32_16x16x32_bf16 v[52:55], v[184:187], v[220:223], v[52:55]
	v_mfma_f32_16x16x32_bf16 v[44:47], v[208:211], v[216:219], v[44:47]
	v_mfma_f32_16x16x32_bf16 v[44:47], v[212:215], v[220:223], v[44:47]
	v_mfma_f32_16x16x32_bf16 v[36:39], v[180:183], v[224:227], v[36:39]
	v_mfma_f32_16x16x32_bf16 v[36:39], v[184:187], v[228:231], v[36:39]
	v_mfma_f32_16x16x32_bf16 v[28:31], v[208:211], v[224:227], v[28:31]
	v_mfma_f32_16x16x32_bf16 v[28:31], v[212:215], v[228:231], v[28:31]
	v_mfma_f32_16x16x32_bf16 v[20:23], v[180:183], v[232:235], v[20:23]
	v_mfma_f32_16x16x32_bf16 v[20:23], v[184:187], v[236:239], v[20:23]
	v_mfma_f32_16x16x32_bf16 v[16:19], v[208:211], v[232:235], v[16:19]
	v_mfma_f32_16x16x32_bf16 v[16:19], v[212:215], v[236:239], v[16:19]
	s_setprio 2
	s_barrier
	v_mfma_f32_16x16x32_bf16 v[4:7], v[180:183], v[240:243], v[4:7]
	v_mfma_f32_16x16x32_bf16 v[4:7], v[184:187], v[244:247], v[4:7]
	v_mfma_f32_16x16x32_bf16 v[0:3], v[208:211], v[240:243], v[0:3]
	v_mfma_f32_16x16x32_bf16 v[0:3], v[212:215], v[244:247], v[0:3]
	s_setprio 0
	s_add_i32 s71, s71, 2
	s_add_u32 s40, s40, 0x100
	s_addc_u32 s41, s41, 0
	s_add_u32 s69, s69, 0x100
	s_addc_u32 s70, s70, 0
	s_cmp_gt_u32 s71, 29
	s_cbranch_scc0 .LBB0_774
	s_and_b64 vcc, exec, s[18:19]
	s_cbranch_vccz .LBB0_777
	s_barrier

; #define PG8_STAGE(bufoff, gbase, voff) do { _Pragma("unroll") for (int _i = 0; _i < 2; ++_i) \
;         __builtin_amdgcn_global_load_lds((const unsigned*)((const char*)(gbase) + (voff)[_i]), (PG8_LAS unsigned*)(lds + (bufoff) + ldsw + _i * 8192), 16, 0, 0); } while (0)
; #define PG8_LDA(dst, b, h) do { _Pragma("unroll") for (int m = 0; m < 4; ++m) _Pragma("unroll") for (int k = 0; k < 2; ++k) dst[m][k] = *(const PG8_LAS bf16x8*)(lds + PG8_SA(b, h) + aoff + m * 2048 + k * 1024); } while (0)
; #define PG8_LDB(dst, b, h) do { _Pragma("unroll") for (int n = 0; n < 2; ++n) _Pragma("unroll") for (int k = 0; k < 2; ++k) dst[n][k] = *(const PG8_LAS bf16x8*)(lds + PG8_SB(b, h) + boff + n * 2048 + k * 1024); } while (0)
; #define PG8_MMA(ai, bj, At, Bt) do { __builtin_amdgcn_s_setprio(1); _Pragma("unroll") for (int m = 0; m < 4; ++m) _Pragma("unroll") for (int n = 0; n < 2; ++n) _Pragma("unroll") for (int k = 0; k < 2; ++k) \
;         acc[ai][bj][m][n] = __builtin_amdgcn_mfma_f32_16x16x32_bf16(Bt[n][k], At[m][k], acc[ai][bj][m][n], 0, 0, 0); __builtin_amdgcn_s_setprio(0); } while (0)
; #define PG8_WAIT_V(n) asm volatile("s_waitcnt vmcnt(" #n ")" ::: "memory")
; #define PG8_WAIT_L(n) asm volatile("s_waitcnt lgkmcnt(" #n ")" ::: "memory")
; #define PG8_BAR __builtin_amdgcn_s_barrier()
; template <class Epi, class Sched, bool ALIGN_EPI = false, bool SP2 = false>
; __device__ __forceinline__ void gemm_phase(PG8_LAS unsigned char* lds, const Gemm g, const Sched& S, const Epi& E) {
;     ...
;             const char* a1 = cA + (size_t)(t + 1) * kstep;
;             const char* a2 = last ? nA : cA + (size_t)(t + 2) * kstep; const char* b2 = last ? nB : cB + (size_t)(t + 2) * kstep;
;             const char* a3 = a2 + kstep; const char* b3 = b2 + kstep;
;             if (last && has_next) S.a_ready(nxt);
;             if constexpr (SP2) {
;             PG8_LDB(B0, 0, 0); PG8_LDB(B1, 0, 1); PG8_SCHED; PG8_LDA(At, 0, 0); PG8_STAGE(PG8_SA(1, 1), a1 + hstep, voffA);
;             PG8_WAIT_V(8); PG8_WAIT_L(0); PG8_BAR; PG8_MMA(0, 0, At, B0); PG8_MMA(0, 1, At, B1); PG8_BAR; PG8_SCHED;
;             PG8_LDA(At, 0, 1); PG8_STAGE(PG8_SB(0, 0), b2, voffB); PG8_STAGE(PG8_SB(0, 1), b2 + hstep, voffB); PG8_STAGE(PG8_SA(0, 0), a2, voffA);
;             PG8_WAIT_V(8); PG8_WAIT_L(0); PG8_BAR; PG8_MMA(1, 0, At, B0); PG8_MMA(1, 1, At, B1); PG8_BAR; PG8_SCHED;
.LBB0_837:
	ds_read_b128 v[134:137], v143
	ds_read_b128 v[146:149], v143 offset:1024
	ds_read_b128 v[150:153], v143 offset:2048
	ds_read_b128 v[154:157], v143 offset:3072
	ds_read_b128 v[172:175], v144
	ds_read_b128 v[176:179], v144 offset:1024
	ds_read_b128 v[180:183], v144 offset:2048
	ds_read_b128 v[184:187], v144 offset:3072
	s_add_u32 s44, s42, 0xffea0080
	s_addc_u32 s45, s43, -1
	s_cmpk_eq_i32 s75, 0x54
	s_cselect_b32 s53, s39, s45
	s_cselect_b32 s52, s38, s44
	s_cselect_b32 s49, s41, s35
	s_cselect_b32 s48, s40, s34
	v_lshl_add_u64 v[138:139], s[42:43], 0, v[128:129]
	s_add_i32 m0, s61, 0xc000
	ds_read_b128 v[208:211], v145
	ds_read_b128 v[212:215], v145 offset:1024
	ds_read_b128 v[216:219], v145 offset:2048
	ds_read_b128 v[220:223], v145 offset:3072
	ds_read_b128 v[224:227], v145 offset:4096
	ds_read_b128 v[228:231], v145 offset:5120
	ds_read_b128 v[232:235], v145 offset:6144
	ds_read_b128 v[236:239], v145 offset:7168
	global_load_lds_dwordx4 v[138:139], off
	v_lshl_add_u64 v[138:139], s[42:43], 0, v[130:131]
	s_add_i32 m0, s61, 0xe000
	s_nop 0
	global_load_lds_dwordx4 v[138:139], off
	s_waitcnt vmcnt(8)
	s_waitcnt lgkmcnt(0)
	s_barrier
	s_setprio 1
	s_waitcnt lgkmcnt(0)
	v_mfma_f32_16x16x32_bf16 v[124:127], v[134:137], v[208:211], v[124:127]
	v_mfma_f32_16x16x32_bf16 v[124:127], v[146:149], v[212:215], v[124:127]
	v_mfma_f32_16x16x32_bf16 v[120:123], v[150:153], v[208:211], v[120:123]
	v_mfma_f32_16x16x32_bf16 v[120:123], v[154:157], v[212:215], v[120:123]
	v_mfma_f32_16x16x32_bf16 v[116:119], v[134:137], v[216:219], v[116:119]
	v_mfma_f32_16x16x32_bf16 v[116:119], v[146:149], v[220:223], v[116:119]
	v_mfma_f32_16x16x32_bf16 v[112:115], v[150:153], v[216:219], v[112:115]
	v_mfma_f32_16x16x32_bf16 v[112:115], v[154:157], v[220:223], v[112:115]
	v_mfma_f32_16x16x32_bf16 v[92:95], v[134:137], v[224:227], v[92:95]
	v_mfma_f32_16x16x32_bf16 v[92:95], v[146:149], v[228:231], v[92:95]
	v_mfma_f32_16x16x32_bf16 v[88:91], v[150:153], v[224:227], v[88:91]
	v_mfma_f32_16x16x32_bf16 v[88:91], v[154:157], v[228:231], v[88:91]
	v_mfma_f32_16x16x32_bf16 v[84:87], v[134:137], v[232:235], v[84:87]
	v_mfma_f32_16x16x32_bf16 v[84:87], v[146:149], v[236:239], v[84:87]
	v_mfma_f32_16x16x32_bf16 v[80:83], v[150:153], v[232:235], v[80:83]
	v_mfma_f32_16x16x32_bf16 v[80:83], v[154:157], v[236:239], v[80:83]
	s_setprio 0
	s_setprio 1
	v_mfma_f32_16x16x32_bf16 v[108:111], v[172:175], v[208:211], v[108:111]
	v_mfma_f32_16x16x32_bf16 v[108:111], v[176:179], v[212:215], v[108:111]
	v_mfma_f32_16x16x32_bf16 v[104:107], v[180:183], v[208:211], v[104:107]
	v_mfma_f32_16x16x32_bf16 v[104:107], v[184:187], v[212:215], v[104:107]
	v_mfma_f32_16x16x32_bf16 v[100:103], v[172:175], v[216:219], v[100:103]
	v_mfma_f32_16x16x32_bf16 v[100:103], v[176:179], v[220:223], v[100:103]
	v_mfma_f32_16x16x32_bf16 v[96:99], v[180:183], v[216:219], v[96:99]
	v_mfma_f32_16x16x32_bf16 v[96:99], v[184:187], v[220:223], v[96:99]
	v_mfma_f32_16x16x32_bf16 v[76:79], v[172:175], v[224:227], v[76:79]
	v_mfma_f32_16x16x32_bf16 v[76:79], v[176:179], v[228:231], v[76:79]
	v_mfma_f32_16x16x32_bf16 v[72:75], v[180:183], v[224:227], v[72:75]
	v_mfma_f32_16x16x32_bf16 v[72:75], v[184:187], v[228:231], v[72:75]
	s_setprio 2
	s_barrier
	v_mfma_f32_16x16x32_bf16 v[68:71], v[172:175], v[232:235], v[68:71]
	v_mfma_f32_16x16x32_bf16 v[68:71], v[176:179], v[236:239], v[68:71]
	v_mfma_f32_16x16x32_bf16 v[64:67], v[180:183], v[232:235], v[64:67]
	v_mfma_f32_16x16x32_bf16 v[64:67], v[184:187], v[236:239], v[64:67]
	s_setprio 0
	s_add_i32 s44, s68, s60
	v_lshl_add_u64 v[138:139], s[48:49], 0, v[160:161]
	s_mov_b32 m0, s44
	ds_read_b128 v[208:211], v145 offset:16384
	ds_read_b128 v[212:215], v145 offset:17408
	ds_read_b128 v[216:219], v145 offset:18432
	ds_read_b128 v[220:223], v145 offset:19456
	ds_read_b128 v[224:227], v145 offset:20480
	ds_read_b128 v[228:231], v145 offset:21504
	ds_read_b128 v[232:235], v145 offset:22528
	ds_read_b128 v[236:239], v145 offset:23552
	global_load_lds_dwordx4 v[138:139], off
	s_add_i32 m0, s44, 0x2000
	s_add_u32 s76, s48, 0x160000
	v_lshl_add_u64 v[158:159], s[48:49], 0, v[162:163]
	s_addc_u32 s77, s49, 0
	s_add_i32 s44, s69, s60
	global_load_lds_dwordx4 v[158:159], off
	v_lshl_add_u64 v[188:189], s[76:77], 0, v[160:161]
	s_mov_b32 m0, s44
	v_lshl_add_u64 v[200:201], s[52:53], 0, v[162:163]
	global_load_lds_dwordx4 v[188:189], off
	v_lshl_add_u64 v[188:189], s[76:77], 0, v[162:163]
	s_add_i32 m0, s44, 0x2000
	s_nop 0
	global_load_lds_dwordx4 v[188:189], off
	v_lshl_add_u64 v[188:189], s[52:53], 0, v[160:161]
	s_mov_b32 m0, s61
	s_nop 0
	global_load_lds_dwordx4 v[188:189], off
	s_mov_b32 m0, s62
	s_nop 0
	global_load_lds_dwordx4 v[200:201], off
	s_waitcnt vmcnt(8)
	s_waitcnt lgkmcnt(0)
	s_barrier
; #define PG8_STAGE(bufoff, gbase, voff) do { _Pragma("unroll") for (int _i = 0; _i < 2; ++_i) \
;         __builtin_amdgcn_global_load_lds((const unsigned*)((const char*)(gbase) + (voff)[_i]), (PG8_LAS unsigned*)(lds + (bufoff) + ldsw + _i * 8192), 16, 0, 0); } while (0)
; #define PG8_LDA(dst, b, h) do { _Pragma("unroll") for (int m = 0; m < 4; ++m) _Pragma("unroll") for (int k = 0; k < 2; ++k) dst[m][k] = *(const PG8_LAS bf16x8*)(lds + PG8_SA(b, h) + aoff + m * 2048 + k * 1024); } while (0)
; #define PG8_LDB(dst, b, h) do { _Pragma("unroll") for (int n = 0; n < 2; ++n) _Pragma("unroll") for (int k = 0; k < 2; ++k) dst[n][k] = *(const PG8_LAS bf16x8*)(lds + PG8_SB(b, h) + boff + n * 2048 + k * 1024); } while (0)
; #define PG8_MMA(ai, bj, At, Bt) do { __builtin_amdgcn_s_setprio(1); _Pragma("unroll") for (int m = 0; m < 4; ++m) _Pragma("unroll") for (int n = 0; n < 2; ++n) _Pragma("unroll") for (int k = 0; k < 2; ++k) \
;         acc[ai][bj][m][n] = __builtin_amdgcn_mfma_f32_16x16x32_bf16(Bt[n][k], At[m][k], acc[ai][bj][m][n], 0, 0, 0); __builtin_amdgcn_s_setprio(0); } while (0)
; #define PG8_WAIT_V(n) asm volatile("s_waitcnt vmcnt(" #n ")" ::: "memory")
; #define PG8_WAIT_L(n) asm volatile("s_waitcnt lgkmcnt(" #n ")" ::: "memory")
; #define PG8_BAR __builtin_amdgcn_s_barrier()
; #define PG8_SCHED __builtin_amdgcn_sched_barrier(0)
; template <class Epi, class Sched, bool ALIGN_EPI = false, bool SP2 = false>
; __device__ __forceinline__ void gemm_phase(PG8_LAS unsigned char* lds, const Gemm g, const Sched& S, const Epi& E) {
;     ...
;             PG8_WAIT_V(8); PG8_WAIT_L(0); PG8_BAR; PG8_MMA(1, 0, At, B0); PG8_MMA(1, 1, At, B1); PG8_BAR; PG8_SCHED;
;             PG8_LDB(B0, 1, 0); PG8_LDB(B1, 1, 1); PG8_SCHED; PG8_LDA(At, 1, 0); PG8_STAGE(PG8_SA(0, 1), a2 + hstep, voffA);
;             PG8_WAIT_V(8); PG8_WAIT_L(0); PG8_BAR; PG8_MMA(0, 0, At, B0); PG8_MMA(0, 1, At, B1); PG8_BAR; PG8_SCHED;
	s_setprio 1
	s_waitcnt lgkmcnt(0)
	v_mfma_f32_16x16x32_bf16 v[60:63], v[134:137], v[208:211], v[60:63]
	v_mfma_f32_16x16x32_bf16 v[60:63], v[146:149], v[212:215], v[60:63]
	v_mfma_f32_16x16x32_bf16 v[56:59], v[150:153], v[208:211], v[56:59]
	v_mfma_f32_16x16x32_bf16 v[56:59], v[154:157], v[212:215], v[56:59]
	v_mfma_f32_16x16x32_bf16 v[52:55], v[134:137], v[216:219], v[52:55]
	v_mfma_f32_16x16x32_bf16 v[52:55], v[146:149], v[220:223], v[52:55]
	v_mfma_f32_16x16x32_bf16 v[48:51], v[150:153], v[216:219], v[48:51]
	v_mfma_f32_16x16x32_bf16 v[48:51], v[154:157], v[220:223], v[48:51]
	v_mfma_f32_16x16x32_bf16 v[28:31], v[134:137], v[224:227], v[28:31]
	v_mfma_f32_16x16x32_bf16 v[28:31], v[146:149], v[228:231], v[28:31]
	v_mfma_f32_16x16x32_bf16 v[24:27], v[150:153], v[224:227], v[24:27]
	v_mfma_f32_16x16x32_bf16 v[24:27], v[154:157], v[228:231], v[24:27]
	v_mfma_f32_16x16x32_bf16 v[20:23], v[134:137], v[232:235], v[20:23]
	v_mfma_f32_16x16x32_bf16 v[20:23], v[146:149], v[236:239], v[20:23]
	v_mfma_f32_16x16x32_bf16 v[16:19], v[150:153], v[232:235], v[16:19]
	v_mfma_f32_16x16x32_bf16 v[16:19], v[154:157], v[236:239], v[16:19]
	s_setprio 0
	s_setprio 1
	v_mfma_f32_16x16x32_bf16 v[44:47], v[172:175], v[208:211], v[44:47]
	v_mfma_f32_16x16x32_bf16 v[44:47], v[176:179], v[212:215], v[44:47]
	v_mfma_f32_16x16x32_bf16 v[40:43], v[180:183], v[208:211], v[40:43]
	v_mfma_f32_16x16x32_bf16 v[40:43], v[184:187], v[212:215], v[40:43]
	v_mfma_f32_16x16x32_bf16 v[36:39], v[172:175], v[216:219], v[36:39]
	v_mfma_f32_16x16x32_bf16 v[36:39], v[176:179], v[220:223], v[36:39]
	v_mfma_f32_16x16x32_bf16 v[32:35], v[180:183], v[216:219], v[32:35]
	v_mfma_f32_16x16x32_bf16 v[32:35], v[184:187], v[220:223], v[32:35]
	v_mfma_f32_16x16x32_bf16 v[12:15], v[172:175], v[224:227], v[12:15]
	v_mfma_f32_16x16x32_bf16 v[12:15], v[176:179], v[228:231], v[12:15]
	v_mfma_f32_16x16x32_bf16 v[8:11], v[180:183], v[224:227], v[8:11]
	v_mfma_f32_16x16x32_bf16 v[8:11], v[184:187], v[228:231], v[8:11]
	s_setprio 2
	s_barrier
	v_mfma_f32_16x16x32_bf16 v[4:7], v[172:175], v[232:235], v[4:7]
	v_mfma_f32_16x16x32_bf16 v[4:7], v[176:179], v[236:239], v[4:7]
	v_mfma_f32_16x16x32_bf16 v[0:3], v[180:183], v[232:235], v[0:3]
	v_mfma_f32_16x16x32_bf16 v[0:3], v[184:187], v[236:239], v[0:3]
	s_setprio 0
	s_add_i32 s44, 0, 0x18000
	s_add_i32 s45, 0, 0x1c000
	v_add_u32_e32 v154, s44, v141
	v_add_u32_e32 v165, s45, v141
	ds_read_b128 v[134:137], v154
	ds_read_b128 v[146:149], v154 offset:1024
	ds_read_b128 v[150:153], v154 offset:2048
	ds_read_b128 v[154:157], v154 offset:3072
	ds_read_b128 v[172:175], v165
	ds_read_b128 v[176:179], v165 offset:1024
	ds_read_b128 v[180:183], v165 offset:2048
	ds_read_b128 v[184:187], v165 offset:3072
	s_add_u32 s52, s52, 0x160000
	s_addc_u32 s53, s53, 0
	s_mov_b32 m0, s63
	v_lshl_add_u64 v[240:241], s[52:53], 0, v[160:161]
	ds_read_b128 v[208:211], v145 offset:32768
	ds_read_b128 v[212:215], v145 offset:33792
	ds_read_b128 v[216:219], v145 offset:34816
	ds_read_b128 v[220:223], v145 offset:35840
	ds_read_b128 v[224:227], v145 offset:36864
	ds_read_b128 v[228:231], v145 offset:37888
	ds_read_b128 v[232:235], v145 offset:38912
	ds_read_b128 v[236:239], v145 offset:39936
	global_load_lds_dwordx4 v[240:241], off
	v_lshl_add_u64 v[240:241], s[52:53], 0, v[162:163]
	s_mov_b32 m0, s64
	s_nop 0
	global_load_lds_dwordx4 v[240:241], off
	s_waitcnt vmcnt(8)
	s_waitcnt lgkmcnt(0)
	s_barrier
	s_setprio 1
	s_waitcnt lgkmcnt(0)
	v_mfma_f32_16x16x32_bf16 v[124:127], v[134:137], v[208:211], v[124:127]
	v_mfma_f32_16x16x32_bf16 v[124:127], v[146:149], v[212:215], v[124:127]
	v_mfma_f32_16x16x32_bf16 v[120:123], v[150:153], v[208:211], v[120:123]
	v_mfma_f32_16x16x32_bf16 v[120:123], v[154:157], v[212:215], v[120:123]
	v_mfma_f32_16x16x32_bf16 v[116:119], v[134:137], v[216:219], v[116:119]
	v_mfma_f32_16x16x32_bf16 v[116:119], v[146:149], v[220:223], v[116:119]
	v_mfma_f32_16x16x32_bf16 v[112:115], v[150:153], v[216:219], v[112:115]
	v_mfma_f32_16x16x32_bf16 v[112:115], v[154:157], v[220:223], v[112:115]
	v_mfma_f32_16x16x32_bf16 v[92:95], v[134:137], v[224:227], v[92:95]
	v_mfma_f32_16x16x32_bf16 v[92:95], v[146:149], v[228:231], v[92:95]
	v_mfma_f32_16x16x32_bf16 v[88:91], v[150:153], v[224:227], v[88:91]
	v_mfma_f32_16x16x32_bf16 v[88:91], v[154:157], v[228:231], v[88:91]
	v_mfma_f32_16x16x32_bf16 v[84:87], v[134:137], v[232:235], v[84:87]
	v_mfma_f32_16x16x32_bf16 v[84:87], v[146:149], v[236:239], v[84:87]
	v_mfma_f32_16x16x32_bf16 v[80:83], v[150:153], v[232:235], v[80:83]
	v_mfma_f32_16x16x32_bf16 v[80:83], v[154:157], v[236:239], v[80:83]
	s_setprio 0
	s_setprio 1
	v_mfma_f32_16x16x32_bf16 v[108:111], v[172:175], v[208:211], v[108:111]
	v_mfma_f32_16x16x32_bf16 v[108:111], v[176:179], v[212:215], v[108:111]
	v_mfma_f32_16x16x32_bf16 v[104:107], v[180:183], v[208:211], v[104:107]
	v_mfma_f32_16x16x32_bf16 v[104:107], v[184:187], v[212:215], v[104:107]
	v_mfma_f32_16x16x32_bf16 v[100:103], v[172:175], v[216:219], v[100:103]
	v_mfma_f32_16x16x32_bf16 v[100:103], v[176:179], v[220:223], v[100:103]
	v_mfma_f32_16x16x32_bf16 v[96:99], v[180:183], v[216:219], v[96:99]
	v_mfma_f32_16x16x32_bf16 v[96:99], v[184:187], v[220:223], v[96:99]
	v_mfma_f32_16x16x32_bf16 v[76:79], v[172:175], v[224:227], v[76:79]
	v_mfma_f32_16x16x32_bf16 v[76:79], v[176:179], v[228:231], v[76:79]
	v_mfma_f32_16x16x32_bf16 v[72:75], v[180:183], v[224:227], v[72:75]
	v_mfma_f32_16x16x32_bf16 v[72:75], v[184:187], v[228:231], v[72:75]
	s_setprio 2
	s_barrier
; #define PG8_STAGE(bufoff, gbase, voff) do { _Pragma("unroll") for (int _i = 0; _i < 2; ++_i) \
;         __builtin_amdgcn_global_load_lds((const unsigned*)((const char*)(gbase) + (voff)[_i]), (PG8_LAS unsigned*)(lds + (bufoff) + ldsw + _i * 8192), 16, 0, 0); } while (0)
; #define PG8_LDA(dst, b, h) do { _Pragma("unroll") for (int m = 0; m < 4; ++m) _Pragma("unroll") for (int k = 0; k < 2; ++k) dst[m][k] = *(const PG8_LAS bf16x8*)(lds + PG8_SA(b, h) + aoff + m * 2048 + k * 1024); } while (0)
; #define PG8_MMA(ai, bj, At, Bt) do { __builtin_amdgcn_s_setprio(1); _Pragma("unroll") for (int m = 0; m < 4; ++m) _Pragma("unroll") for (int n = 0; n < 2; ++n) _Pragma("unroll") for (int k = 0; k < 2; ++k) \
;         acc[ai][bj][m][n] = __builtin_amdgcn_mfma_f32_16x16x32_bf16(Bt[n][k], At[m][k], acc[ai][bj][m][n], 0, 0, 0); __builtin_amdgcn_s_setprio(0); } while (0)
; #define PG8_WAIT_V(n) asm volatile("s_waitcnt vmcnt(" #n ")" ::: "memory")
; #define PG8_WAIT_L(n) asm volatile("s_waitcnt lgkmcnt(" #n ")" ::: "memory")
; #define PG8_BAR __builtin_amdgcn_s_barrier()
; #define PG8_SCHED __builtin_amdgcn_sched_barrier(0)
; template <class Epi, class Sched, bool ALIGN_EPI = false, bool SP2 = false>
; __device__ __forceinline__ void gemm_phase(PG8_LAS unsigned char* lds, const Gemm g, const Sched& S, const Epi& E) {
;     ...
;             PG8_WAIT_V(8); PG8_WAIT_L(0); PG8_BAR; PG8_MMA(0, 0, At, B0); PG8_MMA(0, 1, At, B1); PG8_BAR; PG8_SCHED;
;             PG8_LDA(At, 1, 1); PG8_STAGE(PG8_SB(1, 0), b3, voffB); PG8_STAGE(PG8_SB(1, 1), b3 + hstep, voffB); PG8_STAGE(PG8_SA(1, 0), a3, voffA);
;             PG8_WAIT_V(8); PG8_WAIT_L(0); PG8_BAR; PG8_MMA(1, 0, At, B0); PG8_MMA(1, 1, At, B1); PG8_BAR; PG8_SCHED;
	v_mfma_f32_16x16x32_bf16 v[68:71], v[172:175], v[232:235], v[68:71]
	v_mfma_f32_16x16x32_bf16 v[68:71], v[176:179], v[236:239], v[68:71]
	v_mfma_f32_16x16x32_bf16 v[64:67], v[180:183], v[232:235], v[64:67]
	v_mfma_f32_16x16x32_bf16 v[64:67], v[184:187], v[236:239], v[64:67]
	s_setprio 0
	s_add_i32 s44, s44, s60
	v_lshl_add_u64 v[138:139], v[138:139], 0, s[16:17]
	s_mov_b32 m0, s44
	ds_read_b128 v[208:211], v145 offset:49152
	ds_read_b128 v[212:215], v145 offset:50176
	ds_read_b128 v[216:219], v145 offset:51200
	ds_read_b128 v[220:223], v145 offset:52224
	ds_read_b128 v[224:227], v145 offset:53248
	ds_read_b128 v[228:231], v145 offset:54272
	ds_read_b128 v[232:235], v145 offset:55296
	ds_read_b128 v[236:239], v145 offset:56320
	global_load_lds_dwordx4 v[138:139], off
	s_add_i32 m0, s44, 0x2000
	s_add_u32 s48, s48, 0x160080
	v_lshl_add_u64 v[138:139], v[158:159], 0, s[16:17]
	s_addc_u32 s49, s49, 0
	s_add_i32 s44, s45, s60
	global_load_lds_dwordx4 v[138:139], off
	v_lshl_add_u64 v[138:139], s[48:49], 0, v[160:161]
	s_mov_b32 m0, s44
	s_nop 0
	global_load_lds_dwordx4 v[138:139], off
	v_lshl_add_u64 v[138:139], s[48:49], 0, v[162:163]
	s_add_i32 m0, s44, 0x2000
	s_nop 0
	global_load_lds_dwordx4 v[138:139], off
	v_lshl_add_u64 v[138:139], v[188:189], 0, s[16:17]
	s_mov_b32 m0, s65
	s_nop 0
	global_load_lds_dwordx4 v[138:139], off
	v_lshl_add_u64 v[138:139], v[200:201], 0, s[16:17]
	s_mov_b32 m0, s66
	s_nop 0
	global_load_lds_dwordx4 v[138:139], off
	s_waitcnt vmcnt(8)
	s_waitcnt lgkmcnt(0)
	s_barrier
	s_setprio 1
	s_waitcnt lgkmcnt(0)
	v_mfma_f32_16x16x32_bf16 v[60:63], v[134:137], v[208:211], v[60:63]
	v_mfma_f32_16x16x32_bf16 v[60:63], v[146:149], v[212:215], v[60:63]
	v_mfma_f32_16x16x32_bf16 v[56:59], v[150:153], v[208:211], v[56:59]
	v_mfma_f32_16x16x32_bf16 v[56:59], v[154:157], v[212:215], v[56:59]
	v_mfma_f32_16x16x32_bf16 v[52:55], v[134:137], v[216:219], v[52:55]
	v_mfma_f32_16x16x32_bf16 v[52:55], v[146:149], v[220:223], v[52:55]
	v_mfma_f32_16x16x32_bf16 v[48:51], v[150:153], v[216:219], v[48:51]
	v_mfma_f32_16x16x32_bf16 v[48:51], v[154:157], v[220:223], v[48:51]
	v_mfma_f32_16x16x32_bf16 v[28:31], v[134:137], v[224:227], v[28:31]
	v_mfma_f32_16x16x32_bf16 v[28:31], v[146:149], v[228:231], v[28:31]
	v_mfma_f32_16x16x32_bf16 v[24:27], v[150:153], v[224:227], v[24:27]
	v_mfma_f32_16x16x32_bf16 v[24:27], v[154:157], v[228:231], v[24:27]
	v_mfma_f32_16x16x32_bf16 v[20:23], v[134:137], v[232:235], v[20:23]
	v_mfma_f32_16x16x32_bf16 v[20:23], v[146:149], v[236:239], v[20:23]
	v_mfma_f32_16x16x32_bf16 v[16:19], v[150:153], v[232:235], v[16:19]
	v_mfma_f32_16x16x32_bf16 v[16:19], v[154:157], v[236:239], v[16:19]
	s_setprio 0
	s_setprio 1
	v_mfma_f32_16x16x32_bf16 v[44:47], v[172:175], v[208:211], v[44:47]
	v_mfma_f32_16x16x32_bf16 v[44:47], v[176:179], v[212:215], v[44:47]
	v_mfma_f32_16x16x32_bf16 v[40:43], v[180:183], v[208:211], v[40:43]
	v_mfma_f32_16x16x32_bf16 v[40:43], v[184:187], v[212:215], v[40:43]
	v_mfma_f32_16x16x32_bf16 v[36:39], v[172:175], v[216:219], v[36:39]
	v_mfma_f32_16x16x32_bf16 v[36:39], v[176:179], v[220:223], v[36:39]
	v_mfma_f32_16x16x32_bf16 v[32:35], v[180:183], v[216:219], v[32:35]
	v_mfma_f32_16x16x32_bf16 v[32:35], v[184:187], v[220:223], v[32:35]
	v_mfma_f32_16x16x32_bf16 v[12:15], v[172:175], v[224:227], v[12:15]
	v_mfma_f32_16x16x32_bf16 v[12:15], v[176:179], v[228:231], v[12:15]
	v_mfma_f32_16x16x32_bf16 v[8:11], v[180:183], v[224:227], v[8:11]
	v_mfma_f32_16x16x32_bf16 v[8:11], v[184:187], v[228:231], v[8:11]
	s_setprio 2
	s_barrier
	v_mfma_f32_16x16x32_bf16 v[4:7], v[172:175], v[232:235], v[4:7]
	v_mfma_f32_16x16x32_bf16 v[4:7], v[176:179], v[236:239], v[4:7]
	v_mfma_f32_16x16x32_bf16 v[0:3], v[180:183], v[232:235], v[0:3]
	v_mfma_f32_16x16x32_bf16 v[0:3], v[184:187], v[236:239], v[0:3]
	s_setprio 0
	s_add_i32 s75, s75, 2
	s_add_u32 s42, s42, 0x100
	s_addc_u32 s43, s43, 0
	s_add_u32 s34, s34, 0x100
	s_addc_u32 s35, s35, 0
	s_cmpk_gt_u32 s75, 0x55
	s_cbranch_scc0 .LBB0_837
	s_and_b64 vcc, exec, s[18:19]
	s_cbranch_vccz .LBB0_840
	s_barrier

; #define PG8_STAGE(bufoff, gbase, voff) do { _Pragma("unroll") for (int _i = 0; _i < 2; ++_i) \
;         __builtin_amdgcn_global_load_lds((const unsigned*)((const char*)(gbase) + (voff)[_i]), (PG8_LAS unsigned*)(lds + (bufoff) + ldsw + _i * 8192), 16, 0, 0); } while (0)
; #define PG8_LDA(dst, b, h) do { _Pragma("unroll") for (int m = 0; m < 4; ++m) _Pragma("unroll") for (int k = 0; k < 2; ++k) dst[m][k] = *(const PG8_LAS bf16x8*)(lds + PG8_SA(b, h) + aoff + m * 2048 + k * 1024); } while (0)
; #define PG8_LDB(dst, b, h) do { _Pragma("unroll") for (int n = 0; n < 2; ++n) _Pragma("unroll") for (int k = 0; k < 2; ++k) dst[n][k] = *(const PG8_LAS bf16x8*)(lds + PG8_SB(b, h) + boff + n * 2048 + k * 1024); } while (0)
; #define PG8_MMA(ai, bj, At, Bt) do { __builtin_amdgcn_s_setprio(1); _Pragma("unroll") for (int m = 0; m < 4; ++m) _Pragma("unroll") for (int n = 0; n < 2; ++n) _Pragma("unroll") for (int k = 0; k < 2; ++k) \
;         acc[ai][bj][m][n] = __builtin_amdgcn_mfma_f32_16x16x32_bf16(Bt[n][k], At[m][k], acc[ai][bj][m][n], 0, 0, 0); __builtin_amdgcn_s_setprio(0); } while (0)
; #define PG8_WAIT_V(n) asm volatile("s_waitcnt vmcnt(" #n ")" ::: "memory")
; #define PG8_WAIT_L(n) asm volatile("s_waitcnt lgkmcnt(" #n ")" ::: "memory")
; #define PG8_BAR __builtin_amdgcn_s_barrier()
; template <class Epi, class Sched, bool ALIGN_EPI = false, bool SP2 = false>
; __device__ __forceinline__ void gemm_phase(PG8_LAS unsigned char* lds, const Gemm g, const Sched& S, const Epi& E) {
;     ...
;             const char* a1 = cA + (size_t)(t + 1) * kstep;
;             const char* a2 = last ? nA : cA + (size_t)(t + 2) * kstep; const char* b2 = last ? nB : cB + (size_t)(t + 2) * kstep;
;             const char* a3 = a2 + kstep; const char* b3 = b2 + kstep;
;             if (last && has_next) S.a_ready(nxt);
;             if constexpr (SP2) {
;             PG8_LDB(B0, 0, 0); PG8_LDB(B1, 0, 1); PG8_SCHED; PG8_LDA(At, 0, 0); PG8_STAGE(PG8_SA(1, 1), a1 + hstep, voffA);
;             PG8_WAIT_V(8); PG8_WAIT_L(0); PG8_BAR; PG8_MMA(0, 0, At, B0); PG8_MMA(0, 1, At, B1); PG8_BAR; PG8_SCHED;
;             PG8_LDA(At, 0, 1); PG8_STAGE(PG8_SB(0, 0), b2, voffB); PG8_STAGE(PG8_SB(0, 1), b2 + hstep, voffB); PG8_STAGE(PG8_SA(0, 0), a2, voffA);
;             PG8_WAIT_V(8); PG8_WAIT_L(0); PG8_BAR; PG8_MMA(1, 0, At, B0); PG8_MMA(1, 1, At, B1); PG8_BAR; PG8_SCHED;
.LBB0_880:
	ds_read_b128 v[136:139], v156
	ds_read_b128 v[140:143], v156 offset:1024
	ds_read_b128 v[172:175], v156 offset:2048
	ds_read_b128 v[176:179], v156 offset:3072
	ds_read_b128 v[180:183], v157
	ds_read_b128 v[184:187], v157 offset:1024
	ds_read_b128 v[196:199], v157 offset:2048
	ds_read_b128 v[208:211], v157 offset:3072
	s_add_u32 s40, s38, 0xfff80080
	s_addc_u32 s41, s39, -1
	s_cmp_eq_u32 s63, 28
	s_cselect_b32 s43, s19, s41
	s_cselect_b32 s42, s34, s40
	s_cselect_b32 s41, s21, s62
	s_cselect_b32 s40, s35, s61
	v_lshl_add_u64 v[188:189], s[38:39], 0, v[128:129]
	s_add_i32 m0, s7, 0xc000
	ds_read_b128 v[212:215], v158
	ds_read_b128 v[216:219], v158 offset:1024
	ds_read_b128 v[220:223], v158 offset:2048
	ds_read_b128 v[224:227], v158 offset:3072
	ds_read_b128 v[228:231], v158 offset:4096
	ds_read_b128 v[232:235], v158 offset:5120
	ds_read_b128 v[236:239], v158 offset:6144
	ds_read_b128 v[240:243], v158 offset:7168
	global_load_lds_dwordx4 v[188:189], off
	v_lshl_add_u64 v[188:189], s[38:39], 0, v[130:131]
	s_add_i32 m0, s7, 0xe000
	s_nop 0
	global_load_lds_dwordx4 v[188:189], off
	s_waitcnt vmcnt(8)
	s_waitcnt lgkmcnt(0)
	s_barrier
	s_setprio 1
	s_waitcnt lgkmcnt(0)
	v_mfma_f32_16x16x32_bf16 v[124:127], v[136:139], v[212:215], v[124:127]
	v_mfma_f32_16x16x32_bf16 v[124:127], v[140:143], v[216:219], v[124:127]
	v_mfma_f32_16x16x32_bf16 v[120:123], v[172:175], v[212:215], v[120:123]
	v_mfma_f32_16x16x32_bf16 v[120:123], v[176:179], v[216:219], v[120:123]
	v_mfma_f32_16x16x32_bf16 v[108:111], v[136:139], v[220:223], v[108:111]
	v_mfma_f32_16x16x32_bf16 v[108:111], v[140:143], v[224:227], v[108:111]
	v_mfma_f32_16x16x32_bf16 v[104:107], v[172:175], v[220:223], v[104:107]
	v_mfma_f32_16x16x32_bf16 v[104:107], v[176:179], v[224:227], v[104:107]
	v_mfma_f32_16x16x32_bf16 v[96:99], v[136:139], v[228:231], v[96:99]
	v_mfma_f32_16x16x32_bf16 v[96:99], v[140:143], v[232:235], v[96:99]
	v_mfma_f32_16x16x32_bf16 v[88:91], v[172:175], v[228:231], v[88:91]
	v_mfma_f32_16x16x32_bf16 v[88:91], v[176:179], v[232:235], v[88:91]
	v_mfma_f32_16x16x32_bf16 v[80:83], v[136:139], v[236:239], v[80:83]
	v_mfma_f32_16x16x32_bf16 v[80:83], v[140:143], v[240:243], v[80:83]
	v_mfma_f32_16x16x32_bf16 v[72:75], v[172:175], v[236:239], v[72:75]
	v_mfma_f32_16x16x32_bf16 v[72:75], v[176:179], v[240:243], v[72:75]
	s_setprio 0
	s_setprio 1
	v_mfma_f32_16x16x32_bf16 v[116:119], v[180:183], v[212:215], v[116:119]
	v_mfma_f32_16x16x32_bf16 v[116:119], v[184:187], v[216:219], v[116:119]
	v_mfma_f32_16x16x32_bf16 v[112:115], v[196:199], v[212:215], v[112:115]
	v_mfma_f32_16x16x32_bf16 v[112:115], v[208:211], v[216:219], v[112:115]
	v_mfma_f32_16x16x32_bf16 v[100:103], v[180:183], v[220:223], v[100:103]
	v_mfma_f32_16x16x32_bf16 v[100:103], v[184:187], v[224:227], v[100:103]
	v_mfma_f32_16x16x32_bf16 v[92:95], v[196:199], v[220:223], v[92:95]
	v_mfma_f32_16x16x32_bf16 v[92:95], v[208:211], v[224:227], v[92:95]
	v_mfma_f32_16x16x32_bf16 v[84:87], v[180:183], v[228:231], v[84:87]
	v_mfma_f32_16x16x32_bf16 v[84:87], v[184:187], v[232:235], v[84:87]
	v_mfma_f32_16x16x32_bf16 v[76:79], v[196:199], v[228:231], v[76:79]
	v_mfma_f32_16x16x32_bf16 v[76:79], v[208:211], v[232:235], v[76:79]
	s_setprio 2
	s_barrier
	v_mfma_f32_16x16x32_bf16 v[68:71], v[180:183], v[236:239], v[68:71]
	v_mfma_f32_16x16x32_bf16 v[68:71], v[184:187], v[240:243], v[68:71]
	v_mfma_f32_16x16x32_bf16 v[64:67], v[196:199], v[236:239], v[64:67]
	v_mfma_f32_16x16x32_bf16 v[64:67], v[208:211], v[240:243], v[64:67]
	s_setprio 0
	s_add_i32 s44, s52, s33
	v_lshl_add_u64 v[188:189], s[40:41], 0, v[166:167]
	s_mov_b32 m0, s44
	ds_read_b128 v[212:215], v158 offset:16384
	ds_read_b128 v[216:219], v158 offset:17408
	ds_read_b128 v[220:223], v158 offset:18432
	ds_read_b128 v[224:227], v158 offset:19456
	ds_read_b128 v[228:231], v158 offset:20480
	ds_read_b128 v[232:235], v158 offset:21504
	ds_read_b128 v[236:239], v158 offset:22528
	ds_read_b128 v[240:243], v158 offset:23552
	global_load_lds_dwordx4 v[188:189], off
	s_add_i32 m0, s44, 0x2000
	s_add_u32 s64, s40, 0x80000
	v_lshl_add_u64 v[200:201], s[40:41], 0, v[170:171]
	s_addc_u32 s65, s41, 0
	s_add_i32 s44, s53, s33
	global_load_lds_dwordx4 v[200:201], off
	v_lshl_add_u64 v[244:245], s[64:65], 0, v[166:167]
	s_mov_b32 m0, s44
	v_lshl_add_u64 v[246:247], s[42:43], 0, v[168:169]
	global_load_lds_dwordx4 v[244:245], off
	v_lshl_add_u64 v[244:245], s[64:65], 0, v[170:171]
	s_add_i32 m0, s44, 0x2000
	s_nop 0
	global_load_lds_dwordx4 v[244:245], off
	v_lshl_add_u64 v[244:245], s[42:43], 0, v[164:165]
	s_mov_b32 m0, s7
	s_nop 0
	global_load_lds_dwordx4 v[244:245], off
	s_mov_b32 m0, s37
	s_nop 0
	global_load_lds_dwordx4 v[246:247], off
	s_waitcnt vmcnt(8)
	s_waitcnt lgkmcnt(0)
	s_barrier
; #define PG8_STAGE(bufoff, gbase, voff) do { _Pragma("unroll") for (int _i = 0; _i < 2; ++_i) \
;         __builtin_amdgcn_global_load_lds((const unsigned*)((const char*)(gbase) + (voff)[_i]), (PG8_LAS unsigned*)(lds + (bufoff) + ldsw + _i * 8192), 16, 0, 0); } while (0)
; #define PG8_LDA(dst, b, h) do { _Pragma("unroll") for (int m = 0; m < 4; ++m) _Pragma("unroll") for (int k = 0; k < 2; ++k) dst[m][k] = *(const PG8_LAS bf16x8*)(lds + PG8_SA(b, h) + aoff + m * 2048 + k * 1024); } while (0)
; #define PG8_LDB(dst, b, h) do { _Pragma("unroll") for (int n = 0; n < 2; ++n) _Pragma("unroll") for (int k = 0; k < 2; ++k) dst[n][k] = *(const PG8_LAS bf16x8*)(lds + PG8_SB(b, h) + boff + n * 2048 + k * 1024); } while (0)
; #define PG8_MMA(ai, bj, At, Bt) do { __builtin_amdgcn_s_setprio(1); _Pragma("unroll") for (int m = 0; m < 4; ++m) _Pragma("unroll") for (int n = 0; n < 2; ++n) _Pragma("unroll") for (int k = 0; k < 2; ++k) \
;         acc[ai][bj][m][n] = __builtin_amdgcn_mfma_f32_16x16x32_bf16(Bt[n][k], At[m][k], acc[ai][bj][m][n], 0, 0, 0); __builtin_amdgcn_s_setprio(0); } while (0)
; #define PG8_WAIT_V(n) asm volatile("s_waitcnt vmcnt(" #n ")" ::: "memory")
; #define PG8_WAIT_L(n) asm volatile("s_waitcnt lgkmcnt(" #n ")" ::: "memory")
; #define PG8_BAR __builtin_amdgcn_s_barrier()
; #define PG8_SCHED __builtin_amdgcn_sched_barrier(0)
; template <class Epi, class Sched, bool ALIGN_EPI = false, bool SP2 = false>
; __device__ __forceinline__ void gemm_phase(PG8_LAS unsigned char* lds, const Gemm g, const Sched& S, const Epi& E) {
;     ...
;             PG8_WAIT_V(8); PG8_WAIT_L(0); PG8_BAR; PG8_MMA(1, 0, At, B0); PG8_MMA(1, 1, At, B1); PG8_BAR; PG8_SCHED;
;             PG8_LDB(B0, 1, 0); PG8_LDB(B1, 1, 1); PG8_SCHED; PG8_LDA(At, 1, 0); PG8_STAGE(PG8_SA(0, 1), a2 + hstep, voffA);
;             PG8_WAIT_V(8); PG8_WAIT_L(0); PG8_BAR; PG8_MMA(0, 0, At, B0); PG8_MMA(0, 1, At, B1); PG8_BAR; PG8_SCHED;
	s_setprio 1
	s_waitcnt lgkmcnt(0)
	v_mfma_f32_16x16x32_bf16 v[60:63], v[136:139], v[212:215], v[60:63]
	v_mfma_f32_16x16x32_bf16 v[60:63], v[140:143], v[216:219], v[60:63]
	v_mfma_f32_16x16x32_bf16 v[56:59], v[172:175], v[212:215], v[56:59]
	v_mfma_f32_16x16x32_bf16 v[56:59], v[176:179], v[216:219], v[56:59]
	v_mfma_f32_16x16x32_bf16 v[48:51], v[136:139], v[220:223], v[48:51]
	v_mfma_f32_16x16x32_bf16 v[48:51], v[140:143], v[224:227], v[48:51]
	v_mfma_f32_16x16x32_bf16 v[40:43], v[172:175], v[220:223], v[40:43]
	v_mfma_f32_16x16x32_bf16 v[40:43], v[176:179], v[224:227], v[40:43]
	v_mfma_f32_16x16x32_bf16 v[32:35], v[136:139], v[228:231], v[32:35]
	v_mfma_f32_16x16x32_bf16 v[32:35], v[140:143], v[232:235], v[32:35]
	v_mfma_f32_16x16x32_bf16 v[24:27], v[172:175], v[228:231], v[24:27]
	v_mfma_f32_16x16x32_bf16 v[24:27], v[176:179], v[232:235], v[24:27]
	v_mfma_f32_16x16x32_bf16 v[12:15], v[136:139], v[236:239], v[12:15]
	v_mfma_f32_16x16x32_bf16 v[12:15], v[140:143], v[240:243], v[12:15]
	v_mfma_f32_16x16x32_bf16 v[8:11], v[172:175], v[236:239], v[8:11]
	v_mfma_f32_16x16x32_bf16 v[8:11], v[176:179], v[240:243], v[8:11]
	s_setprio 0
	s_setprio 1
	v_mfma_f32_16x16x32_bf16 v[52:55], v[180:183], v[212:215], v[52:55]
	v_mfma_f32_16x16x32_bf16 v[52:55], v[184:187], v[216:219], v[52:55]
	v_mfma_f32_16x16x32_bf16 v[44:47], v[196:199], v[212:215], v[44:47]
	v_mfma_f32_16x16x32_bf16 v[44:47], v[208:211], v[216:219], v[44:47]
	v_mfma_f32_16x16x32_bf16 v[36:39], v[180:183], v[220:223], v[36:39]
	v_mfma_f32_16x16x32_bf16 v[36:39], v[184:187], v[224:227], v[36:39]
	v_mfma_f32_16x16x32_bf16 v[28:31], v[196:199], v[220:223], v[28:31]
	v_mfma_f32_16x16x32_bf16 v[28:31], v[208:211], v[224:227], v[28:31]
	v_mfma_f32_16x16x32_bf16 v[20:23], v[180:183], v[228:231], v[20:23]
	v_mfma_f32_16x16x32_bf16 v[20:23], v[184:187], v[232:235], v[20:23]
	v_mfma_f32_16x16x32_bf16 v[16:19], v[196:199], v[228:231], v[16:19]
	v_mfma_f32_16x16x32_bf16 v[16:19], v[208:211], v[232:235], v[16:19]
	s_setprio 2
	s_barrier
	v_mfma_f32_16x16x32_bf16 v[4:7], v[180:183], v[236:239], v[4:7]
	v_mfma_f32_16x16x32_bf16 v[4:7], v[184:187], v[240:243], v[4:7]
	v_mfma_f32_16x16x32_bf16 v[0:3], v[196:199], v[236:239], v[0:3]
	v_mfma_f32_16x16x32_bf16 v[0:3], v[208:211], v[240:243], v[0:3]
	s_setprio 0
	s_add_i32 s44, 0, 0x18000
	v_add_u32_e32 v144, s44, v146
	s_add_i32 s45, 0, 0x1c000
	ds_read_b128 v[136:139], v144
	ds_read_b128 v[140:143], v144 offset:1024
	ds_read_b128 v[172:175], v144 offset:2048
	ds_read_b128 v[176:179], v144 offset:3072
	v_add_u32_e32 v144, s45, v146
	ds_read_b128 v[180:183], v144
	ds_read_b128 v[184:187], v144 offset:1024
	ds_read_b128 v[196:199], v144 offset:2048
	ds_read_b128 v[208:211], v144 offset:3072
	s_add_u32 s42, s42, 0x80000
	s_addc_u32 s43, s43, 0
	s_mov_b32 m0, s48
	v_lshl_add_u64 v[248:249], s[42:43], 0, v[164:165]
	ds_read_b128 v[212:215], v158 offset:32768
	ds_read_b128 v[216:219], v158 offset:33792
	ds_read_b128 v[220:223], v158 offset:34816
	ds_read_b128 v[224:227], v158 offset:35840
	ds_read_b128 v[228:231], v158 offset:36864
	ds_read_b128 v[232:235], v158 offset:37888
	ds_read_b128 v[236:239], v158 offset:38912
	ds_read_b128 v[240:243], v158 offset:39936
	global_load_lds_dwordx4 v[248:249], off
	v_lshl_add_u64 v[248:249], s[42:43], 0, v[168:169]
	s_mov_b32 m0, s49
	s_nop 0
	global_load_lds_dwordx4 v[248:249], off
	s_waitcnt vmcnt(8)
	s_waitcnt lgkmcnt(0)
	s_barrier
	s_setprio 1
	s_waitcnt lgkmcnt(0)
	v_mfma_f32_16x16x32_bf16 v[124:127], v[136:139], v[212:215], v[124:127]
	v_mfma_f32_16x16x32_bf16 v[124:127], v[140:143], v[216:219], v[124:127]
	v_mfma_f32_16x16x32_bf16 v[120:123], v[172:175], v[212:215], v[120:123]
	v_mfma_f32_16x16x32_bf16 v[120:123], v[176:179], v[216:219], v[120:123]
	v_mfma_f32_16x16x32_bf16 v[108:111], v[136:139], v[220:223], v[108:111]
	v_mfma_f32_16x16x32_bf16 v[108:111], v[140:143], v[224:227], v[108:111]
	v_mfma_f32_16x16x32_bf16 v[104:107], v[172:175], v[220:223], v[104:107]
	v_mfma_f32_16x16x32_bf16 v[104:107], v[176:179], v[224:227], v[104:107]
	v_mfma_f32_16x16x32_bf16 v[96:99], v[136:139], v[228:231], v[96:99]
	v_mfma_f32_16x16x32_bf16 v[96:99], v[140:143], v[232:235], v[96:99]
	v_mfma_f32_16x16x32_bf16 v[88:91], v[172:175], v[228:231], v[88:91]
	v_mfma_f32_16x16x32_bf16 v[88:91], v[176:179], v[232:235], v[88:91]
	v_mfma_f32_16x16x32_bf16 v[80:83], v[136:139], v[236:239], v[80:83]
	v_mfma_f32_16x16x32_bf16 v[80:83], v[140:143], v[240:243], v[80:83]
	v_mfma_f32_16x16x32_bf16 v[72:75], v[172:175], v[236:239], v[72:75]
	v_mfma_f32_16x16x32_bf16 v[72:75], v[176:179], v[240:243], v[72:75]
	s_setprio 0
	s_setprio 1
	v_mfma_f32_16x16x32_bf16 v[116:119], v[180:183], v[212:215], v[116:119]
	v_mfma_f32_16x16x32_bf16 v[116:119], v[184:187], v[216:219], v[116:119]
	v_mfma_f32_16x16x32_bf16 v[112:115], v[196:199], v[212:215], v[112:115]
	v_mfma_f32_16x16x32_bf16 v[112:115], v[208:211], v[216:219], v[112:115]
	v_mfma_f32_16x16x32_bf16 v[100:103], v[180:183], v[220:223], v[100:103]
	v_mfma_f32_16x16x32_bf16 v[100:103], v[184:187], v[224:227], v[100:103]
	v_mfma_f32_16x16x32_bf16 v[92:95], v[196:199], v[220:223], v[92:95]
	v_mfma_f32_16x16x32_bf16 v[92:95], v[208:211], v[224:227], v[92:95]
	v_mfma_f32_16x16x32_bf16 v[84:87], v[180:183], v[228:231], v[84:87]
	v_mfma_f32_16x16x32_bf16 v[84:87], v[184:187], v[232:235], v[84:87]
	v_mfma_f32_16x16x32_bf16 v[76:79], v[196:199], v[228:231], v[76:79]
	v_mfma_f32_16x16x32_bf16 v[76:79], v[208:211], v[232:235], v[76:79]
	s_setprio 2
	s_barrier
; #define PG8_STAGE(bufoff, gbase, voff) do { _Pragma("unroll") for (int _i = 0; _i < 2; ++_i) \
;         __builtin_amdgcn_global_load_lds((const unsigned*)((const char*)(gbase) + (voff)[_i]), (PG8_LAS unsigned*)(lds + (bufoff) + ldsw + _i * 8192), 16, 0, 0); } while (0)
; #define PG8_LDA(dst, b, h) do { _Pragma("unroll") for (int m = 0; m < 4; ++m) _Pragma("unroll") for (int k = 0; k < 2; ++k) dst[m][k] = *(const PG8_LAS bf16x8*)(lds + PG8_SA(b, h) + aoff + m * 2048 + k * 1024); } while (0)
; #define PG8_MMA(ai, bj, At, Bt) do { __builtin_amdgcn_s_setprio(1); _Pragma("unroll") for (int m = 0; m < 4; ++m) _Pragma("unroll") for (int n = 0; n < 2; ++n) _Pragma("unroll") for (int k = 0; k < 2; ++k) \
;         acc[ai][bj][m][n] = __builtin_amdgcn_mfma_f32_16x16x32_bf16(Bt[n][k], At[m][k], acc[ai][bj][m][n], 0, 0, 0); __builtin_amdgcn_s_setprio(0); } while (0)
; #define PG8_WAIT_V(n) asm volatile("s_waitcnt vmcnt(" #n ")" ::: "memory")
; #define PG8_WAIT_L(n) asm volatile("s_waitcnt lgkmcnt(" #n ")" ::: "memory")
; #define PG8_BAR __builtin_amdgcn_s_barrier()
; #define PG8_SCHED __builtin_amdgcn_sched_barrier(0)
; template <class Epi, class Sched, bool ALIGN_EPI = false, bool SP2 = false>
; __device__ __forceinline__ void gemm_phase(PG8_LAS unsigned char* lds, const Gemm g, const Sched& S, const Epi& E) {
;     ...
;             PG8_WAIT_V(8); PG8_WAIT_L(0); PG8_BAR; PG8_MMA(0, 0, At, B0); PG8_MMA(0, 1, At, B1); PG8_BAR; PG8_SCHED;
;             PG8_LDA(At, 1, 1); PG8_STAGE(PG8_SB(1, 0), b3, voffB); PG8_STAGE(PG8_SB(1, 1), b3 + hstep, voffB); PG8_STAGE(PG8_SA(1, 0), a3, voffA);
;             PG8_WAIT_V(8); PG8_WAIT_L(0); PG8_BAR; PG8_MMA(1, 0, At, B0); PG8_MMA(1, 1, At, B1); PG8_BAR; PG8_SCHED;
	v_mfma_f32_16x16x32_bf16 v[68:71], v[180:183], v[236:239], v[68:71]
	v_mfma_f32_16x16x32_bf16 v[68:71], v[184:187], v[240:243], v[68:71]
	v_mfma_f32_16x16x32_bf16 v[64:67], v[196:199], v[236:239], v[64:67]
	v_mfma_f32_16x16x32_bf16 v[64:67], v[208:211], v[240:243], v[64:67]
	s_setprio 0
	s_add_i32 s42, s44, s33
	v_lshl_add_u64 v[188:189], v[188:189], 0, s[14:15]
	s_mov_b32 m0, s42
	ds_read_b128 v[212:215], v158 offset:49152
	ds_read_b128 v[216:219], v158 offset:50176
	ds_read_b128 v[220:223], v158 offset:51200
	ds_read_b128 v[224:227], v158 offset:52224
	ds_read_b128 v[228:231], v158 offset:53248
	ds_read_b128 v[232:235], v158 offset:54272
	ds_read_b128 v[236:239], v158 offset:55296
	ds_read_b128 v[240:243], v158 offset:56320
	global_load_lds_dwordx4 v[188:189], off
	s_add_i32 m0, s42, 0x2000
	s_add_u32 s40, s40, 0x80080
	v_lshl_add_u64 v[188:189], v[200:201], 0, s[14:15]
	s_addc_u32 s41, s41, 0
	s_add_i32 s42, s45, s33
	global_load_lds_dwordx4 v[188:189], off
	v_lshl_add_u64 v[188:189], s[40:41], 0, v[166:167]
	s_mov_b32 m0, s42
	s_nop 0
	global_load_lds_dwordx4 v[188:189], off
	v_lshl_add_u64 v[188:189], s[40:41], 0, v[170:171]
	s_add_i32 m0, s42, 0x2000
	s_nop 0
	global_load_lds_dwordx4 v[188:189], off
	v_lshl_add_u64 v[188:189], v[244:245], 0, s[14:15]
	s_mov_b32 m0, s50
	s_nop 0
	global_load_lds_dwordx4 v[188:189], off
	v_lshl_add_u64 v[188:189], v[246:247], 0, s[14:15]
	s_mov_b32 m0, s51
	s_nop 0
	global_load_lds_dwordx4 v[188:189], off
	s_waitcnt vmcnt(8)
	s_waitcnt lgkmcnt(0)
	s_barrier
	s_setprio 1
	s_waitcnt lgkmcnt(0)
	v_mfma_f32_16x16x32_bf16 v[60:63], v[136:139], v[212:215], v[60:63]
	v_mfma_f32_16x16x32_bf16 v[60:63], v[140:143], v[216:219], v[60:63]
	v_mfma_f32_16x16x32_bf16 v[56:59], v[172:175], v[212:215], v[56:59]
	v_mfma_f32_16x16x32_bf16 v[56:59], v[176:179], v[216:219], v[56:59]
	v_mfma_f32_16x16x32_bf16 v[48:51], v[136:139], v[220:223], v[48:51]
	v_mfma_f32_16x16x32_bf16 v[48:51], v[140:143], v[224:227], v[48:51]
	v_mfma_f32_16x16x32_bf16 v[40:43], v[172:175], v[220:223], v[40:43]
	v_mfma_f32_16x16x32_bf16 v[40:43], v[176:179], v[224:227], v[40:43]
	v_mfma_f32_16x16x32_bf16 v[32:35], v[136:139], v[228:231], v[32:35]
	v_mfma_f32_16x16x32_bf16 v[32:35], v[140:143], v[232:235], v[32:35]
	v_mfma_f32_16x16x32_bf16 v[24:27], v[172:175], v[228:231], v[24:27]
	v_mfma_f32_16x16x32_bf16 v[24:27], v[176:179], v[232:235], v[24:27]
	v_mfma_f32_16x16x32_bf16 v[12:15], v[136:139], v[236:239], v[12:15]
	v_mfma_f32_16x16x32_bf16 v[12:15], v[140:143], v[240:243], v[12:15]
	v_mfma_f32_16x16x32_bf16 v[8:11], v[172:175], v[236:239], v[8:11]
	v_mfma_f32_16x16x32_bf16 v[8:11], v[176:179], v[240:243], v[8:11]
	s_setprio 0
	s_setprio 1
	v_mfma_f32_16x16x32_bf16 v[52:55], v[180:183], v[212:215], v[52:55]
	v_mfma_f32_16x16x32_bf16 v[52:55], v[184:187], v[216:219], v[52:55]
	v_mfma_f32_16x16x32_bf16 v[44:47], v[196:199], v[212:215], v[44:47]
	v_mfma_f32_16x16x32_bf16 v[44:47], v[208:211], v[216:219], v[44:47]
	v_mfma_f32_16x16x32_bf16 v[36:39], v[180:183], v[220:223], v[36:39]
	v_mfma_f32_16x16x32_bf16 v[36:39], v[184:187], v[224:227], v[36:39]
	v_mfma_f32_16x16x32_bf16 v[28:31], v[196:199], v[220:223], v[28:31]
	v_mfma_f32_16x16x32_bf16 v[28:31], v[208:211], v[224:227], v[28:31]
	v_mfma_f32_16x16x32_bf16 v[20:23], v[180:183], v[228:231], v[20:23]
	v_mfma_f32_16x16x32_bf16 v[20:23], v[184:187], v[232:235], v[20:23]
	v_mfma_f32_16x16x32_bf16 v[16:19], v[196:199], v[228:231], v[16:19]
	v_mfma_f32_16x16x32_bf16 v[16:19], v[208:211], v[232:235], v[16:19]
	s_setprio 2
	s_barrier
	v_mfma_f32_16x16x32_bf16 v[4:7], v[180:183], v[236:239], v[4:7]
	v_mfma_f32_16x16x32_bf16 v[4:7], v[184:187], v[240:243], v[4:7]
	v_mfma_f32_16x16x32_bf16 v[0:3], v[196:199], v[236:239], v[0:3]
	v_mfma_f32_16x16x32_bf16 v[0:3], v[208:211], v[240:243], v[0:3]
	s_setprio 0
	s_add_i32 s63, s63, 2
	s_add_u32 s38, s38, 0x100
	s_addc_u32 s39, s39, 0
	s_add_u32 s61, s61, 0x100
	s_addc_u32 s62, s62, 0
	s_cmp_gt_u32 s63, 29
	s_cbranch_scc0 .LBB0_880
	s_and_b64 vcc, exec, s[16:17]
	s_cbranch_vccz .LBB0_883
	s_barrier

; #define PG8_STAGE(bufoff, gbase, voff) do { _Pragma("unroll") for (int _i = 0; _i < 2; ++_i) \
;         __builtin_amdgcn_global_load_lds((const unsigned*)((const char*)(gbase) + (voff)[_i]), (PG8_LAS unsigned*)(lds + (bufoff) + ldsw + _i * 8192), 16, 0, 0); } while (0)
; #define PG8_LDA(dst, b, h) do { _Pragma("unroll") for (int m = 0; m < 4; ++m) _Pragma("unroll") for (int k = 0; k < 2; ++k) dst[m][k] = *(const PG8_LAS bf16x8*)(lds + PG8_SA(b, h) + aoff + m * 2048 + k * 1024); } while (0)
; #define PG8_LDB(dst, b, h) do { _Pragma("unroll") for (int n = 0; n < 2; ++n) _Pragma("unroll") for (int k = 0; k < 2; ++k) dst[n][k] = *(const PG8_LAS bf16x8*)(lds + PG8_SB(b, h) + boff + n * 2048 + k * 1024); } while (0)
; #define PG8_MMA(ai, bj, At, Bt) do { __builtin_amdgcn_s_setprio(1); _Pragma("unroll") for (int m = 0; m < 4; ++m) _Pragma("unroll") for (int n = 0; n < 2; ++n) _Pragma("unroll") for (int k = 0; k < 2; ++k) \
;         acc[ai][bj][m][n] = __builtin_amdgcn_mfma_f32_16x16x32_bf16(Bt[n][k], At[m][k], acc[ai][bj][m][n], 0, 0, 0); __builtin_amdgcn_s_setprio(0); } while (0)
; #define PG8_WAIT_V(n) asm volatile("s_waitcnt vmcnt(" #n ")" ::: "memory")
; #define PG8_WAIT_L(n) asm volatile("s_waitcnt lgkmcnt(" #n ")" ::: "memory")
; #define PG8_BAR __builtin_amdgcn_s_barrier()
; template <class Epi, class Sched, bool ALIGN_EPI = false, bool SP2 = false>
; __device__ __forceinline__ void gemm_phase(PG8_LAS unsigned char* lds, const Gemm g, const Sched& S, const Epi& E) {
;     ...
;             const char* a1 = cA + (size_t)(t + 1) * kstep;
;             const char* a2 = last ? nA : cA + (size_t)(t + 2) * kstep; const char* b2 = last ? nB : cB + (size_t)(t + 2) * kstep;
;             const char* a3 = a2 + kstep; const char* b3 = b2 + kstep;
;             if (last && has_next) S.a_ready(nxt);
;             if constexpr (SP2) {
;             PG8_LDB(B0, 0, 0); PG8_LDB(B1, 0, 1); PG8_SCHED; PG8_LDA(At, 0, 0); PG8_STAGE(PG8_SA(1, 1), a1 + hstep, voffA);
;             PG8_WAIT_V(8); PG8_WAIT_L(0); PG8_BAR; PG8_MMA(0, 0, At, B0); PG8_MMA(0, 1, At, B1); PG8_BAR; PG8_SCHED;
;             PG8_LDA(At, 0, 1); PG8_STAGE(PG8_SB(0, 0), b2, voffB); PG8_STAGE(PG8_SB(0, 1), b2 + hstep, voffB); PG8_STAGE(PG8_SA(0, 0), a2, voffA);
;             PG8_WAIT_V(8); PG8_WAIT_L(0); PG8_BAR; PG8_MMA(1, 0, At, B0); PG8_MMA(1, 1, At, B1); PG8_BAR; PG8_SCHED;
.LBB0_937:
	ds_read_b128 v[128:131], v199
	ds_read_b128 v[132:135], v199 offset:1024
	ds_read_b128 v[136:139], v199 offset:2048
	ds_read_b128 v[140:143], v199 offset:3072
	ds_read_b128 v[150:153], v200
	ds_read_b128 v[154:157], v200 offset:1024
	ds_read_b128 v[164:167], v200 offset:2048
	ds_read_b128 v[168:171], v200 offset:3072
	s_add_u32 s22, s20, 0xffea0080
	s_addc_u32 s23, s21, -1
	s_cmpk_eq_i32 s49, 0x54
	s_cselect_b32 s25, s17, s23
	s_cselect_b32 s24, s16, s22
	s_cselect_b32 s23, s19, s48
	s_cselect_b32 s22, s18, s47
	v_lshl_add_u64 v[158:159], s[20:21], 0, v[144:145]
	s_add_i32 m0, s31, 0xc000
	ds_read_b128 v[172:175], v201
	ds_read_b128 v[176:179], v201 offset:1024
	ds_read_b128 v[180:183], v201 offset:2048
	ds_read_b128 v[184:187], v201 offset:3072
	ds_read_b128 v[188:191], v201 offset:4096
	ds_read_b128 v[204:207], v201 offset:5120
	ds_read_b128 v[208:211], v201 offset:6144
	ds_read_b128 v[212:215], v201 offset:7168
	global_load_lds_dwordx4 v[158:159], off
	v_lshl_add_u64 v[158:159], s[20:21], 0, v[146:147]
	s_add_i32 m0, s31, 0xe000
	s_nop 0
	global_load_lds_dwordx4 v[158:159], off
	s_waitcnt vmcnt(8)
	s_waitcnt lgkmcnt(0)
	s_barrier
	s_setprio 1
	s_waitcnt lgkmcnt(0)
	v_mfma_f32_16x16x32_bf16 v[124:127], v[128:131], v[172:175], v[124:127]
	v_mfma_f32_16x16x32_bf16 v[124:127], v[132:135], v[176:179], v[124:127]
	v_mfma_f32_16x16x32_bf16 v[120:123], v[136:139], v[172:175], v[120:123]
	v_mfma_f32_16x16x32_bf16 v[120:123], v[140:143], v[176:179], v[120:123]
	v_mfma_f32_16x16x32_bf16 v[108:111], v[128:131], v[180:183], v[108:111]
	v_mfma_f32_16x16x32_bf16 v[108:111], v[132:135], v[184:187], v[108:111]
	v_mfma_f32_16x16x32_bf16 v[104:107], v[136:139], v[180:183], v[104:107]
	v_mfma_f32_16x16x32_bf16 v[104:107], v[140:143], v[184:187], v[104:107]
	v_mfma_f32_16x16x32_bf16 v[92:95], v[128:131], v[188:191], v[92:95]
	v_mfma_f32_16x16x32_bf16 v[92:95], v[132:135], v[204:207], v[92:95]
	v_mfma_f32_16x16x32_bf16 v[88:91], v[136:139], v[188:191], v[88:91]
	v_mfma_f32_16x16x32_bf16 v[88:91], v[140:143], v[204:207], v[88:91]
	v_mfma_f32_16x16x32_bf16 v[76:79], v[128:131], v[208:211], v[76:79]
	v_mfma_f32_16x16x32_bf16 v[76:79], v[132:135], v[212:215], v[76:79]
	v_mfma_f32_16x16x32_bf16 v[72:75], v[136:139], v[208:211], v[72:75]
	v_mfma_f32_16x16x32_bf16 v[72:75], v[140:143], v[212:215], v[72:75]
	s_setprio 0
	s_setprio 1
	v_mfma_f32_16x16x32_bf16 v[116:119], v[150:153], v[172:175], v[116:119]
	v_mfma_f32_16x16x32_bf16 v[116:119], v[154:157], v[176:179], v[116:119]
	v_mfma_f32_16x16x32_bf16 v[112:115], v[164:167], v[172:175], v[112:115]
	v_mfma_f32_16x16x32_bf16 v[112:115], v[168:171], v[176:179], v[112:115]
	v_mfma_f32_16x16x32_bf16 v[100:103], v[150:153], v[180:183], v[100:103]
	v_mfma_f32_16x16x32_bf16 v[100:103], v[154:157], v[184:187], v[100:103]
	v_mfma_f32_16x16x32_bf16 v[96:99], v[164:167], v[180:183], v[96:99]
	v_mfma_f32_16x16x32_bf16 v[96:99], v[168:171], v[184:187], v[96:99]
	v_mfma_f32_16x16x32_bf16 v[84:87], v[150:153], v[188:191], v[84:87]
	v_mfma_f32_16x16x32_bf16 v[84:87], v[154:157], v[204:207], v[84:87]
	v_mfma_f32_16x16x32_bf16 v[80:83], v[164:167], v[188:191], v[80:83]
	v_mfma_f32_16x16x32_bf16 v[80:83], v[168:171], v[204:207], v[80:83]
	s_setprio 2
	s_barrier
	v_mfma_f32_16x16x32_bf16 v[68:71], v[150:153], v[208:211], v[68:71]
	v_mfma_f32_16x16x32_bf16 v[68:71], v[154:157], v[212:215], v[68:71]
	v_mfma_f32_16x16x32_bf16 v[64:67], v[164:167], v[208:211], v[64:67]
	v_mfma_f32_16x16x32_bf16 v[64:67], v[168:171], v[212:215], v[64:67]
	s_setprio 0
	s_add_i32 s50, s41, s30
	v_lshl_add_u64 v[158:159], s[22:23], 0, v[160:161]
	s_mov_b32 m0, s50
	ds_read_b128 v[172:175], v201 offset:16384
	ds_read_b128 v[176:179], v201 offset:17408
	ds_read_b128 v[180:183], v201 offset:18432
	ds_read_b128 v[184:187], v201 offset:19456
	ds_read_b128 v[188:191], v201 offset:20480
	ds_read_b128 v[204:207], v201 offset:21504
	ds_read_b128 v[208:211], v201 offset:22528
	ds_read_b128 v[212:215], v201 offset:23552
	global_load_lds_dwordx4 v[158:159], off
	s_add_i32 m0, s50, 0x2000
	s_add_u32 s50, s22, 0x160000
	v_lshl_add_u64 v[192:193], s[22:23], 0, v[162:163]
	s_addc_u32 s51, s23, 0
	s_add_i32 s52, s42, s30
	global_load_lds_dwordx4 v[192:193], off
	v_lshl_add_u64 v[216:217], s[50:51], 0, v[160:161]
	s_mov_b32 m0, s52
	v_lshl_add_u64 v[218:219], s[24:25], 0, v[162:163]
	global_load_lds_dwordx4 v[216:217], off
	v_lshl_add_u64 v[216:217], s[50:51], 0, v[162:163]
	s_add_i32 m0, s52, 0x2000
	s_nop 0
	global_load_lds_dwordx4 v[216:217], off
	v_lshl_add_u64 v[216:217], s[24:25], 0, v[160:161]
	s_mov_b32 m0, s31
	s_nop 0
	global_load_lds_dwordx4 v[216:217], off
	s_mov_b32 m0, s33
	s_nop 0
	global_load_lds_dwordx4 v[218:219], off
	s_waitcnt vmcnt(8)
	s_waitcnt lgkmcnt(0)
	s_barrier
; #define PG8_STAGE(bufoff, gbase, voff) do { _Pragma("unroll") for (int _i = 0; _i < 2; ++_i) \
;         __builtin_amdgcn_global_load_lds((const unsigned*)((const char*)(gbase) + (voff)[_i]), (PG8_LAS unsigned*)(lds + (bufoff) + ldsw + _i * 8192), 16, 0, 0); } while (0)
; #define PG8_LDA(dst, b, h) do { _Pragma("unroll") for (int m = 0; m < 4; ++m) _Pragma("unroll") for (int k = 0; k < 2; ++k) dst[m][k] = *(const PG8_LAS bf16x8*)(lds + PG8_SA(b, h) + aoff + m * 2048 + k * 1024); } while (0)
; #define PG8_LDB(dst, b, h) do { _Pragma("unroll") for (int n = 0; n < 2; ++n) _Pragma("unroll") for (int k = 0; k < 2; ++k) dst[n][k] = *(const PG8_LAS bf16x8*)(lds + PG8_SB(b, h) + boff + n * 2048 + k * 1024); } while (0)
; #define PG8_MMA(ai, bj, At, Bt) do { __builtin_amdgcn_s_setprio(1); _Pragma("unroll") for (int m = 0; m < 4; ++m) _Pragma("unroll") for (int n = 0; n < 2; ++n) _Pragma("unroll") for (int k = 0; k < 2; ++k) \
;         acc[ai][bj][m][n] = __builtin_amdgcn_mfma_f32_16x16x32_bf16(Bt[n][k], At[m][k], acc[ai][bj][m][n], 0, 0, 0); __builtin_amdgcn_s_setprio(0); } while (0)
; #define PG8_WAIT_V(n) asm volatile("s_waitcnt vmcnt(" #n ")" ::: "memory")
; #define PG8_WAIT_L(n) asm volatile("s_waitcnt lgkmcnt(" #n ")" ::: "memory")
; #define PG8_BAR __builtin_amdgcn_s_barrier()
; #define PG8_SCHED __builtin_amdgcn_sched_barrier(0)
; template <class Epi, class Sched, bool ALIGN_EPI = false, bool SP2 = false>
; __device__ __forceinline__ void gemm_phase(PG8_LAS unsigned char* lds, const Gemm g, const Sched& S, const Epi& E) {
;     ...
;             PG8_WAIT_V(8); PG8_WAIT_L(0); PG8_BAR; PG8_MMA(1, 0, At, B0); PG8_MMA(1, 1, At, B1); PG8_BAR; PG8_SCHED;
;             PG8_LDB(B0, 1, 0); PG8_LDB(B1, 1, 1); PG8_SCHED; PG8_LDA(At, 1, 0); PG8_STAGE(PG8_SA(0, 1), a2 + hstep, voffA);
;             PG8_WAIT_V(8); PG8_WAIT_L(0); PG8_BAR; PG8_MMA(0, 0, At, B0); PG8_MMA(0, 1, At, B1); PG8_BAR; PG8_SCHED;
	s_setprio 1
	s_waitcnt lgkmcnt(0)
	v_mfma_f32_16x16x32_bf16 v[60:63], v[128:131], v[172:175], v[60:63]
	v_mfma_f32_16x16x32_bf16 v[60:63], v[132:135], v[176:179], v[60:63]
	v_mfma_f32_16x16x32_bf16 v[56:59], v[136:139], v[172:175], v[56:59]
	v_mfma_f32_16x16x32_bf16 v[56:59], v[140:143], v[176:179], v[56:59]
	v_mfma_f32_16x16x32_bf16 v[44:47], v[128:131], v[180:183], v[44:47]
	v_mfma_f32_16x16x32_bf16 v[44:47], v[132:135], v[184:187], v[44:47]
	v_mfma_f32_16x16x32_bf16 v[40:43], v[136:139], v[180:183], v[40:43]
	v_mfma_f32_16x16x32_bf16 v[40:43], v[140:143], v[184:187], v[40:43]
	v_mfma_f32_16x16x32_bf16 v[28:31], v[128:131], v[188:191], v[28:31]
	v_mfma_f32_16x16x32_bf16 v[28:31], v[132:135], v[204:207], v[28:31]
	v_mfma_f32_16x16x32_bf16 v[24:27], v[136:139], v[188:191], v[24:27]
	v_mfma_f32_16x16x32_bf16 v[24:27], v[140:143], v[204:207], v[24:27]
	v_mfma_f32_16x16x32_bf16 v[12:15], v[128:131], v[208:211], v[12:15]
	v_mfma_f32_16x16x32_bf16 v[12:15], v[132:135], v[212:215], v[12:15]
	v_mfma_f32_16x16x32_bf16 v[8:11], v[136:139], v[208:211], v[8:11]
	v_mfma_f32_16x16x32_bf16 v[8:11], v[140:143], v[212:215], v[8:11]
	s_setprio 0
	s_setprio 1
	v_mfma_f32_16x16x32_bf16 v[52:55], v[150:153], v[172:175], v[52:55]
	v_mfma_f32_16x16x32_bf16 v[52:55], v[154:157], v[176:179], v[52:55]
	v_mfma_f32_16x16x32_bf16 v[48:51], v[164:167], v[172:175], v[48:51]
	v_mfma_f32_16x16x32_bf16 v[48:51], v[168:171], v[176:179], v[48:51]
	v_mfma_f32_16x16x32_bf16 v[36:39], v[150:153], v[180:183], v[36:39]
	v_mfma_f32_16x16x32_bf16 v[36:39], v[154:157], v[184:187], v[36:39]
	v_mfma_f32_16x16x32_bf16 v[32:35], v[164:167], v[180:183], v[32:35]
	v_mfma_f32_16x16x32_bf16 v[32:35], v[168:171], v[184:187], v[32:35]
	v_mfma_f32_16x16x32_bf16 v[20:23], v[150:153], v[188:191], v[20:23]
	v_mfma_f32_16x16x32_bf16 v[20:23], v[154:157], v[204:207], v[20:23]
	v_mfma_f32_16x16x32_bf16 v[16:19], v[164:167], v[188:191], v[16:19]
	v_mfma_f32_16x16x32_bf16 v[16:19], v[168:171], v[204:207], v[16:19]
	s_setprio 2
	s_barrier
	v_mfma_f32_16x16x32_bf16 v[4:7], v[150:153], v[208:211], v[4:7]
	v_mfma_f32_16x16x32_bf16 v[4:7], v[154:157], v[212:215], v[4:7]
	v_mfma_f32_16x16x32_bf16 v[0:3], v[164:167], v[208:211], v[0:3]
	v_mfma_f32_16x16x32_bf16 v[0:3], v[168:171], v[212:215], v[0:3]
	s_setprio 0
	s_add_i32 s50, 0, 0x18000
	s_add_i32 s51, 0, 0x1c000
	v_add_u32_e32 v140, s50, v196
	v_add_u32_e32 v168, s51, v196
	ds_read_b128 v[128:131], v140
	ds_read_b128 v[132:135], v140 offset:1024
	ds_read_b128 v[136:139], v140 offset:2048
	ds_read_b128 v[140:143], v140 offset:3072
	ds_read_b128 v[150:153], v168
	ds_read_b128 v[154:157], v168 offset:1024
	ds_read_b128 v[164:167], v168 offset:2048
	ds_read_b128 v[168:171], v168 offset:3072
	s_add_u32 s24, s24, 0x160000
	s_addc_u32 s25, s25, 0
	s_mov_b32 m0, s34
	v_lshl_add_u64 v[220:221], s[24:25], 0, v[160:161]
	ds_read_b128 v[172:175], v201 offset:32768
	ds_read_b128 v[176:179], v201 offset:33792
	ds_read_b128 v[180:183], v201 offset:34816
	ds_read_b128 v[184:187], v201 offset:35840
	ds_read_b128 v[188:191], v201 offset:36864
	ds_read_b128 v[204:207], v201 offset:37888
	ds_read_b128 v[208:211], v201 offset:38912
	ds_read_b128 v[212:215], v201 offset:39936
	global_load_lds_dwordx4 v[220:221], off
	v_lshl_add_u64 v[220:221], s[24:25], 0, v[162:163]
	s_mov_b32 m0, s35
	s_nop 0
	global_load_lds_dwordx4 v[220:221], off
	s_waitcnt vmcnt(8)
	s_waitcnt lgkmcnt(0)
	s_barrier
	s_setprio 1
	s_waitcnt lgkmcnt(0)
	v_mfma_f32_16x16x32_bf16 v[124:127], v[128:131], v[172:175], v[124:127]
	v_mfma_f32_16x16x32_bf16 v[124:127], v[132:135], v[176:179], v[124:127]
	v_mfma_f32_16x16x32_bf16 v[120:123], v[136:139], v[172:175], v[120:123]
	v_mfma_f32_16x16x32_bf16 v[120:123], v[140:143], v[176:179], v[120:123]
	v_mfma_f32_16x16x32_bf16 v[108:111], v[128:131], v[180:183], v[108:111]
	v_mfma_f32_16x16x32_bf16 v[108:111], v[132:135], v[184:187], v[108:111]
	v_mfma_f32_16x16x32_bf16 v[104:107], v[136:139], v[180:183], v[104:107]
	v_mfma_f32_16x16x32_bf16 v[104:107], v[140:143], v[184:187], v[104:107]
	v_mfma_f32_16x16x32_bf16 v[92:95], v[128:131], v[188:191], v[92:95]
	v_mfma_f32_16x16x32_bf16 v[92:95], v[132:135], v[204:207], v[92:95]
	v_mfma_f32_16x16x32_bf16 v[88:91], v[136:139], v[188:191], v[88:91]
	v_mfma_f32_16x16x32_bf16 v[88:91], v[140:143], v[204:207], v[88:91]
	v_mfma_f32_16x16x32_bf16 v[76:79], v[128:131], v[208:211], v[76:79]
	v_mfma_f32_16x16x32_bf16 v[76:79], v[132:135], v[212:215], v[76:79]
	v_mfma_f32_16x16x32_bf16 v[72:75], v[136:139], v[208:211], v[72:75]
	v_mfma_f32_16x16x32_bf16 v[72:75], v[140:143], v[212:215], v[72:75]
	s_setprio 0
	s_setprio 1
	v_mfma_f32_16x16x32_bf16 v[116:119], v[150:153], v[172:175], v[116:119]
	v_mfma_f32_16x16x32_bf16 v[116:119], v[154:157], v[176:179], v[116:119]
	v_mfma_f32_16x16x32_bf16 v[112:115], v[164:167], v[172:175], v[112:115]
	v_mfma_f32_16x16x32_bf16 v[112:115], v[168:171], v[176:179], v[112:115]
	v_mfma_f32_16x16x32_bf16 v[100:103], v[150:153], v[180:183], v[100:103]
	v_mfma_f32_16x16x32_bf16 v[100:103], v[154:157], v[184:187], v[100:103]
	v_mfma_f32_16x16x32_bf16 v[96:99], v[164:167], v[180:183], v[96:99]
	v_mfma_f32_16x16x32_bf16 v[96:99], v[168:171], v[184:187], v[96:99]
	v_mfma_f32_16x16x32_bf16 v[84:87], v[150:153], v[188:191], v[84:87]
	v_mfma_f32_16x16x32_bf16 v[84:87], v[154:157], v[204:207], v[84:87]
	v_mfma_f32_16x16x32_bf16 v[80:83], v[164:167], v[188:191], v[80:83]
	v_mfma_f32_16x16x32_bf16 v[80:83], v[168:171], v[204:207], v[80:83]
	s_setprio 2
	s_barrier
; #define PG8_STAGE(bufoff, gbase, voff) do { _Pragma("unroll") for (int _i = 0; _i < 2; ++_i) \
;         __builtin_amdgcn_global_load_lds((const unsigned*)((const char*)(gbase) + (voff)[_i]), (PG8_LAS unsigned*)(lds + (bufoff) + ldsw + _i * 8192), 16, 0, 0); } while (0)
; #define PG8_LDA(dst, b, h) do { _Pragma("unroll") for (int m = 0; m < 4; ++m) _Pragma("unroll") for (int k = 0; k < 2; ++k) dst[m][k] = *(const PG8_LAS bf16x8*)(lds + PG8_SA(b, h) + aoff + m * 2048 + k * 1024); } while (0)
; #define PG8_MMA(ai, bj, At, Bt) do { __builtin_amdgcn_s_setprio(1); _Pragma("unroll") for (int m = 0; m < 4; ++m) _Pragma("unroll") for (int n = 0; n < 2; ++n) _Pragma("unroll") for (int k = 0; k < 2; ++k) \
;         acc[ai][bj][m][n] = __builtin_amdgcn_mfma_f32_16x16x32_bf16(Bt[n][k], At[m][k], acc[ai][bj][m][n], 0, 0, 0); __builtin_amdgcn_s_setprio(0); } while (0)
; #define PG8_WAIT_V(n) asm volatile("s_waitcnt vmcnt(" #n ")" ::: "memory")
; #define PG8_WAIT_L(n) asm volatile("s_waitcnt lgkmcnt(" #n ")" ::: "memory")
; #define PG8_BAR __builtin_amdgcn_s_barrier()
; #define PG8_SCHED __builtin_amdgcn_sched_barrier(0)
; template <class Epi, class Sched, bool ALIGN_EPI = false, bool SP2 = false>
; __device__ __forceinline__ void gemm_phase(PG8_LAS unsigned char* lds, const Gemm g, const Sched& S, const Epi& E) {
;     ...
;             PG8_WAIT_V(8); PG8_WAIT_L(0); PG8_BAR; PG8_MMA(0, 0, At, B0); PG8_MMA(0, 1, At, B1); PG8_BAR; PG8_SCHED;
;             PG8_LDA(At, 1, 1); PG8_STAGE(PG8_SB(1, 0), b3, voffB); PG8_STAGE(PG8_SB(1, 1), b3 + hstep, voffB); PG8_STAGE(PG8_SA(1, 0), a3, voffA);
;             PG8_WAIT_V(8); PG8_WAIT_L(0); PG8_BAR; PG8_MMA(1, 0, At, B0); PG8_MMA(1, 1, At, B1); PG8_BAR; PG8_SCHED;
	v_mfma_f32_16x16x32_bf16 v[68:71], v[150:153], v[208:211], v[68:71]
	v_mfma_f32_16x16x32_bf16 v[68:71], v[154:157], v[212:215], v[68:71]
	v_mfma_f32_16x16x32_bf16 v[64:67], v[164:167], v[208:211], v[64:67]
	v_mfma_f32_16x16x32_bf16 v[64:67], v[168:171], v[212:215], v[64:67]
	s_setprio 0
	s_add_i32 s24, s50, s30
	v_lshl_add_u64 v[158:159], v[158:159], 0, s[12:13]
	s_mov_b32 m0, s24
	ds_read_b128 v[172:175], v201 offset:49152
	ds_read_b128 v[176:179], v201 offset:50176
	ds_read_b128 v[180:183], v201 offset:51200
	ds_read_b128 v[184:187], v201 offset:52224
	ds_read_b128 v[188:191], v201 offset:53248
	ds_read_b128 v[204:207], v201 offset:54272
	ds_read_b128 v[208:211], v201 offset:55296
	ds_read_b128 v[212:215], v201 offset:56320
	global_load_lds_dwordx4 v[158:159], off
	s_add_i32 m0, s24, 0x2000
	s_add_u32 s22, s22, 0x160080
	v_lshl_add_u64 v[158:159], v[192:193], 0, s[12:13]
	s_addc_u32 s23, s23, 0
	s_add_i32 s24, s51, s30
	global_load_lds_dwordx4 v[158:159], off
	v_lshl_add_u64 v[158:159], s[22:23], 0, v[160:161]
	s_mov_b32 m0, s24
	s_nop 0
	global_load_lds_dwordx4 v[158:159], off
	v_lshl_add_u64 v[158:159], s[22:23], 0, v[162:163]
	s_add_i32 m0, s24, 0x2000
	s_nop 0
	global_load_lds_dwordx4 v[158:159], off
	v_lshl_add_u64 v[158:159], v[216:217], 0, s[12:13]
	s_mov_b32 m0, s39
	s_nop 0
	global_load_lds_dwordx4 v[158:159], off
	v_lshl_add_u64 v[158:159], v[218:219], 0, s[12:13]
	s_mov_b32 m0, s40
	s_nop 0
	global_load_lds_dwordx4 v[158:159], off
	s_waitcnt vmcnt(8)
	s_waitcnt lgkmcnt(0)
	s_barrier
	s_setprio 1
	s_waitcnt lgkmcnt(0)
	v_mfma_f32_16x16x32_bf16 v[60:63], v[128:131], v[172:175], v[60:63]
	v_mfma_f32_16x16x32_bf16 v[60:63], v[132:135], v[176:179], v[60:63]
	v_mfma_f32_16x16x32_bf16 v[56:59], v[136:139], v[172:175], v[56:59]
	v_mfma_f32_16x16x32_bf16 v[56:59], v[140:143], v[176:179], v[56:59]
	v_mfma_f32_16x16x32_bf16 v[44:47], v[128:131], v[180:183], v[44:47]
	v_mfma_f32_16x16x32_bf16 v[44:47], v[132:135], v[184:187], v[44:47]
	v_mfma_f32_16x16x32_bf16 v[40:43], v[136:139], v[180:183], v[40:43]
	v_mfma_f32_16x16x32_bf16 v[40:43], v[140:143], v[184:187], v[40:43]
	v_mfma_f32_16x16x32_bf16 v[28:31], v[128:131], v[188:191], v[28:31]
	v_mfma_f32_16x16x32_bf16 v[28:31], v[132:135], v[204:207], v[28:31]
	v_mfma_f32_16x16x32_bf16 v[24:27], v[136:139], v[188:191], v[24:27]
	v_mfma_f32_16x16x32_bf16 v[24:27], v[140:143], v[204:207], v[24:27]
	v_mfma_f32_16x16x32_bf16 v[12:15], v[128:131], v[208:211], v[12:15]
	v_mfma_f32_16x16x32_bf16 v[12:15], v[132:135], v[212:215], v[12:15]
	v_mfma_f32_16x16x32_bf16 v[8:11], v[136:139], v[208:211], v[8:11]
	v_mfma_f32_16x16x32_bf16 v[8:11], v[140:143], v[212:215], v[8:11]
	s_setprio 0
	s_setprio 1
	v_mfma_f32_16x16x32_bf16 v[52:55], v[150:153], v[172:175], v[52:55]
	v_mfma_f32_16x16x32_bf16 v[52:55], v[154:157], v[176:179], v[52:55]
	v_mfma_f32_16x16x32_bf16 v[48:51], v[164:167], v[172:175], v[48:51]
	v_mfma_f32_16x16x32_bf16 v[48:51], v[168:171], v[176:179], v[48:51]
	v_mfma_f32_16x16x32_bf16 v[36:39], v[150:153], v[180:183], v[36:39]
	v_mfma_f32_16x16x32_bf16 v[36:39], v[154:157], v[184:187], v[36:39]
	v_mfma_f32_16x16x32_bf16 v[32:35], v[164:167], v[180:183], v[32:35]
	v_mfma_f32_16x16x32_bf16 v[32:35], v[168:171], v[184:187], v[32:35]
	v_mfma_f32_16x16x32_bf16 v[20:23], v[150:153], v[188:191], v[20:23]
	v_mfma_f32_16x16x32_bf16 v[20:23], v[154:157], v[204:207], v[20:23]
	v_mfma_f32_16x16x32_bf16 v[16:19], v[164:167], v[188:191], v[16:19]
	v_mfma_f32_16x16x32_bf16 v[16:19], v[168:171], v[204:207], v[16:19]
	s_setprio 2
	s_barrier
	v_mfma_f32_16x16x32_bf16 v[4:7], v[150:153], v[208:211], v[4:7]
	v_mfma_f32_16x16x32_bf16 v[4:7], v[154:157], v[212:215], v[4:7]
	v_mfma_f32_16x16x32_bf16 v[0:3], v[164:167], v[208:211], v[0:3]
	v_mfma_f32_16x16x32_bf16 v[0:3], v[168:171], v[212:215], v[0:3]
	s_setprio 0
	s_add_i32 s49, s49, 2
	s_add_u32 s20, s20, 0x100
	s_addc_u32 s21, s21, 0
	s_add_u32 s47, s47, 0x100
	s_addc_u32 s48, s48, 0
	s_cmpk_gt_u32 s49, 0x55
	s_cbranch_scc0 .LBB0_937
	s_and_b64 vcc, exec, s[14:15]
	s_cbranch_vccz .LBB0_940
	s_barrier
